# plus kernel-invariant kernarg pointers kept in spill-VGPR lanes (v_readlane) instead of s_load+wait per use inside the layer loop
# baseline (speedup 1.0000x reference)
; #define LAS __attribute__((address_space(3)))
; __device__ __forceinline__ const float* karg(int k) { kargp_t p = (kargp_t)__builtin_amdgcn_kernarg_segment_ptr(); asm volatile("" : "+s"(p)); return *(const float* const __attribute__((address_space(4)))*)(p + 8 * k); }
; __device__ __forceinline__ unsigned xb_add(unsigned* p, unsigned v) { return __hip_atomic_fetch_add(p, v, __ATOMIC_RELAXED, __HIP_MEMORY_SCOPE_AGENT); }
; __device__ __forceinline__ unsigned xb_xcc_id() { return (unsigned)__builtin_amdgcn_s_getreg((3 << 11) | 20) & 0xFu; }
; __device__ __forceinline__ XcdBarrier xcd_barrier_post(unsigned* bar, volatile LAS unsigned* st) {
;     XcdBarrier b; b.bar = bar; b.x = xb_xcc_id(); b.st = st;
;     if (threadIdx.x == 0) (void)xb_add(&bar[XB_XCNT(b.x)], 1u);
;     return b;
; __global__ void __launch_bounds__(512, 2) fwd_mega(Args args) {
;     extern __shared__ __attribute__((aligned(16))) unsigned char lds_raw[];
;     LAS unsigned char* const lds0 = (LAS unsigned char*)lds_raw;
;     cg::grid_group grid = cg::this_grid();
;     volatile LAS unsigned* barst = (volatile LAS unsigned*)(lds0 + EXTRA_OFF + X_BAR);
;     if (threadIdx.x < 2) barst[threadIdx.x] = 0u;
;     __syncthreads();
;     (void)xcd_barrier_post((unsigned*)((unsigned char*)karg(20) + WS_CTL + 4096), barst);
_Z8fwd_mega4Args:
	s_load_dwordx2 s[94:95], s[0:1], 0xa8
	s_load_dword s33, s[0:1], 0xb0
	s_mov_b64 s[88:89], s[0:1]
	s_mov_b32 s91, s2
	s_load_dwordx2 s[98:99], s[88:89], 0x98
	s_load_dwordx2 s[100:101], s[88:89], 0xa0
	s_waitcnt lgkmcnt(0)
	v_writelane_b32 v255, s98, 50
	v_writelane_b32 v255, s99, 51
	v_writelane_b32 v255, s100, 52
	v_writelane_b32 v255, s101, 53
	s_load_dwordx2 s[98:99], s[88:89], 0x78
	s_load_dwordx2 s[100:101], s[88:89], 0x80
	s_waitcnt lgkmcnt(0)
	v_writelane_b32 v255, s98, 54
	v_writelane_b32 v255, s99, 55
	v_writelane_b32 v255, s100, 56
	v_writelane_b32 v255, s101, 57
	s_add_u32 s2, s88, 0xa8
	v_and_b32_e32 v191, 0x3ff, v0
	s_addc_u32 s3, s89, 0
	v_cmp_gt_u32_e32 vcc, 2, v191
	s_and_saveexec_b64 s[4:5], vcc
	v_lshl_add_u32 v1, v191, 2, 0
	v_add_u32_e32 v1, 0x26100, v1
	v_mov_b32_e32 v2, 0
	ds_write_b32 v1, v2
	s_or_b64 exec, exec, s[4:5]
	s_mov_b64 s[6:7], s[88:89]
	s_waitcnt lgkmcnt(0)
	s_barrier
	s_getreg_b32 s0, hwreg(HW_REG_XCC_ID, 0, 4)
	s_mov_b32 s10, 0
	v_cmp_eq_u32_e32 vcc, 0, v191
	s_and_saveexec_b64 s[4:5], vcc
	s_cbranch_execz .LBB0_5
	s_mov_b64 s[8:9], exec
	v_mbcnt_lo_u32_b32 v1, s8, 0
	v_mbcnt_hi_u32_b32 v1, s9, v1
	v_cmp_eq_u32_e32 vcc, 0, v1
	s_and_b64 s[12:13], exec, vcc
	s_mov_b64 exec, s[12:13]
	s_cbranch_execz .LBB0_5
	s_load_dwordx2 s[6:7], s[6:7], 0xa0
	s_lshl_b32 s0, s0, 8
	s_and_b32 s0, s0, 0xf00
	v_mov_b32_e32 v1, 0x1000
	s_waitcnt lgkmcnt(0)
	s_add_u32 s0, s6, s0
	s_addc_u32 s1, s7, 0
	s_bcnt1_i32_b64 s6, s[8:9]
	v_mov_b32_e32 v2, s6
	global_atomic_add v1, v2, s[0:1] offset:1024

;     __device__ __forceinline__ bool next(int i, Unit& u) const {
;         long L = (long)i * G + c;
;         u.pad = 0; u.nt = 16; u.slice = 0; u.nsplit = 1; u.tile = 0;
;         if (L < 1280) { pg8::map_tile((int)L, 128, 10, u.pm, u.pn); u.kind = 0; u.a = XG + (size_t)u.pm * TSTEP1K; u.b = Wmain + (size_t)u.pn * TSTEP1K; return true; }
;         L -= 1280;
;         if (L < 256) { u.pm = (int)(L & 1); u.pn = (int)(L >> 1); u.kind = 1; u.a = Wv + (size_t)u.pm * TSTEP1K; u.b = XG + (size_t)u.pn * TSTEP1K; return true; }
;         L -= 256; if (L >= 24) return false;
;         const int tile = (int)L;
;         if (tile < 20) { u.pm = 128 + (tile & 1); u.pn = tile >> 1; u.kind = 0; u.a = XG + (size_t)u.pm * TSTEP1K; u.b = Wmain + (size_t)u.pn * TSTEP1K; }
; __global__ void __launch_bounds__(512, 2) fwd_mega(Args args) {
;     ...
;             SchedIn S{(const char*)XG, (const char*)(wl + W_IN), (const char*)(wl + W_IN) + (size_t)2560 * 2048, G, bxp, (l * 4 + 0) * 64};
.LBB0_189:
	v_mov_b32_e32 v0, v191
	s_mov_b32 s40, s91
	s_mov_b64 s[0:1], s[88:89]
	v_readlane_b32 s0, v255, 52
	v_readlane_b32 s1, v255, 53
	s_nop 4
	s_mul_i32 s3, s82, 0x1900000
	s_mul_hi_u32 s2, s82, 0x1900000
	s_mov_b32 s41, s75
	v_writelane_b32 v255, s3, 22
	s_waitcnt lgkmcnt(0)
	s_add_u32 s42, s0, 0x6500000
	s_addc_u32 s43, s1, 0
	s_add_u32 s0, s0, s3
	s_addc_u32 s1, s1, s2
	s_add_u32 s44, s0, 0x100000
	s_addc_u32 s45, s1, 0
	s_add_u32 s46, s0, 0x600000
	s_addc_u32 s47, s1, 0
	v_mov_b32_e32 v10, v191
	s_ashr_i32 s48, s40, 31
	v_writelane_b32 v255, s2, 23
	s_cmpk_gt_i32 s40, 0x4ff
	v_readfirstlane_b32 s1, v10
	s_mov_b64 s[10:11], -1
	s_cbranch_scc0 .LBB0_201
	s_cmpk_gt_u32 s40, 0x5ff
	s_cbranch_scc0 .LBB0_197
	s_mov_b64 s[10:11], 0
	s_cmpk_gt_u32 s40, 0x617
	s_mov_b64 s[8:9], 0
	s_cbranch_scc1 .LBB0_197
	s_add_i32 s8, s40, 0xfffffa00
	s_cmp_gt_u32 s8, 19
	s_mov_b64 s[2:3], -1
	s_cbranch_scc0 .LBB0_194
	s_add_i32 s0, s40, 0xfffff9ec
	s_lshr_b32 s0, s0, 1
	s_add_i32 s74, s0, 0x80
	s_lshl_b32 s0, s40, 19
	s_and_b32 s49, s40, 1
	s_and_b32 s0, s0, 0x80000
	s_add_u32 s4, s46, s0
	s_addc_u32 s5, s47, 0
	s_lshl_b64 s[2:3], s[74:75], 19
	s_add_u32 s6, s42, s2
	s_addc_u32 s7, s43, s3
	s_mov_b64 s[2:3], 0
	s_mov_b32 s14, s74

; #define PG8_STAGE(bufoff, gbase, voff) do { _Pragma("unroll") for (int _i = 0; _i < 2; ++_i) \
;         __builtin_amdgcn_global_load_lds((const unsigned*)((const char*)(gbase) + (voff)[_i]), (PG8_LAS unsigned*)(lds + (bufoff) + ldsw + _i * 8192), 16, 0, 0); } while (0)
; #define PG8_BAR __builtin_amdgcn_s_barrier()
; template <class Epi, class Sched, bool ALIGN_EPI = false, bool SP2 = false>
; __device__ __forceinline__ void gemm_phase(PG8_LAS unsigned char* lds, const int Kdim, const Sched& S, const Epi& E) {
;     int tid_o = threadIdx.x; asm volatile("" : "+v"(tid_o));
;     const int tid = tid_o, wid = __builtin_amdgcn_readfirstlane(tid >> 6), lane = tid & 63, wr = wid >> 2, wc = wid & 3, fr = lane & 15, fq = lane >> 4;
;     const int K = Kdim;
;     unsigned voffA[2], voffB[2]; int aoff, boff;
;     ...
;     PG8_ADDR_SETUP(tid);
;     ...
;     if constexpr (SP2) {
;         PG8_STAGE(PG8_SB(0, 0), cB, voffB); PG8_STAGE(PG8_SB(0, 1), cB + hstep, voffB); PG8_STAGE(PG8_SA(0, 0), cA, voffA); PG8_STAGE(PG8_SA(0, 1), cA + hstep, voffA);
;         if (wr == 1) PG8_BAR;
.LBB0_203:
	v_bfe_i32 v2, v10, 27, 1
	v_lshlrev_b32_e32 v1, 4, v10
	v_lshrrev_b32_e32 v2, 22, v2
	v_add_u32_e32 v2, v1, v2
	v_and_b32_e32 v2, 0xfffffc00, v2
	v_sub_u32_e32 v2, v1, v2
	v_ashrrev_i32_e32 v0, 31, v10
	v_lshrrev_b32_e32 v3, 4, v2
	v_lshrrev_b32_e32 v0, 26, v0
	v_bitop3_b32 v2, v3, v2, 32 bitop3:0x6c
	v_add_u32_e32 v0, v10, v0
	v_ashrrev_i32_e32 v4, 31, v2
	v_ashrrev_i32_e32 v0, 6, v0
	v_lshrrev_b32_e32 v4, 26, v4
	v_lshlrev_b32_e32 v3, 3, v0
	v_add_u32_e32 v4, v2, v4
	v_and_b32_e32 v3, -16, v3
	v_ashrrev_i32_e32 v5, 6, v4
	v_and_b32_e32 v4, 0xc0, v4
	v_add_u32_e32 v3, v5, v3
	v_sub_u32_e32 v2, v2, v4
	v_lshlrev_b32_e32 v0, 5, v0
	v_ashrrev_i16_sdwa v2, v207, sext(v2) dst_sel:DWORD dst_unused:UNUSED_PAD src0_sel:DWORD src1_sel:BYTE_0
	v_lshlrev_b32_e32 v4, 1, v3
	v_lshrrev_b32_e32 v6, 2, v3
	v_and_b32_e32 v5, 3, v5
	s_mov_b32 s3, 0x1fffe0
	v_and_b32_e32 v0, 32, v0
	v_bfe_i32 v2, v2, 0, 16
	v_and_b32_e32 v4, 24, v4
	v_and_b32_e32 v6, 4, v6
	v_and_or_b32 v5, v3, s3, v5
	v_or3_b32 v4, v5, v6, v4
	v_add_lshl_u32 v2, v0, v2, 1
	v_add_u32_e32 v1, 0x2000, v1
	v_lshl_add_u32 v0, v3, 11, v2
	v_lshl_add_u32 v128, v4, 11, v2
	v_ashrrev_i32_e32 v2, 31, v1
	v_lshrrev_b32_e32 v2, 22, v2
	v_add_u32_e32 v2, v1, v2
	v_ashrrev_i32_e32 v2, 10, v2
	v_mul_i32_i24_e32 v3, 0x400, v2
	v_sub_u32_e32 v1, v1, v3
	v_lshrrev_b32_e32 v3, 4, v1
	v_bitop3_b32 v1, v3, v1, 32 bitop3:0x6c
	v_ashrrev_i32_e32 v4, 31, v1
	v_lshrrev_b32_e32 v4, 26, v4
	v_lshlrev_b32_e32 v3, 3, v2
	v_add_u32_e32 v4, v1, v4
	v_and_b32_e32 v3, -16, v3
	v_ashrrev_i32_e32 v5, 6, v4
	s_mov_b64 s[10:11], s[88:89]
	v_add_u32_e32 v3, v5, v3
	v_and_b32_e32 v5, 3, v5
	s_ashr_i32 s9, s1, 6
	v_and_or_b32 v5, v3, s3, v5
	s_lshl_b32 s15, s9, 5
	s_lshl_b32 s3, s9, 10
	v_readlane_b32 s10, v255, 52
	v_readlane_b32 s11, v255, 53
	s_nop 4
	s_lshl_b32 s2, s2, 8
	s_add_i32 s50, s41, 0x22100
	s_lshl_b32 s9, s9, 9
	s_ashr_i32 s8, s1, 8
	s_add_i32 s51, s50, s9
	s_ashr_i32 s9, s2, 31
	s_ashr_i32 s52, s15, 31
	v_and_b32_e32 v4, 0xc0, v4
	s_add_u32 s12, s2, s15
	v_sub_u32_e32 v1, v1, v4
	s_addc_u32 s13, s9, s52
	v_lshlrev_b32_e32 v2, 5, v2
	v_ashrrev_i16_sdwa v1, v207, sext(v1) dst_sel:DWORD dst_unused:UNUSED_PAD src0_sel:DWORD src1_sel:BYTE_0
	s_lshl_b64 s[12:13], s[12:13], 4
	v_and_b32_e32 v152, 63, v10
	v_and_b32_e32 v2, 32, v2
	v_bfe_i32 v1, v1, 0, 16
	v_lshlrev_b32_e32 v4, 1, v3
	v_lshrrev_b32_e32 v6, 2, v3
	s_waitcnt lgkmcnt(0)
	s_add_u32 s10, s10, s12
	v_and_b32_e32 v4, 24, v4
	v_and_b32_e32 v6, 4, v6
	v_add_lshl_u32 v1, v2, v1, 1
	s_addc_u32 s11, s11, s13
	v_lshlrev_b32_e32 v146, 2, v152
	v_mov_b32_e32 v147, v189
	v_or3_b32 v4, v5, v6, v4
	v_lshl_add_u32 v132, v3, 11, v1
	v_lshl_add_u64 v[2:3], s[10:11], 0, v[146:147]
	s_mov_b64 s[10:11], 0xa700000
	s_add_i32 s53, s41, 0x10000
	v_lshl_add_u32 v130, v4, 11, v1
	v_lshl_add_u64 v[4:5], v[2:3], 0, s[10:11]
	s_mov_b32 m0, s51
	s_add_i32 s54, s53, s3
	global_load_lds_dword v[4:5], off
	s_mov_b64 s[10:11], 0xa700100
	s_add_i32 m0, s51, 0x100
	s_add_i32 s55, s54, 0x2000
	v_lshl_add_u64 v[2:3], v[2:3], 0, s[10:11]
	s_add_u32 s10, s6, 0x40000
	global_load_lds_dword v[2:3], off
	s_mov_b32 m0, s54
	s_addc_u32 s11, s7, 0
	s_add_i32 s56, s41, 0x14000
	global_load_lds_dwordx4 v128, s[6:7]
	s_mov_b32 m0, s55
	s_add_i32 s57, s56, s3
	global_load_lds_dwordx4 v130, s[6:7]
	s_mov_b32 m0, s57
	s_add_i32 s58, s57, 0x2000
	s_add_i32 s59, s41, s3
	global_load_lds_dwordx4 v128, s[10:11]
	s_mov_b32 m0, s58
	s_add_i32 s60, s59, 0x2000
	global_load_lds_dwordx4 v130, s[10:11]
	s_mov_b32 m0, s59
	s_add_u32 s10, s4, 0x40000
	global_load_lds_dwordx4 v0, s[4:5]
	s_mov_b32 m0, s60
	s_addc_u32 s11, s5, 0
	s_add_i32 s61, s59, 0x4000
	global_load_lds_dwordx4 v132, s[4:5]
	s_mov_b32 m0, s61
	s_add_i32 s62, s59, 0x6000
	global_load_lds_dwordx4 v0, s[10:11]
	s_mov_b32 m0, s62
	v_mov_b32_e32 v129, v189
	global_load_lds_dwordx4 v132, s[10:11]
	v_mov_b32_e32 v131, v189
	v_mov_b32_e32 v1, v189
	v_mov_b32_e32 v133, v189
	s_cmp_eq_u32 s8, 1
	v_lshl_add_u64 v[8:9], s[6:7], 0, v[128:129]
	v_lshl_add_u64 v[6:7], s[6:7], 0, v[130:131]
	v_lshl_add_u64 v[2:3], s[4:5], 0, v[0:1]
	s_cselect_b64 s[16:17], -1, 0
	s_cmp_lg_u32 s8, 1
	v_lshl_add_u64 v[4:5], s[4:5], 0, v[132:133]
	s_cbranch_scc1 .LBB0_205
	s_barrier

; #define LAS __attribute__((address_space(3)))
;     __device__ __forceinline__ void operator()(f32x4 (&acc)[2][2][4][2], const Unit& u, int ui, int wr, int wc, int fr, int fq, int lane, LAS unsigned char* lds) const {
;     ...
;         unsigned char* wsb = (unsigned char*)karg(20); float* outb = (float*)karg(19);
;         const LAS f32x4* pre = (const LAS f32x4*)(lds + EXTRA_OFF + X_PRE) + (ui & 1) * 256; bf16_t* P5 = (bf16_t*)(wsb + WS_P5); bf16_t* VT = (bf16_t*)(wsb + WS_VT); bf16_t* KF = (bf16_t*)(wsb + WS_KF);
;         float* okp = outb + O_KP + (size_t)l * NB * 512 * 512; float* ovp = outb + O_VP + (size_t)l * NB * 512 * 512;
;         float* oks = outb + O_KS + (size_t)l * SB * SS * 512; float* ovs = outb + O_VS + (size_t)l * SB * SS * 512;
;         asm volatile("s_waitcnt lgkmcnt(0)" ::: "memory"); __builtin_amdgcn_s_barrier(); asm volatile("" ::: "memory");
;     ...
;         } else {
;             const int tok0 = u.pn * 256 + wc * 32;
;             const float st = rstd_of(pre[32 * wc + 128 * (lane >> 5) + (lane & 31)]);
;             float cs[2][2][4];
; #pragma unroll
;             for (int bj = 0; bj < 2; ++bj)
; #pragma unroll
;                 for (int n = 0; n < 2; ++n)
; #pragma unroll
;                     for (int j = 0; j < 4; ++j) cs[bj][n][j] = __shfl(st, 32 * bj + 8 * fq + 4 * n + j);
;             const bool samp = u.pn >= 128; const bool vout = samp || (u.pn & 7) >= 6;
; #pragma unroll
;             for (int ai = 0; ai < 2; ++ai)
; #pragma unroll
;                 for (int m = 0; m < 4; ++m) {
;                     const int ch = u.pm * 256 + 128 * ai + 64 * wr + 16 * m + fr;
; #pragma unroll
;                     for (int bj = 0; bj < 2; ++bj) {
;                         f32x4 v0 = acc[ai][bj][m][0], v1 = acc[ai][bj][m][1];
; #pragma unroll
;                         for (int j = 0; j < 4; ++j) { v0[j] *= cs[bj][0][j]; v1[j] *= cs[bj][1][j]; }
;                         const int tokc = u.pn * 256 + bj * 128 + wc * 32 + 8 * fq;
;                         { u32x2 w0, w1; w0.x = cvt_pk_bf16(v0[0], v0[1]); w0.y = cvt_pk_bf16(v0[2], v0[3]); w1.x = cvt_pk_bf16(v1[0], v1[1]); w1.y = cvt_pk_bf16(v1[2], v1[3]);
;                           const unsigned vb = (((unsigned)tokc >> 4) * 512 + (unsigned)ch) * 16 + 4 * (((unsigned)tokc >> 3) & 1);
;                           *(u32x2*)(VT + vb) = w0; *(u32x2*)(VT + vb + 8) = w1; }
.LBB0_225:
	v_mov_b32_e32 v147, v153
	v_mov_b32_e32 v128, v152
	v_mov_b32_e32 v129, v154
	s_mov_b64 s[4:5], s[88:89]
	v_readlane_b32 s34, v255, 52
	v_readlane_b32 s35, v255, 53
	s_nop 4
	s_mov_b64 s[4:5], s[88:89]
	v_readlane_b32 s8, v255, 50
	v_readlane_b32 s9, v255, 51
	s_nop 4
	s_lshl_b32 s1, s1, 12
	s_and_b32 s1, s1, 0x1000
	s_waitcnt lgkmcnt(0)
	s_barrier
	s_add_i32 s76, s50, s1
	s_cmp_lg_u32 s0, 0
	v_lshlrev_b32_e32 v155, 3, v129
	s_cbranch_scc0 .LBB0_324
	s_waitcnt lgkmcnt(0)
	s_add_u32 s36, s34, 0x14f00000
	s_addc_u32 s37, s35, 0
	s_lshl_b64 s[0:1], s[20:21], 2
	s_add_u32 s0, s8, s0
	s_addc_u32 s1, s9, s1
	s_add_u32 s10, s0, 0xc200000
	s_addc_u32 s11, s1, 0
	s_lshl_b64 s[0:1], s[22:23], 2
	s_add_u32 s0, s8, s0
	s_addc_u32 s1, s9, s1
	v_lshlrev_b32_e32 v131, 6, v128
	s_add_u32 s12, s0, 0x10900000
	v_and_b32_e32 v130, 31, v128
	v_and_b32_e32 v131, 0xfffff800, v131
	s_addc_u32 s13, s1, 0
	v_add_u32_e32 v131, s76, v131
	v_lshlrev_b32_e32 v130, 4, v130
	s_lshl_b32 s0, s65, 4
	v_add3_u32 v130, v131, v130, s0
	ds_read_b128 v[130:133], v130
	s_cmpk_lt_i32 s14, 0x80
	s_cselect_b64 s[4:5], -1, 0
	s_cmpk_gt_i32 s14, 0x7f
	s_cselect_b64 s[0:1], -1, 0
	s_waitcnt lgkmcnt(0)
	v_mov_b32_e32 v134, v131
	v_mov_b32_e32 v135, v132
	v_mov_b32_e32 v131, v133
	v_pk_add_f32 v[130:131], v[134:135], v[130:131]
	s_and_b32 s6, s14, 6
	v_add_f32_e32 v130, v130, v131
	v_fmamk_f32 v130, v130, 0x3a800000, v190
	v_mul_f32_e32 v131, 0x4b800000, v130
	v_cmp_gt_f32_e32 vcc, s93, v130
	s_cmp_eq_u32 s6, 6
	s_cselect_b64 s[6:7], -1, 0
	v_cndmask_b32_e32 v130, v130, v131, vcc
	v_rsq_f32_e32 v130, v130
	s_lshl_b32 s25, s49, 8
	s_add_i32 s25, s25, s63
	v_add_u32_e32 v150, s25, v147
	v_mul_f32_e32 v131, 0x45800000, v130
	v_cndmask_b32_e32 v134, v130, v131, vcc
	v_and_b32_e32 v130, 56, v155
	v_and_or_b32 v130, v208, 64, v130
	v_lshlrev_b32_e32 v130, 2, v130
	s_lshl_b32 s25, s14, 8
	v_xor_b32_e32 v135, 0x80, v130
	v_lshlrev_b32_e32 v129, 2, v129
	s_or_b32 s25, s25, s65
	ds_bpermute_b32 v142, v130, v134
	ds_bpermute_b32 v141, v130, v134 offset:4
	ds_bpermute_b32 v140, v130, v134 offset:8
	ds_bpermute_b32 v139, v130, v134 offset:12
	ds_bpermute_b32 v148, v130, v134 offset:16
	ds_bpermute_b32 v145, v130, v134 offset:20
	ds_bpermute_b32 v144, v130, v134 offset:24
	ds_bpermute_b32 v143, v130, v134 offset:28
	ds_bpermute_b32 v133, v135, v134
	ds_bpermute_b32 v132, v135, v134 offset:4
	ds_bpermute_b32 v131, v135, v134 offset:8
	ds_bpermute_b32 v130, v135, v134 offset:12
	ds_bpermute_b32 v138, v135, v134 offset:16
	ds_bpermute_b32 v137, v135, v134 offset:20
	ds_bpermute_b32 v136, v135, v134 offset:24
	ds_bpermute_b32 v134, v135, v134 offset:28
	v_and_b32_e32 v135, 4, v129
	v_add_u32_e32 v129, s25, v155
	v_lshlrev_b32_e32 v151, 5, v129
	v_and_b32_e32 v151, 0xffffe00, v151
	v_add_u32_e32 v168, v151, v150
	v_lshl_or_b32 v168, v168, 4, v135
	v_mov_b32_e32 v169, v189
	s_waitcnt lgkmcnt(0)
	v_mul_f32_e32 v163, v124, v142
	v_mul_f32_e32 v161, v125, v141
	v_cvt_pk_bf16_f32 v164, v163, v161
	v_lshl_add_u64 v[168:169], v[168:169], 1, s[36:37]
	s_or_b64 s[0:1], s[0:1], s[6:7]
	v_mul_f32_e32 v162, v120, v148
	v_mul_f32_e32 v160, v121, v145
	v_mul_f32_e32 v159, v126, v140
	v_mul_f32_e32 v158, v122, v144
	v_mul_f32_e32 v156, v127, v139
	v_mul_f32_e32 v149, v123, v143
	v_cvt_pk_bf16_f32 v165, v159, v156
	v_cvt_pk_bf16_f32 v166, v162, v160
	v_cvt_pk_bf16_f32 v167, v158, v149
	global_store_dwordx2 v[168:169], v[164:165], off
	v_cndmask_b32_e64 v164, 0, 1, s[0:1]
	v_add_u32_e32 v157, 0x800, v150
	v_cmp_ne_u32_e64 s[6:7], 1, v164
	s_andn2_b64 vcc, exec, s[0:1]
	global_store_dwordx2 v[168:169], v[166:167], off offset:16
	s_cbranch_vccnz .LBB0_232
	s_mov_b64 s[38:39], -1
	s_and_b64 vcc, exec, s[4:5]
	s_cbranch_vccz .LBB0_229
	s_lshl_b32 s0, s14, 6
	s_and_b32 s0, s0, 0xfffffe00
	v_and_b32_e32 v164, 0x7f8, v129
	s_addk_i32 s0, 0xfa00
	v_add_u32_e32 v164, s0, v164
	s_mov_b64 s[38:39], 0

; #define LAS __attribute__((address_space(3)))
; #define PG8_BAR __builtin_amdgcn_s_barrier()
; template <class Epi, class Sched, bool ALIGN_EPI = false, bool SP2 = false>
; __device__ __forceinline__ void gemm_phase(PG8_LAS unsigned char* lds, const int Kdim, const Sched& S, const Epi& E) {
;     ...
;         asm volatile("s_waitcnt lgkmcnt(0)" ::: "memory"); E.pre_issue(cur, ui, wid, lane, lds);
;         { int t2 = threadIdx.x; asm volatile("" : "+v"(t2)); PG8_ADDR_SETUP(t2); }
;         if constexpr (ALIGN_EPI) { if (wr == 1) PG8_BAR; }
; __device__ __forceinline__ void pre_rows(const float* ssq4, int rowbase, int ui, int wid, int lane, LAS unsigned char* lds) {
;     LAS unsigned* dst = (LAS unsigned*)(lds + EXTRA_OFF + X_PRE) + (ui & 1) * 1024 + wid * 128;
;     const float* src = ssq4 + ((ptrdiff_t)rowbase + wid * 32) * 4 + lane;
;     __builtin_amdgcn_global_load_lds((const unsigned*)src, dst, 4, 0, 0);
;     __builtin_amdgcn_global_load_lds((const unsigned*)(src + 64), dst + 64, 4, 0, 0);
; }
.LBB0_454:
	s_mov_b64 s[0:1], s[88:89]
	s_cmp_eq_u32 s74, 0
	s_waitcnt lgkmcnt(0)
	s_cselect_b32 s2, s24, s28
	s_lshl_b32 s3, s79, 12
	v_readlane_b32 s0, v255, 52
	v_readlane_b32 s1, v255, 53
	s_nop 4
	s_lshl_b32 s2, s2, 8
	s_and_b32 s3, s3, 0x1000
	s_add_i32 s4, s51, s3
	s_ashr_i32 s3, s2, 31
	s_add_u32 s2, s2, s15
	s_addc_u32 s3, s3, s52
	s_lshl_b64 s[2:3], s[2:3], 4
	s_waitcnt lgkmcnt(0)
	s_add_u32 s0, s0, s2
	s_addc_u32 s1, s1, s3
	v_mov_b32_e32 v147, v189
	v_lshl_add_u64 v[0:1], s[0:1], 0, v[146:147]
	s_mov_b64 s[0:1], 0xa700000
	v_lshl_add_u64 v[2:3], v[0:1], 0, s[0:1]
	s_mov_b32 m0, s4
	s_mov_b64 s[0:1], 0xa700100
	global_load_lds_dword v[2:3], off
	v_lshl_add_u64 v[0:1], v[0:1], 0, s[0:1]
	s_add_i32 m0, s4, 0x100
	s_andn2_b64 vcc, exec, s[16:17]
	global_load_lds_dword v[0:1], off
	v_mov_b32_e32 v0, v191
	s_cbranch_vccnz .LBB0_206
	s_barrier
	s_branch .LBB0_206

; __device__ __forceinline__ unsigned xb_ld(unsigned* p)              { return __hip_atomic_load(p, __ATOMIC_RELAXED, __HIP_MEMORY_SCOPE_AGENT); }
; __device__ __forceinline__ void xcd_barrier_complete(unsigned* bar, unsigned x, unsigned& nloc, unsigned& nx) {
;     const unsigned G = gridDim.x * gridDim.y * gridDim.z;
;     unsigned sum, cnt, mine, sp = 0u;
;     for (;;) {
;         sum = 0u; cnt = 0u; mine = 0u;
; #pragma unroll
;         for (unsigned j = 0; j < 16; ++j) { const unsigned c = xb_ld(&bar[XB_XCNT(j)]); sum += c; cnt += (c > 0u) ? 1u : 0u; mine = (j == x) ? c : mine; }
; __device__ __forceinline__ void xcd_barrier(const XcdBarrier& b) {
;     asm volatile("s_waitcnt vmcnt(0)" ::: "memory");
;     __syncthreads();
;     int t_o = threadIdx.x; asm volatile("" : "+v"(t_o));
;     if (t_o == 0) {
;         unsigned* bar = b.bar;
;         __builtin_amdgcn_s_waitcnt(0);
;         unsigned nloc = b.st[0], nx = b.st[1];
;         if (nloc == 0u) { xcd_barrier_complete(bar, b.x, nloc, nx); b.st[0] = nloc; b.st[1] = nx; }
.LBB0_457:
	s_mov_b64 s[4:5], s[88:89]
	s_getreg_b32 s0, hwreg(HW_REG_XCC_ID, 0, 4)
	s_waitcnt vmcnt(0)
	v_mov_b32_e32 v0, v191
	s_waitcnt vmcnt(0) lgkmcnt(0)
	s_barrier
	s_nop 0
	v_cmp_eq_u32_e32 vcc, 0, v0
	s_and_saveexec_b64 s[2:3], vcc
	s_cbranch_execz .LBB0_509
	v_readlane_b32 s1, v255, 8
	v_readlane_b32 s4, v255, 52
	v_readlane_b32 s5, v255, 53
	s_nop 4
	s_waitcnt vmcnt(0) expcnt(0) lgkmcnt(0)
	v_mov_b32_e32 v0, s1
	ds_read_b32 v2, v0
	v_readlane_b32 s1, v255, 9
	s_and_b32 s0, s0, 15
	s_waitcnt lgkmcnt(0)
	v_cmp_ne_u32_e32 vcc, 0, v2
	v_mov_b32_e32 v0, s1
	ds_read_b32 v0, v0
	s_cbranch_vccnz .LBB0_473
	s_add_u32 s6, s4, 0x1200
	s_addc_u32 s7, s5, 0
	s_add_u32 s8, s4, 0x1400
	s_addc_u32 s9, s5, 0
	s_add_u32 s10, s4, 0x1500
	s_addc_u32 s11, s5, 0
	s_add_u32 s12, s4, 0x1600
	s_addc_u32 s13, s5, 0
	s_add_u32 s14, s4, 0x1700
	s_addc_u32 s15, s5, 0
	s_add_u32 s16, s4, 0x1800
	s_addc_u32 s17, s5, 0
	s_add_u32 s18, s4, 0x1900
	s_addc_u32 s19, s5, 0
	s_add_u32 s20, s4, 0x1a00
	s_addc_u32 s21, s5, 0
	s_add_u32 s22, s4, 0x1b00
	s_addc_u32 s23, s5, 0
	s_add_u32 s24, s4, 0x1c00
	s_addc_u32 s25, s5, 0
	s_add_u32 s26, s4, 0x1d00
	s_addc_u32 s27, s5, 0
	s_add_u32 s28, s4, 0x1e00
	s_addc_u32 s29, s5, 0
	s_add_u32 s30, s4, 0x1f00
	s_addc_u32 s31, s5, 0
	s_add_u32 s34, s4, 0x2000
	s_addc_u32 s35, s5, 0
	s_add_u32 s36, s4, 0x2100
	s_addc_u32 s37, s5, 0
	s_add_u32 s38, s4, 0x2200
	s_addc_u32 s39, s5, 0
	s_add_u32 s40, s4, 0x2300
	s_addc_u32 s41, s5, 0
	s_mov_b32 s1, 1
	s_branch .LBB0_461

; #define LAS __attribute__((address_space(3)))
; #define rel_table (karg(8))
; __global__ void __launch_bounds__(512, 2) fwd_mega(Args args) {
;     ...
;             LAS float* T = (LAS float*)lds;
;             for (int i = tid; i < 8 * 256; i += 512) { const int hh = i >> 8, j = i & 255; int rel = j - 63; rel = rel > 128 ? 128 : rel; T[hh * 256 + j] = rel_table[(size_t)l * 8 * 257 + hh * 257 + rel + 128] * LOG2E; }
.LBB0_509:
	s_or_b64 exec, exec, s[2:3]
	v_mov_b32_e32 v113, v191
	s_mov_b32 s0, s91
	s_waitcnt lgkmcnt(0)
	s_barrier
	s_mov_b64 s[0:1], s[88:89]
	v_readlane_b32 s0, v255, 52
	v_readlane_b32 s1, v255, 53
	s_nop 4
	v_readfirstlane_b32 s29, v113
	s_mov_b32 s28, s75
	s_waitcnt lgkmcnt(0)
	v_writelane_b32 v255, s0, 24
	s_nop 1
	v_writelane_b32 v255, s1, 25
	s_movk_i32 s0, 0x800
	v_cmp_gt_i32_e32 vcc, s0, v113
	s_and_saveexec_b64 s[2:3], vcc
	s_cbranch_execz .LBB0_512
	s_movk_i32 s4, 0xbf
	v_min_u32_sdwa v2, v113, s4 dst_sel:DWORD dst_unused:UNUSED_PAD src0_sel:BYTE_0 src1_sel:DWORD
	s_mul_hi_u32 s0, s82, 0x2020
	s_mul_i32 s1, s82, 0x2020
	v_lshl_add_u32 v0, v113, 2, s28
	s_mov_b64 s[4:5], 0
	v_lshlrev_b32_e32 v188, 2, v2
	v_mov_b32_e32 v1, v113

; #define st_mix (karg(4))
; #define conv_w (karg(9))
; __device__ __forceinline__ void conv_run(int run, const bf16_t* P5, bf16_t* MIX, const float* cw, const float* cg_, const float* smix, float* ocp, float* ocs, int lane) {
;     ...
;     float* op = nullptr;
;     if (samp) op = ocs + (size_t)((R0 - NP) >> 4) * 1024;
;     else if (((R0 + 16) & 2047) == 0) op = ocp + (size_t)(R0 >> 11) * 1024;
; __global__ void __launch_bounds__(512, 2) fwd_mega(Args args) {
;     ...
;             for (int run = gw; run < M / 16; run += NGW)
;                 conv_run(run, P5, MIX, conv_w + (size_t)l * 3 * 512, conv_g + (size_t)l * 512, st_mix + (size_t)l * SB * 2 * 512, out + O_CP + (size_t)l * NB * 2 * 512, out + O_CS + (size_t)l * SB * 2 * 512, lane);
.LBB0_520:
	v_readlane_b32 s14, v255, 50
	v_readlane_b32 s15, v255, 51
	s_nop 4
	s_nop 0
	v_readlane_b32 s12, v255, 50
	v_readlane_b32 s13, v255, 51
	s_nop 4
	s_andn2_b64 vcc, exec, s[16:17]
	s_cbranch_vccnz .LBB0_522

; #define st_mix (karg(4))
; #define conv_w (karg(9))
; __device__ __forceinline__ void conv_run(int run, const bf16_t* P5, bf16_t* MIX, const float* cw, const float* cg_, const float* smix, float* ocp, float* ocs, int lane) {
;     ...
;     } else if ((R0 & 2047) == 0) {
; #pragma unroll
;         for (int j = 0; j < 8; ++j) { h0[j] = 0.f; h1[j] = 0.f; }
; __global__ void __launch_bounds__(512, 2) fwd_mega(Args args) {
;     ...
;             for (int run = gw; run < M / 16; run += NGW)
;                 conv_run(run, P5, MIX, conv_w + (size_t)l * 3 * 512, conv_g + (size_t)l * 512, st_mix + (size_t)l * SB * 2 * 512, out + O_CP + (size_t)l * NB * 2 * 512, out + O_CS + (size_t)l * SB * 2 * 512, lane);
.LBB0_530:
	v_mov_b32_e32 v35, 0
	v_mov_b32_e32 v34, v35
	v_mov_b32_e32 v33, v35
	v_mov_b32_e32 v32, v35
	v_mov_b32_e32 v39, v35
	v_mov_b32_e32 v38, v35
	v_mov_b32_e32 v37, v35
	v_mov_b32_e32 v36, v35
	v_mov_b32_e32 v43, v35
	v_mov_b32_e32 v42, v35
	v_mov_b32_e32 v41, v35
	v_mov_b32_e32 v40, v35
	v_mov_b32_e32 v47, v35
	v_mov_b32_e32 v46, v35
	v_mov_b32_e32 v45, v35
	v_mov_b32_e32 v44, v35
	v_readlane_b32 s14, v255, 50
	v_readlane_b32 s15, v255, 51
	s_nop 4
	s_nop 0
	v_readlane_b32 s12, v255, 50
	v_readlane_b32 s13, v255, 51
	s_nop 4
	s_cbranch_execz .LBB0_521
	s_branch .LBB0_522

; __device__ __forceinline__ unsigned xb_ld(unsigned* p)              { return __hip_atomic_load(p, __ATOMIC_RELAXED, __HIP_MEMORY_SCOPE_AGENT); }
; __device__ __forceinline__ void xcd_barrier_complete(unsigned* bar, unsigned x, unsigned& nloc, unsigned& nx) {
;     const unsigned G = gridDim.x * gridDim.y * gridDim.z;
;     unsigned sum, cnt, mine, sp = 0u;
;     for (;;) {
;         sum = 0u; cnt = 0u; mine = 0u;
; #pragma unroll
;         for (unsigned j = 0; j < 16; ++j) { const unsigned c = xb_ld(&bar[XB_XCNT(j)]); sum += c; cnt += (c > 0u) ? 1u : 0u; mine = (j == x) ? c : mine; }
; __device__ __forceinline__ void xcd_barrier(const XcdBarrier& b) {
;     asm volatile("s_waitcnt vmcnt(0)" ::: "memory");
;     __syncthreads();
;     int t_o = threadIdx.x; asm volatile("" : "+v"(t_o));
;     if (t_o == 0) {
;         unsigned* bar = b.bar;
;         __builtin_amdgcn_s_waitcnt(0);
;         unsigned nloc = b.st[0], nx = b.st[1];
;         if (nloc == 0u) { xcd_barrier_complete(bar, b.x, nloc, nx); b.st[0] = nloc; b.st[1] = nx; }
.LBB0_574:
	s_mov_b64 s[4:5], s[88:89]
	s_getreg_b32 s0, hwreg(HW_REG_XCC_ID, 0, 4)
	s_waitcnt vmcnt(0)
	v_mov_b32_e32 v0, v191
	s_waitcnt lgkmcnt(0)
	s_barrier
	s_nop 0
	v_cmp_eq_u32_e32 vcc, 0, v0
	s_and_saveexec_b64 s[2:3], vcc
	v_readlane_b32 s94, v255, 15
	v_readlane_b32 s95, v255, 16
	v_readlane_b32 s90, v255, 14
	v_readlane_b32 s91, v255, 17
	v_readlane_b32 s95, v255, 18
	v_readlane_b32 s96, v255, 26
	v_readlane_b32 s97, v255, 27
	s_cbranch_execz .LBB0_626
	v_readlane_b32 s1, v255, 8
	v_readlane_b32 s4, v255, 52
	v_readlane_b32 s5, v255, 53
	s_nop 4
	s_waitcnt vmcnt(0) expcnt(0) lgkmcnt(0)
	v_mov_b32_e32 v0, s1
	ds_read_b32 v2, v0
	v_readlane_b32 s1, v255, 9
	s_and_b32 s0, s0, 15
	s_waitcnt lgkmcnt(0)
	v_cmp_ne_u32_e32 vcc, 0, v2
	v_mov_b32_e32 v0, s1
	ds_read_b32 v0, v0
	s_cbranch_vccnz .LBB0_590
	s_add_u32 s6, s4, 0x1200
	s_addc_u32 s7, s5, 0
	s_add_u32 s8, s4, 0x1400
	s_addc_u32 s9, s5, 0
	s_add_u32 s10, s4, 0x1500
	s_addc_u32 s11, s5, 0
	s_add_u32 s12, s4, 0x1600
	s_addc_u32 s13, s5, 0
	s_add_u32 s14, s4, 0x1700
	s_addc_u32 s15, s5, 0
	s_add_u32 s16, s4, 0x1800
	s_addc_u32 s17, s5, 0
	s_add_u32 s18, s4, 0x1900
	s_addc_u32 s19, s5, 0
	s_add_u32 s20, s4, 0x1a00
	s_addc_u32 s21, s5, 0
	s_add_u32 s22, s4, 0x1b00
	s_addc_u32 s23, s5, 0
	s_add_u32 s24, s4, 0x1c00
	s_addc_u32 s25, s5, 0
	s_add_u32 s26, s4, 0x1d00
	s_addc_u32 s27, s5, 0
	s_add_u32 s28, s4, 0x1e00
	s_addc_u32 s29, s5, 0
	s_add_u32 s30, s4, 0x1f00
	s_addc_u32 s31, s5, 0
	s_add_u32 s34, s4, 0x2000
	s_addc_u32 s35, s5, 0
	s_add_u32 s36, s4, 0x2100
	s_addc_u32 s37, s5, 0
	s_add_u32 s38, s4, 0x2200
	s_addc_u32 s39, s5, 0
	s_add_u32 s40, s4, 0x2300
	s_addc_u32 s41, s5, 0
	s_mov_b32 s1, 1
	s_branch .LBB0_578

;     __device__ __forceinline__ bool next(int i, Unit& u) const {
;         long L = (long)i * G + c; const int npr = 128 * nN;
;         u.kind = 0; u.pad = 0;
;         if (L < npr) { pg8::map_tile((int)L, 128, nN, u.pm, u.pn); u.nt = nt; u.slice = 0; u.nsplit = 1; u.tile = 0; u.a = A + (size_t)u.pm * tstep; u.b = Bt + (size_t)u.pn * tstep; return true; }
;         L -= npr; if (L >= 2 * nN * S) return false;
;         const int tile = (int)(L / S), sl = (int)(L % S), nts = nt / S;
;         u.pm = 128 + (tile & 1); u.pn = tile >> 1; u.nt = nts; u.slice = sl; u.nsplit = S; u.tile = tile;
;         u.a = A + (size_t)u.pm * tstep + (size_t)sl * nts * 128; u.b = Bt + (size_t)u.pn * tstep + (size_t)sl * nts * 128; return true;
; __global__ void __launch_bounds__(512, 2) fwd_mega(Args args) {
;     ...
;         {
;             PHASE_BEGIN
;             SchedGemm S{(const char*)MIX, (const char*)(wl + W_OUT), 4, G, bxp, 16, 1, (l * 4 + 1) * 64, TSTEP1K};
;             EpiRes E{XG, SSQ + (1u << 18)};
;             pg8::gemm_phase<EpiRes, SchedGemm, true, true>(lds, 1024, S, E);
.LBB0_626:
	s_or_b64 exec, exec, s[2:3]
	s_waitcnt lgkmcnt(0)
	v_mov_b32_e32 v0, v191
	s_mov_b32 s34, s91
	s_mov_b64 s[0:1], s[88:89]
	s_barrier
	v_readlane_b32 s10, v255, 52
	v_readlane_b32 s11, v255, 53
	s_nop 4
	v_readlane_b32 s0, v255, 22
	v_readlane_b32 s1, v255, 23
	s_mov_b32 s35, s75
	v_mov_b32_e32 v10, v191
	s_waitcnt lgkmcnt(0)
	s_add_u32 s36, s10, 0x17000000
	s_addc_u32 s37, s11, 0
	s_add_u32 s0, s10, s0
	s_addc_u32 s1, s11, s1
	s_add_u32 s38, s0, 0x700000
	s_addc_u32 s39, s1, 0
	s_cmpk_gt_i32 s34, 0x1ff
	v_readfirstlane_b32 s0, v10
	s_mov_b64 s[8:9], -1
	s_cbranch_scc0 .LBB0_629
	s_add_u32 s12, s34, 0xfffffe00
	s_addc_u32 s13, 0, -1
	v_cmp_gt_u64_e64 s[2:3], s[12:13], 7
	s_mov_b64 s[8:9], 0
	s_and_b64 vcc, exec, s[2:3]
	s_mov_b64 s[6:7], 0
	s_cbranch_vccnz .LBB0_629
	s_and_b32 s1, s12, 1
	s_or_b32 s2, s1, 0x80
	s_lshr_b32 s40, s12, 1
	s_lshl_b32 s1, s2, 19
	s_add_u32 s4, s36, s1
	s_addc_u32 s5, s37, 0
	s_lshl_b32 s1, s40, 19
	s_add_u32 s24, s38, s1
	s_addc_u32 s25, s39, 0
	s_mov_b64 s[6:7], -1

; __device__ __forceinline__ unsigned xb_ld(unsigned* p)              { return __hip_atomic_load(p, __ATOMIC_RELAXED, __HIP_MEMORY_SCOPE_AGENT); }
; __device__ __forceinline__ void xcd_barrier_complete(unsigned* bar, unsigned x, unsigned& nloc, unsigned& nx) {
;     const unsigned G = gridDim.x * gridDim.y * gridDim.z;
;     unsigned sum, cnt, mine, sp = 0u;
;     for (;;) {
;         sum = 0u; cnt = 0u; mine = 0u;
; #pragma unroll
;         for (unsigned j = 0; j < 16; ++j) { const unsigned c = xb_ld(&bar[XB_XCNT(j)]); sum += c; cnt += (c > 0u) ? 1u : 0u; mine = (j == x) ? c : mine; }
; __device__ __forceinline__ void xcd_barrier(const XcdBarrier& b) {
;     asm volatile("s_waitcnt vmcnt(0)" ::: "memory");
;     __syncthreads();
;     int t_o = threadIdx.x; asm volatile("" : "+v"(t_o));
;     if (t_o == 0) {
;         unsigned* bar = b.bar;
;         __builtin_amdgcn_s_waitcnt(0);
;         unsigned nloc = b.st[0], nx = b.st[1];
;         if (nloc == 0u) { xcd_barrier_complete(bar, b.x, nloc, nx); b.st[0] = nloc; b.st[1] = nx; }
.LBB0_668:
	s_mov_b64 s[4:5], s[88:89]
	s_getreg_b32 s0, hwreg(HW_REG_XCC_ID, 0, 4)
	s_waitcnt vmcnt(0)
	v_mov_b32_e32 v0, v191
	s_waitcnt lgkmcnt(0)
	s_barrier
	s_nop 0
	v_cmp_eq_u32_e32 vcc, 0, v0
	s_and_saveexec_b64 s[2:3], vcc
	s_cbranch_execz .LBB0_720
	v_readlane_b32 s1, v255, 8
	v_readlane_b32 s4, v255, 52
	v_readlane_b32 s5, v255, 53
	s_nop 4
	s_waitcnt vmcnt(0) expcnt(0) lgkmcnt(0)
	v_mov_b32_e32 v0, s1
	ds_read_b32 v2, v0
	v_readlane_b32 s1, v255, 9
	s_and_b32 s0, s0, 15
	s_waitcnt lgkmcnt(0)
	v_cmp_ne_u32_e32 vcc, 0, v2
	v_mov_b32_e32 v0, s1
	ds_read_b32 v0, v0
	s_cbranch_vccnz .LBB0_684
	s_add_u32 s6, s4, 0x1200
	s_addc_u32 s7, s5, 0
	s_add_u32 s8, s4, 0x1400
	s_addc_u32 s9, s5, 0
	s_add_u32 s10, s4, 0x1500
	s_addc_u32 s11, s5, 0
	s_add_u32 s12, s4, 0x1600
	s_addc_u32 s13, s5, 0
	s_add_u32 s14, s4, 0x1700
	s_addc_u32 s15, s5, 0
	s_add_u32 s16, s4, 0x1800
	s_addc_u32 s17, s5, 0
	s_add_u32 s18, s4, 0x1900
	s_addc_u32 s19, s5, 0
	s_add_u32 s20, s4, 0x1a00
	s_addc_u32 s21, s5, 0
	s_add_u32 s22, s4, 0x1b00
	s_addc_u32 s23, s5, 0
	s_add_u32 s24, s4, 0x1c00
	s_addc_u32 s25, s5, 0
	s_add_u32 s26, s4, 0x1d00
	s_addc_u32 s27, s5, 0
	s_add_u32 s28, s4, 0x1e00
	s_addc_u32 s29, s5, 0
	s_add_u32 s30, s4, 0x1f00
	s_addc_u32 s31, s5, 0
	s_add_u32 s34, s4, 0x2000
	s_addc_u32 s35, s5, 0
	s_add_u32 s36, s4, 0x2100
	s_addc_u32 s37, s5, 0
	s_add_u32 s38, s4, 0x2200
	s_addc_u32 s39, s5, 0
	s_add_u32 s40, s4, 0x2300
	s_addc_u32 s41, s5, 0
	s_mov_b32 s1, 1
	s_branch .LBB0_672

;     __device__ __forceinline__ bool next(int i, Unit& u) const {
;         long L = (long)i * G + c;
;         u.kind = 0; u.nt = 16; u.slice = 0; u.nsplit = 1; u.tile = 0;
;         if (L < 130 * 22) { pg8::map_tile((int)L, 130, 22, u.pm, u.pn); u.pad = 254 * u.pm - 2; }
;         else { L -= 130 * 22; if (L >= 44) return false; u.pm = 130 + (int)(L & 1); u.pn = (int)(L >> 1); u.pad = NP + 256 * (int)(L & 1); }
;         u.a = A + (ptrdiff_t)u.pad * 2048; u.b = Bt + (size_t)u.pn * TSTEP1K; return true;
; __global__ void __launch_bounds__(512, 2) fwd_mega(Args args) {
;     ...
;         {
;             PHASE_BEGIN
;             SchedUp S{(const char*)XG, (const char*)(wl + W_UP), G, bxp, 0};
;             EpiUp E{l};
;             pg8::gemm_phase<EpiUp, SchedUp, true, true>(lds, 1024, S, E);
.LBB0_720:
	s_or_b64 exec, exec, s[2:3]
	s_waitcnt lgkmcnt(0)
	v_mov_b32_e32 v0, v191
	s_mov_b32 s74, s91
	s_mov_b64 s[0:1], s[88:89]
	s_barrier
	v_readlane_b32 s0, v255, 52
	v_readlane_b32 s1, v255, 53
	s_nop 4
	v_readlane_b32 s2, v255, 22
	s_mov_b32 s60, s75
	v_mov_b32_e32 v10, v191
	s_waitcnt lgkmcnt(0)
	s_add_u32 s61, s0, 0x6500000
	s_addc_u32 s62, s1, 0
	s_add_u32 s0, s0, s2
	v_readlane_b32 s2, v255, 23
	s_addc_u32 s1, s1, s2
	s_add_u32 s63, s0, 0x900000
	s_addc_u32 s64, s1, 0
	s_cmpk_gt_i32 s74, 0xb2b
	v_readfirstlane_b32 s18, v10
	s_cbranch_scc0 .LBB0_726
	s_mov_b64 s[6:7], 0
	s_cmpk_lt_u32 s74, 0xb58
	s_mov_b64 s[4:5], 0
	s_cbranch_scc0 .LBB0_725
	s_add_u32 s2, s74, 0xfffff4d4
	s_addc_u32 s3, 0, 1
	s_and_b32 s1, s74, 1
	s_or_b32 s0, s1, 0x82
	s_lshl_b32 s1, s1, 8
	s_lshr_b64 s[38:39], s[2:3], 1
	s_or_b32 s2, s1, 0x8000
	s_mov_b64 s[4:5], -1
	s_and_b64 vcc, exec, s[6:7]
	s_cbranch_vccnz .LBB0_727

; #define LAS __attribute__((address_space(3)))
; __device__ __forceinline__ const float* karg(int k) { kargp_t p = (kargp_t)__builtin_amdgcn_kernarg_segment_ptr(); asm volatile("" : "+s"(p)); return *(const float* const __attribute__((address_space(4)))*)(p + 8 * k); }
; __device__ __forceinline__ void pre_rows(const float* ssq4, int rowbase, int ui, int wid, int lane, LAS unsigned char* lds) {
;     LAS unsigned* dst = (LAS unsigned*)(lds + EXTRA_OFF + X_PRE) + (ui & 1) * 1024 + wid * 128;
;     const float* src = ssq4 + ((ptrdiff_t)rowbase + wid * 32) * 4 + lane;
;     __builtin_amdgcn_global_load_lds((const unsigned*)src, dst, 4, 0, 0);
;     __builtin_amdgcn_global_load_lds((const unsigned*)(src + 64), dst + 64, 4, 0, 0);
; }
;     __device__ __forceinline__ void pre_issue(const Unit& u, int ui, int wid, int lane, LAS unsigned char* lds) const {
;         pre_rows((const float*)((unsigned char*)karg(20) + WS_SSQ) + (1u << 18), u.pad, ui, wid, lane, lds);
;         const int arr = wid >> 1, hf = wid & 1;
;         const float* src = (arr < 3 ? karg(15) + (size_t)l * 3 * UPW + (size_t)arr * UPW : karg(16) + (size_t)l * UPW) + hf * DFF + u.pn * 128 + lane;
;         LAS unsigned* wd = (LAS unsigned*)(lds + EXTRA_OFF + X_W) + (ui & 1) * 1024 + arr * 256 + hf * 128;
;         __builtin_amdgcn_global_load_lds((const unsigned*)src, wd, 4, 0, 0);
;         __builtin_amdgcn_global_load_lds((const unsigned*)(src + 64), wd + 64, 4, 0, 0);
.LBB0_733:
	s_mov_b64 s[8:9], s[88:89]
	s_ashr_i32 s1, s18, 6
	s_lshl_b32 s39, s1, 5
	v_readlane_b32 s8, v255, 52
	v_readlane_b32 s9, v255, 53
	s_nop 4
	s_add_i32 s11, s60, 0x22100
	s_lshl_b32 s3, s1, 9
	s_add_i32 s65, s11, s3
	s_ashr_i32 s3, s2, 31
	s_ashr_i32 s66, s39, 31
	s_add_u32 s12, s2, s39
	s_addc_u32 s13, s3, s66
	s_lshl_b64 s[12:13], s[12:13], 4
	v_and_b32_e32 v202, 63, v10
	s_waitcnt lgkmcnt(0)
	s_add_u32 s8, s8, s12
	s_addc_u32 s9, s9, s13
	v_lshlrev_b32_e32 v194, 2, v202
	v_mov_b32_e32 v195, v189
	v_lshl_add_u64 v[0:1], s[8:9], 0, v[194:195]
	s_mov_b64 s[8:9], 0xa800000
	v_lshl_add_u64 v[2:3], v[0:1], 0, s[8:9]
	s_mov_b32 m0, s65
	s_mov_b64 s[8:9], 0xa800100
	global_load_lds_dword v[2:3], off
	v_lshl_add_u64 v[0:1], v[0:1], 0, s[8:9]
	s_add_i32 m0, s65, 0x100
	s_ashr_i32 s10, s18, 7
	global_load_lds_dword v[0:1], off
	s_mov_b32 s8, s10
	s_cmp_gt_i32 s10, 2
	v_writelane_b32 v255, s8, 24
	s_cselect_b64 s[12:13], -1, 0
	s_mov_b64 s[14:15], -1
	v_writelane_b32 v255, s9, 25
	s_and_b64 vcc, exec, s[12:13]
	s_cbranch_vccz .LBB0_735
	s_mov_b64 s[8:9], s[88:89]
	v_readlane_b32 s8, v255, 56
	v_readlane_b32 s9, v255, 57
	s_nop 4
	s_mov_b64 s[14:15], 0
.LBB0_735:
	s_andn2_b64 vcc, exec, s[14:15]
	s_mov_b32 s10, s96
	s_cbranch_vccnz .LBB0_737
	s_waitcnt lgkmcnt(0)
	v_readlane_b32 s8, v255, 54
	v_readlane_b32 s9, v255, 55
	s_nop 4
	s_mul_i32 s3, s96, 0x10800
	v_readlane_b32 s14, v255, 24
	s_mov_b32 s10, s14
	v_readlane_b32 s15, v255, 25
	s_waitcnt lgkmcnt(0)
	s_add_u32 s8, s8, s3
	s_addc_u32 s9, s9, 0

; #define LAS __attribute__((address_space(3)))
; __device__ __forceinline__ float rstd_of(f32x4 p) { return rsqrtf(((p.x + p.y) + (p.z + p.w)) * (1.0f / 1024.0f) + EPS); }
; __device__ __forceinline__ const float* karg(int k) { kargp_t p = (kargp_t)__builtin_amdgcn_kernarg_segment_ptr(); asm volatile("" : "+s"(p)); return *(const float* const __attribute__((address_space(4)))*)(p + 8 * k); }
;     __device__ __forceinline__ void operator()(f32x4 (&acc)[2][2][4][2], const Unit& u, int ui, int wr, int wc, int fr, int fq, int lane, LAS unsigned char* lds) const {
;         asm volatile("" : "+v"(fr), "+v"(fq), "+v"(lane));
;         unsigned char* wsb = (unsigned char*)karg(20); float* outb = (float*)karg(19);
;         const LAS f32x4* pre = (const LAS f32x4*)(lds + EXTRA_OFF + X_PRE) + (ui & 1) * 256; (void)wsb;
;         float* offs = outb + O_FS + (size_t)l * SB * 2 * UPW;
;         const int rbase = u.pad + wr * 64;
;         const bool samp = u.pm >= 130;
;         asm volatile("s_waitcnt lgkmcnt(0)" ::: "memory"); __builtin_amdgcn_s_barrier(); asm volatile("" ::: "memory");
;         const float st0 = rstd_of(pre[64 * wr + lane]), st1 = rstd_of(pre[128 + 64 * wr + lane]);
;         LAS float* halo = (LAS float*)(lds + EXTRA_OFF);
;         const int ccol = wc * 32 + 8 * fq;
; #pragma unroll
;         for (int ai = 0; ai < 2; ++ai)
; #pragma unroll
;             for (int m = 0; m < 4; ++m) {
;                 const float rs = __shfl(ai ? st1 : st0, 16 * m + fr);
; #pragma unroll
;                 for (int bj = 0; bj < 2; ++bj)
; #pragma unroll
;                     for (int n = 0; n < 2; ++n) acc[ai][bj][m][n] *= rs;
;             }
;         if (fr >= 14) {
; #pragma unroll
;             for (int ai = 0; ai < 2; ++ai)
; #pragma unroll
;                 for (int bj = 0; bj < 2; ++bj)
; #pragma unroll
;                     for (int n = 0; n < 2; ++n) *(LAS f32x4*)(halo + ((2 * ai + wr) * 2 + (fr - 14)) * 256 + bj * 128 + ccol + 4 * n) = acc[ai][bj][3][n];
;         }
.LBB0_758:
	v_readlane_b32 s6, v255, 11
	v_readlane_b32 s7, v255, 12
	v_mov_b32_e32 v96, v202
	v_mov_b32_e32 v139, v212
	v_mov_b32_e32 v195, v203
	s_mov_b64 s[4:5], s[6:7]
	s_lshl_b32 s1, s1, 12
	s_and_b32 s1, s1, 0x1000
	s_mov_b64 s[4:5], s[6:7]
	s_add_i32 s3, s11, s1
	v_readlane_b32 s6, v255, 50
	v_readlane_b32 s7, v255, 51
	s_nop 4
	s_waitcnt lgkmcnt(0)
	s_barrier
	v_lshl_add_u32 v100, v96, 4, s3
	ds_read_b128 v[96:99], v100
	ds_read_b128 v[100:103], v100 offset:2048
	s_mov_b32 s4, 0x3a800000
	v_lshl_add_u32 v188, v139, 3, s88
	s_waitcnt lgkmcnt(0)
	v_mov_b32_e32 v136, v97
	v_mov_b32_e32 v137, v98
	v_mov_b32_e32 v97, v99
	v_mov_b32_e32 v98, v101
	v_mov_b32_e32 v99, v102
	v_mov_b32_e32 v101, v103
	v_pk_add_f32 v[96:97], v[136:137], v[96:97]
	v_pk_add_f32 v[98:99], v[98:99], v[100:101]
	v_mov_b32_e32 v101, v96
	v_mov_b32_e32 v100, v98
	v_mov_b32_e32 v96, v99
	v_pk_add_f32 v[96:97], v[100:101], v[96:97]
	v_add_u32_e32 v99, 48, v195
	v_pk_fma_f32 v[96:97], v[96:97], s[4:5], v[190:191] op_sel_hi:[1,0,0]
	s_nop 0
	v_mul_f32_e32 v98, 0x4b800000, v97
	v_cmp_gt_f32_e32 vcc, s93, v97
	v_cmp_gt_f32_e64 s[4:5], s93, v96
	s_nop 0
	v_cndmask_b32_e32 v97, v97, v98, vcc
	v_mul_f32_e32 v98, 0x4b800000, v96
	v_rsq_f32_e32 v97, v97
	v_cndmask_b32_e64 v96, v96, v98, s[4:5]
	v_rsq_f32_e32 v96, v96
	v_mul_f32_e32 v98, 0x45800000, v97
	v_cndmask_b32_e32 v97, v97, v98, vcc
	v_mul_f32_e32 v98, 0x45800000, v96
	v_cndmask_b32_e64 v137, v96, v98, s[4:5]
	v_and_b32_e32 v96, 64, v208
	v_and_or_b32 v98, v195, 63, v96
	v_lshlrev_b32_e32 v138, 2, v98
	v_add_u32_e32 v98, 16, v195
	v_and_or_b32 v98, v98, 63, v96
	v_and_or_b32 v96, v99, 63, v96
	v_lshlrev_b32_e32 v141, 2, v96
	ds_bpermute_b32 v136, v141, v97
	v_lshlrev_b32_e32 v143, 2, v98
	v_xor_b32_e32 v145, 0x80, v138
	ds_bpermute_b32 v148, v141, v137
	ds_bpermute_b32 v146, v138, v97
	ds_bpermute_b32 v144, v143, v97
	ds_bpermute_b32 v140, v145, v97
	s_waitcnt lgkmcnt(0)
	v_pk_mul_f32 v[98:99], v[70:71], v[136:137] op_sel_hi:[1,0]
	v_pk_mul_f32 v[96:97], v[68:69], v[136:137] op_sel_hi:[1,0]
	v_pk_mul_f32 v[34:35], v[34:35], v[136:137] op_sel_hi:[1,0]
	v_pk_mul_f32 v[32:33], v[32:33], v[136:137] op_sel_hi:[1,0]
	v_pk_mul_f32 v[102:103], v[66:67], v[136:137] op_sel_hi:[1,0]
	v_pk_mul_f32 v[100:101], v[64:65], v[136:137] op_sel_hi:[1,0]
	v_pk_mul_f32 v[38:39], v[38:39], v[136:137] op_sel_hi:[1,0]
	v_pk_mul_f32 v[36:37], v[36:37], v[136:137] op_sel_hi:[1,0]
	ds_bpermute_b32 v142, v138, v137
	ds_bpermute_b32 v138, v143, v137
	ds_bpermute_b32 v136, v145, v137
	v_pk_mul_f32 v[70:71], v[62:63], v[148:149] op_sel_hi:[1,0]
	v_pk_mul_f32 v[68:69], v[60:61], v[148:149] op_sel_hi:[1,0]
	v_pk_mul_f32 v[6:7], v[6:7], v[148:149] op_sel_hi:[1,0]
	v_pk_mul_f32 v[4:5], v[4:5], v[148:149] op_sel_hi:[1,0]
	v_pk_mul_f32 v[66:67], v[50:51], v[148:149] op_sel_hi:[1,0]
	v_pk_mul_f32 v[64:65], v[48:49], v[148:149] op_sel_hi:[1,0]
	v_pk_mul_f32 v[2:3], v[2:3], v[148:149] op_sel_hi:[1,0]
	v_pk_mul_f32 v[0:1], v[0:1], v[148:149] op_sel_hi:[1,0]
	v_cmp_lt_i32_e32 vcc, 13, v195
	v_lshlrev_b32_e32 v137, 2, v188
	s_and_saveexec_b64 s[4:5], vcc
	s_cbranch_execz .LBB0_760
	v_readlane_b32 s3, v255, 35
	s_nop 1
	v_add_lshl_u32 v48, s3, v195, 10
	v_add3_u32 v48, s14, v137, v48
	ds_write_b128 v48, v[96:99]
	ds_write_b128 v48, v[32:35] offset:16
	ds_write_b128 v48, v[100:103] offset:512
	ds_write_b128 v48, v[36:39] offset:528
	ds_write_b128 v48, v[68:71] offset:4096
	ds_write_b128 v48, v[4:7] offset:4112
	ds_write_b128 v48, v[64:67] offset:4608
	ds_write_b128 v48, v[0:3] offset:4624

; #define LAS __attribute__((address_space(3)))
;     template <bool SAMP, bool BND>
;     __device__ __forceinline__ void conv_act(const f32x4 (&acc)[2][2][4][2], const Unit& u, int wr, int fr, int rbase, int ccol, LAS float* halo, const LAS float* wl_) const {
;         unsigned char* wsb = (unsigned char*)karg(20);
;         bf16_t* ACT = (bf16_t*)(wsb + WS_ACT); const float* sffn = karg(5) + (size_t)l * SB * 2 * UPW; float* offp = (float*)karg(19) + O_FP + (size_t)l * NB * 2 * UPW;
;         u32x2 keep[2][4];
; #pragma unroll
;         for (int n = 0; n < 2; ++n) {
;             f32x4 W0[2], W1[2], W2[2], BB[2];
; #pragma unroll
;             for (int bj = 0; bj < 2; ++bj) {
;                 const int tc = bj * 128 + ccol + 4 * n;
;                 W0[bj] = *(const LAS f32x4*)(wl_ + tc); W1[bj] = *(const LAS f32x4*)(wl_ + 256 + tc); W2[bj] = *(const LAS f32x4*)(wl_ + 512 + tc); BB[bj] = *(const LAS f32x4*)(wl_ + 768 + tc);
;             }
; #pragma unroll
;             for (int ai = 0; ai < 2; ++ai)
; #pragma unroll
;                 for (int m = 0; m < 4; ++m) {
;                     const int row = rbase + 128 * ai + 16 * m + fr;
;                     const bool ok = SAMP || (row < NP && !(ai == 0 && m == 0 && wr == 0 && fr < 2));
;                     const int t4 = (row + 2) & 2047;
;                     const float z1 = (BND && t4 == 2) ? 0.f : 1.f, z2 = (BND && (t4 == 2 || t4 == 3)) ? 0.f : 1.f;
;                     f32x4 a[2];
; #pragma unroll
;                     for (int bj = 0; bj < 2; ++bj) {
;                         f32x4 prev;
;                         if (SAMP) { const int s = (rbase + 128 * ai + 16 * m - NP) >> 4; prev = *(const f32x4*)(sffn + (unsigned)((s * 2 + (fr & 1)) * UPW + bj * DFF + u.pn * 128 + ccol + 4 * n)); }
;                         else if (m > 0) prev = acc[ai][bj][m > 0 ? m - 1 : 0][n];
;                         else { const int blk = 2 * ai + wr; prev = (f32x4){0.f, 0.f, 0.f, 0.f}; if (blk > 0) prev = *(const LAS f32x4*)(halo + ((blk - 1) * 2 + (fr & 1)) * 256 + bj * 128 + ccol + 4 * n); }
;                         const f32x4 cur = acc[ai][bj][m][n];
; #pragma unroll
;                         for (int j = 0; j < 4; ++j) {
;                             const float p1 = dppf<0x111>(dppf<0x121>(0.f, prev[j]), cur[j]);
;                             const float p2 = dppf<0x112>(dppf<0x122>(0.f, prev[j]), cur[j]);
.LBB0_767:
	v_readlane_b32 s2, v255, 11
	v_readlane_b32 s3, v255, 12
	s_mov_b64 s[0:1], s[2:3]
	v_readlane_b32 s0, v255, 52
	v_readlane_b32 s1, v255, 53
	s_nop 4
	v_readlane_b32 s6, v255, 30
	v_and_b32_e32 v215, 1, v195
	v_mov_b32_e32 v161, v189
	v_lshl_add_u32 v213, v188, 2, s31
	s_waitcnt lgkmcnt(0)
	s_add_u32 s4, s0, 0xaa00000
	s_addc_u32 s5, s1, 0
	s_mov_b64 s[0:1], s[2:3]
	s_load_dwordx2 s[0:1], s[0:1], 0x28
	v_mov_b32_e32 v168, v189
	v_mov_b32_e32 v174, v189
	v_mov_b32_e32 v170, v189
	v_mov_b32_e32 v172, v189
	s_waitcnt lgkmcnt(0)
	s_add_u32 s6, s0, s6
	s_addc_u32 s7, s1, s76
	s_mov_b64 s[0:1], s[2:3]
	s_add_i32 s0, s19, 0xffff8000
	s_lshr_b32 s0, s0, 3
	s_and_b32 s0, s0, 0x7ffffe
	v_or_b32_e32 v214, s0, v215
	s_movk_i32 s1, 0x1600
	v_mad_u32_u24 v164, v214, s1, v188
	s_lshl_b32 s3, s38, 7
	v_add_u32_e32 v160, s3, v164
	v_lshl_add_u64 v[160:161], v[160:161], 2, s[6:7]
	ds_read_b128 v[144:147], v213
	ds_read_b128 v[156:159], v213 offset:1024
	ds_read_b128 v[148:151], v213 offset:2048
	ds_read_b128 v[140:143], v213 offset:3072
	ds_read_b128 v[132:135], v213 offset:512
	ds_read_b128 v[152:155], v213 offset:1536
	ds_read_b128 v[136:139], v213 offset:2560
	ds_read_b128 v[128:131], v213 offset:3584
	global_load_dwordx4 v[160:163], v[160:161], off
	v_mov_b32_e32 v200, v189
	v_mov_b32_e32 v196, v189
	v_mov_b32_e32 v186, v189
	s_waitcnt vmcnt(0)
	v_mov_b32_dpp v168, v160 row_ror:1 row_mask:0xf bank_mask:0xf
	v_mov_b32_dpp v174, v160 row_ror:2 row_mask:0xf bank_mask:0xf
	v_mov_b32_e32 v160, v189
	v_mov_b32_dpp v170, v161 row_ror:1 row_mask:0xf bank_mask:0xf
	v_mov_b32_dpp v172, v161 row_ror:2 row_mask:0xf bank_mask:0xf
	v_mov_b32_dpp v160, v162 row_ror:1 row_mask:0xf bank_mask:0xf
	v_mov_b32_dpp v200, v162 row_ror:2 row_mask:0xf bank_mask:0xf
	v_mov_b32_dpp v196, v163 row_ror:1 row_mask:0xf bank_mask:0xf
	v_mov_b32_dpp v186, v163 row_ror:2 row_mask:0xf bank_mask:0xf
	v_mov_b32_dpp v168, v124 row_shr:1 row_mask:0xf bank_mask:0xf
	v_mov_b32_dpp v174, v124 row_shr:2 row_mask:0xf bank_mask:0xf
	v_mov_b32_dpp v170, v125 row_shr:1 row_mask:0xf bank_mask:0xf
	v_mov_b32_dpp v172, v125 row_shr:2 row_mask:0xf bank_mask:0xf
	v_mov_b32_dpp v160, v126 row_shr:1 row_mask:0xf bank_mask:0xf
	v_mov_b32_dpp v200, v126 row_shr:2 row_mask:0xf bank_mask:0xf
	v_mov_b32_dpp v196, v127 row_shr:1 row_mask:0xf bank_mask:0xf
	v_mov_b32_dpp v186, v127 row_shr:2 row_mask:0xf bank_mask:0xf
	s_add_i32 s2, s3, 0xb00
	v_add_u32_e32 v162, s2, v164
	v_mov_b32_e32 v163, v189
	v_lshl_add_u64 v[162:163], v[162:163], 2, s[6:7]
	global_load_dwordx4 v[216:219], v[162:163], off
	v_mov_b32_e32 v169, v189
	v_mov_b32_e32 v175, v189
	v_mov_b32_e32 v166, v124
	v_mov_b32_e32 v167, v120
	s_waitcnt lgkmcnt(5)
	v_mov_b32_e32 v162, v148
	s_waitcnt lgkmcnt(1)
	v_mov_b32_e32 v163, v136
	v_mov_b32_e32 v164, v140
	s_waitcnt lgkmcnt(0)
	v_mov_b32_e32 v165, v128
	v_pk_fma_f32 v[176:177], v[166:167], v[162:163], v[164:165]
	v_mov_b32_e32 v166, v156
	v_mov_b32_e32 v167, v152
	v_mov_b32_e32 v171, v189
	v_mov_b32_e32 v173, v189
	v_mov_b32_e32 v180, v157
	v_mov_b32_e32 v181, v153
	v_mov_b32_e32 v184, v145
	v_mov_b32_e32 v185, v133
	v_mov_b32_e32 v161, v189
	v_mov_b32_e32 v201, v189
	v_mov_b32_e32 v124, v126
	v_mov_b32_e32 v178, v158
	v_mov_b32_e32 v179, v154
	v_mov_b32_e32 v182, v146
	v_mov_b32_e32 v183, v134
	v_mov_b32_e32 v197, v189
	v_mov_b32_e32 v187, v189
	s_waitcnt vmcnt(0)
	v_mov_b32_dpp v169, v216 row_ror:1 row_mask:0xf bank_mask:0xf
	s_nop 1
	v_mov_b32_dpp v169, v120 row_shr:1 row_mask:0xf bank_mask:0xf
	v_mov_b32_dpp v175, v216 row_ror:2 row_mask:0xf bank_mask:0xf
	v_pk_fma_f32 v[176:177], v[166:167], v[168:169], v[176:177]
	v_mov_b32_e32 v168, v144
	v_mov_b32_dpp v175, v120 row_shr:2 row_mask:0xf bank_mask:0xf
	v_mov_b32_e32 v169, v132
	v_pk_fma_f32 v[198:199], v[168:169], v[174:175], v[176:177]
	v_mov_b32_dpp v171, v217 row_ror:1 row_mask:0xf bank_mask:0xf
	v_mov_b32_dpp v173, v217 row_ror:2 row_mask:0xf bank_mask:0xf
	v_mov_b32_e32 v120, v125
	v_mov_b32_e32 v174, v149
	v_mov_b32_e32 v175, v137
	v_mov_b32_e32 v176, v141
	v_mov_b32_e32 v177, v129
	v_mov_b32_dpp v171, v121 row_shr:1 row_mask:0xf bank_mask:0xf
	v_mov_b32_dpp v173, v121 row_shr:2 row_mask:0xf bank_mask:0xf
	v_pk_fma_f32 v[120:121], v[120:121], v[174:175], v[176:177]
	v_mov_b32_dpp v161, v218 row_ror:1 row_mask:0xf bank_mask:0xf
	v_pk_fma_f32 v[120:121], v[180:181], v[170:171], v[120:121]
	v_mov_b32_e32 v125, v122
	v_pk_fma_f32 v[120:121], v[184:185], v[172:173], v[120:121]
	v_mov_b32_e32 v170, v150
	v_mov_b32_e32 v171, v138
	v_mov_b32_e32 v172, v142
	v_mov_b32_e32 v173, v130
	v_mov_b32_dpp v161, v122 row_shr:1 row_mask:0xf bank_mask:0xf
	v_mov_b32_dpp v201, v218 row_ror:2 row_mask:0xf bank_mask:0xf
	v_pk_fma_f32 v[124:125], v[124:125], v[170:171], v[172:173]
	v_mov_b32_dpp v197, v219 row_ror:1 row_mask:0xf bank_mask:0xf
	v_mov_b32_dpp v201, v122 row_shr:2 row_mask:0xf bank_mask:0xf
	v_pk_fma_f32 v[124:125], v[178:179], v[160:161], v[124:125]
	v_mov_b32_dpp v187, v219 row_ror:2 row_mask:0xf bank_mask:0xf
	v_pk_fma_f32 v[200:201], v[182:183], v[200:201], v[124:125]
	v_mov_b32_e32 v122, v127
	v_mov_b32_e32 v124, v151
	v_mov_b32_e32 v125, v139
	v_mov_b32_e32 v160, v143
	v_mov_b32_e32 v161, v131
	v_mov_b32_dpp v197, v123 row_shr:1 row_mask:0xf bank_mask:0xf
	v_mov_b32_dpp v187, v123 row_shr:2 row_mask:0xf bank_mask:0xf
	v_pk_fma_f32 v[126:127], v[122:123], v[124:125], v[160:161]
	v_mov_b32_e32 v122, v159
	v_mov_b32_e32 v123, v155
	v_pk_fma_f32 v[196:197], v[122:123], v[196:197], v[126:127]
	v_mov_b32_e32 v126, v147
	v_mov_b32_e32 v127, v135
	v_pk_fma_f32 v[186:187], v[126:127], v[186:187], v[196:197]
	v_mul_f32_e32 v197, 0xbfb8aa3b, v120
	v_exp_f32_e32 v197, v197
	v_mul_f32_e32 v196, 0xbfb8aa3b, v198
	v_exp_f32_e32 v196, v196
	v_add_u32_e32 v195, s19, v195
	v_add_f32_e32 v197, 1.0, v197
	v_rcp_f32_e32 v197, v197
	v_add_f32_e32 v196, 1.0, v196
	v_rcp_f32_e32 v196, v196
	v_mul_f32_e32 v120, v120, v197
	v_mul_f32_e32 v120, v120, v121
	v_mul_f32_e32 v121, 0xbfb8aa3b, v200
	v_exp_f32_e32 v121, v121
	v_mul_f32_e32 v197, 0xbfb8aa3b, v186
	v_exp_f32_e32 v197, v197
	v_mul_f32_e32 v196, v198, v196
	v_add_f32_e32 v121, 1.0, v121
	v_rcp_f32_e32 v121, v121
	v_add_f32_e32 v197, 1.0, v197
	v_rcp_f32_e32 v197, v197
	v_mul_f32_e32 v196, v196, v199
	v_mul_f32_e32 v121, v200, v121
	v_mul_f32_e32 v121, v121, v201
	v_mul_f32_e32 v186, v186, v197
	v_mul_f32_e32 v186, v186, v187
	v_cvt_pk_bf16_f32 v120, v196, v120
	v_cvt_pk_bf16_f32 v121, v121, v186
	s_add_i32 s0, s19, 0xffff8010
	s_lshr_b32 s0, s0, 3
	s_and_b32 s0, s0, 0x7ffffe
	v_or_b32_e32 v198, s0, v215
	v_mad_u32_u24 v197, v198, s1, v188
	v_add_u32_e32 v186, s3, v197
	v_mov_b32_e32 v187, v189
	v_lshl_add_u64 v[186:187], v[186:187], 2, s[6:7]
	global_load_dwordx4 v[216:219], v[186:187], off
	v_mov_b32_e32 v200, v189
	v_mov_b32_e32 v204, v189
	v_mov_b32_e32 v220, v189
	v_mov_b32_e32 v222, v189
	v_mov_b32_e32 v224, v189
	v_mov_b32_e32 v226, v189
	v_mov_b32_e32 v186, v189
	v_mov_b32_e32 v196, v189
	s_waitcnt vmcnt(0)
; #define LAS __attribute__((address_space(3)))
; __device__ __forceinline__ unsigned cvt_pk_bf16(float lo, float hi) { unsigned r; asm volatile("v_cvt_pk_bf16_f32 %0, %1, %2" : "=v"(r) : "v"(lo), "v"(hi)); return r; }
;     template <bool SAMP, bool BND>
;     __device__ __forceinline__ void conv_act(const f32x4 (&acc)[2][2][4][2], const Unit& u, int wr, int fr, int rbase, int ccol, LAS float* halo, const LAS float* wl_) const {
;     ...
;                     for (int bj = 0; bj < 2; ++bj) {
;                         f32x4 prev;
;                         if (SAMP) { const int s = (rbase + 128 * ai + 16 * m - NP) >> 4; prev = *(const f32x4*)(sffn + (unsigned)((s * 2 + (fr & 1)) * UPW + bj * DFF + u.pn * 128 + ccol + 4 * n)); }
;                         else if (m > 0) prev = acc[ai][bj][m > 0 ? m - 1 : 0][n];
;                         else { const int blk = 2 * ai + wr; prev = (f32x4){0.f, 0.f, 0.f, 0.f}; if (blk > 0) prev = *(const LAS f32x4*)(halo + ((blk - 1) * 2 + (fr & 1)) * 256 + bj * 128 + ccol + 4 * n); }
;                         const f32x4 cur = acc[ai][bj][m][n];
; #pragma unroll
;                         for (int j = 0; j < 4; ++j) {
;                             const float p1 = dppf<0x111>(dppf<0x121>(0.f, prev[j]), cur[j]);
;                             const float p2 = dppf<0x112>(dppf<0x122>(0.f, prev[j]), cur[j]);
;                             a[bj][j] = BB[bj][j] + W2[bj][j] * cur[j] + W1[bj][j] * (BND ? p1 * z1 : p1) + W0[bj][j] * (BND ? p2 * z2 : p2);
;                         }
;                         if (BND) { if (ok && t4 < 2 && row >= 2046) *(f32x4*)(offp + (unsigned)(((((row + 2) >> 11) - 1) * 2 + t4) * UPW + bj * DFF + u.pn * 128 + ccol + 4 * n)) = cur; }
;                         __builtin_amdgcn_sched_barrier(0);
;                     }
;                     float o[4];
; #pragma unroll
;                     for (int j = 0; j < 4; ++j) { const float g = a[0][j], v = a[1][j]; o[j] = g * __builtin_amdgcn_rcpf(1.0f + __builtin_amdgcn_exp2f(-g * LOG2E)) * v; }
;                     u32x2 w; w.x = cvt_pk_bf16(o[0], o[1]); w.y = cvt_pk_bf16(o[2], o[3]);
;                     if (n == 0) keep[ai][m] = w;
;                     else if (ok) { u32x4 w4; w4.x = keep[ai][m].x; w4.y = keep[ai][m].y; w4.z = w.x; w4.w = w.y; *(u32x4*)(ACT + (unsigned)(row * DFF + u.pn * 128 + ccol)) = w4; }
	v_mov_b32_dpp v200, v216 row_ror:1 row_mask:0xf bank_mask:0xf
	v_mov_b32_dpp v204, v216 row_ror:2 row_mask:0xf bank_mask:0xf
	v_mov_b32_dpp v220, v217 row_ror:1 row_mask:0xf bank_mask:0xf
	v_mov_b32_dpp v222, v217 row_ror:2 row_mask:0xf bank_mask:0xf
	v_mov_b32_dpp v224, v218 row_ror:1 row_mask:0xf bank_mask:0xf
	v_mov_b32_dpp v226, v218 row_ror:2 row_mask:0xf bank_mask:0xf
	v_mov_b32_dpp v186, v219 row_ror:1 row_mask:0xf bank_mask:0xf
	v_mov_b32_dpp v196, v219 row_ror:2 row_mask:0xf bank_mask:0xf
	v_mov_b32_dpp v200, v112 row_shr:1 row_mask:0xf bank_mask:0xf
	v_mov_b32_dpp v204, v112 row_shr:2 row_mask:0xf bank_mask:0xf
	v_mov_b32_dpp v220, v113 row_shr:1 row_mask:0xf bank_mask:0xf
	v_mov_b32_dpp v222, v113 row_shr:2 row_mask:0xf bank_mask:0xf
	v_mov_b32_dpp v224, v114 row_shr:1 row_mask:0xf bank_mask:0xf
	v_mov_b32_dpp v226, v114 row_shr:2 row_mask:0xf bank_mask:0xf
	v_mov_b32_dpp v186, v115 row_shr:1 row_mask:0xf bank_mask:0xf
	v_mov_b32_dpp v196, v115 row_shr:2 row_mask:0xf bank_mask:0xf
	v_add_u32_e32 v216, s2, v197
	v_mov_b32_e32 v217, v189
	v_lshl_add_u64 v[216:217], v[216:217], 2, s[6:7]
	global_load_dwordx4 v[216:219], v[216:217], off
	v_mov_b32_e32 v201, v189
	v_mov_b32_e32 v205, v189
	v_mov_b32_e32 v221, v189
	v_mov_b32_e32 v223, v189
	v_mov_b32_e32 v225, v189
	v_mov_b32_e32 v227, v189
	v_mov_b32_e32 v229, v116
	v_mov_b32_e32 v187, v189
	v_mov_b32_e32 v228, v112
	v_mov_b32_e32 v197, v189
	v_pk_fma_f32 v[228:229], v[228:229], v[162:163], v[164:165]
	s_waitcnt vmcnt(0)
	v_mov_b32_dpp v201, v216 row_ror:1 row_mask:0xf bank_mask:0xf
	v_mov_b32_dpp v205, v216 row_ror:2 row_mask:0xf bank_mask:0xf
	s_nop 0
	v_mov_b32_dpp v201, v116 row_shr:1 row_mask:0xf bank_mask:0xf
	v_mov_b32_dpp v221, v217 row_ror:1 row_mask:0xf bank_mask:0xf
	v_mov_b32_dpp v205, v116 row_shr:2 row_mask:0xf bank_mask:0xf
	v_mov_b32_dpp v223, v217 row_ror:2 row_mask:0xf bank_mask:0xf
	v_mov_b32_e32 v116, v113
	v_mov_b32_dpp v225, v218 row_ror:1 row_mask:0xf bank_mask:0xf
	v_mov_b32_dpp v227, v218 row_ror:2 row_mask:0xf bank_mask:0xf
	v_mov_b32_dpp v221, v117 row_shr:1 row_mask:0xf bank_mask:0xf
	v_mov_b32_dpp v223, v117 row_shr:2 row_mask:0xf bank_mask:0xf
	v_pk_fma_f32 v[112:113], v[116:117], v[174:175], v[176:177]
	v_mov_b32_dpp v225, v118 row_shr:1 row_mask:0xf bank_mask:0xf
	v_mov_b32_dpp v227, v118 row_shr:2 row_mask:0xf bank_mask:0xf
	v_mov_b32_e32 v116, v114
	v_mov_b32_e32 v117, v118
	v_mov_b32_dpp v187, v219 row_ror:1 row_mask:0xf bank_mask:0xf
	v_mov_b32_e32 v118, v115
	v_pk_fma_f32 v[116:117], v[116:117], v[170:171], v[172:173]
	v_mov_b32_dpp v187, v119 row_shr:1 row_mask:0xf bank_mask:0xf
	v_mov_b32_dpp v197, v219 row_ror:2 row_mask:0xf bank_mask:0xf
	v_pk_fma_f32 v[114:115], v[118:119], v[124:125], v[160:161]
	v_pk_fma_f32 v[200:201], v[166:167], v[200:201], v[228:229]
	v_pk_fma_f32 v[112:113], v[180:181], v[220:221], v[112:113]
	v_pk_fma_f32 v[116:117], v[178:179], v[224:225], v[116:117]
	v_mov_b32_dpp v197, v119 row_shr:2 row_mask:0xf bank_mask:0xf
	v_pk_fma_f32 v[114:115], v[122:123], v[186:187], v[114:115]
	v_pk_fma_f32 v[200:201], v[168:169], v[204:205], v[200:201]
	v_pk_fma_f32 v[112:113], v[184:185], v[222:223], v[112:113]
	v_pk_fma_f32 v[116:117], v[182:183], v[226:227], v[116:117]
	v_pk_fma_f32 v[114:115], v[126:127], v[196:197], v[114:115]
	v_mul_f32_e32 v119, 0xbfb8aa3b, v112
	v_exp_f32_e32 v119, v119
	v_mul_f32_e32 v118, 0xbfb8aa3b, v200
	v_exp_f32_e32 v118, v118
	v_add_f32_e32 v119, 1.0, v119
	v_rcp_f32_e32 v119, v119
	v_add_f32_e32 v118, 1.0, v118
	v_rcp_f32_e32 v118, v118
	v_mul_f32_e32 v112, v112, v119
	v_mul_f32_e32 v112, v112, v113
	v_mul_f32_e32 v113, 0xbfb8aa3b, v116
	v_exp_f32_e32 v113, v113
	v_mul_f32_e32 v118, v200, v118
	v_mul_f32_e32 v118, v118, v201
	v_cvt_pk_bf16_f32 v112, v118, v112
	v_add_f32_e32 v113, 1.0, v113
	v_rcp_f32_e32 v113, v113
	s_nop 0
	v_mul_f32_e32 v113, v116, v113
	v_mul_f32_e32 v116, 0xbfb8aa3b, v114
	v_exp_f32_e32 v116, v116
	v_mul_f32_e32 v113, v113, v117
	v_add_f32_e32 v116, 1.0, v116
	v_rcp_f32_e32 v116, v116
	s_nop 0
	v_mul_f32_e32 v114, v114, v116
	v_mul_f32_e32 v114, v114, v115
	v_cvt_pk_bf16_f32 v113, v113, v114
	s_add_i32 s0, s19, 0xffff8020
	s_lshr_b32 s0, s0, 3
	s_and_b32 s0, s0, 0x7ffffe
	v_or_b32_e32 v187, s0, v215
	v_mad_u32_u24 v119, v187, s1, v188
	v_add_u32_e32 v114, s3, v119
	v_mov_b32_e32 v115, v189
	v_lshl_add_u64 v[114:115], v[114:115], 2, s[6:7]
	global_load_dwordx4 v[114:117], v[114:115], off
	v_mov_b32_e32 v118, v189
	v_mov_b32_e32 v196, v189
	v_mov_b32_e32 v220, v189
	v_mov_b32_e32 v222, v189
	v_mov_b32_e32 v200, v189
	v_mov_b32_e32 v204, v189
	s_waitcnt vmcnt(0)
	v_mov_b32_dpp v118, v114 row_ror:1 row_mask:0xf bank_mask:0xf
	v_mov_b32_dpp v196, v114 row_ror:2 row_mask:0xf bank_mask:0xf
	v_mov_b32_dpp v220, v116 row_ror:1 row_mask:0xf bank_mask:0xf
	v_mov_b32_dpp v222, v116 row_ror:2 row_mask:0xf bank_mask:0xf
	v_mov_b32_e32 v114, v189
	v_mov_b32_e32 v116, v189
	v_mov_b32_dpp v200, v115 row_ror:1 row_mask:0xf bank_mask:0xf
	v_mov_b32_dpp v204, v115 row_ror:2 row_mask:0xf bank_mask:0xf
	v_mov_b32_dpp v114, v117 row_ror:1 row_mask:0xf bank_mask:0xf
	v_mov_b32_dpp v116, v117 row_ror:2 row_mask:0xf bank_mask:0xf
	v_mov_b32_dpp v118, v104 row_shr:1 row_mask:0xf bank_mask:0xf
	v_mov_b32_dpp v196, v104 row_shr:2 row_mask:0xf bank_mask:0xf
	v_mov_b32_dpp v200, v105 row_shr:1 row_mask:0xf bank_mask:0xf
	v_mov_b32_dpp v204, v105 row_shr:2 row_mask:0xf bank_mask:0xf
	v_mov_b32_dpp v220, v106 row_shr:1 row_mask:0xf bank_mask:0xf
	v_mov_b32_dpp v222, v106 row_shr:2 row_mask:0xf bank_mask:0xf
	v_mov_b32_dpp v114, v107 row_shr:1 row_mask:0xf bank_mask:0xf
	v_mov_b32_dpp v116, v107 row_shr:2 row_mask:0xf bank_mask:0xf
	v_add_u32_e32 v216, s2, v119
	v_mov_b32_e32 v217, v189
	v_lshl_add_u64 v[216:217], v[216:217], 2, s[6:7]
	global_load_dwordx4 v[216:219], v[216:217], off
	v_mov_b32_e32 v119, v189
	v_mov_b32_e32 v197, v189
	v_mov_b32_e32 v201, v189
	v_mov_b32_e32 v205, v189
	v_mov_b32_e32 v221, v189
	v_mov_b32_e32 v223, v189
	v_mov_b32_e32 v225, v108
	v_mov_b32_e32 v115, v189
	v_mov_b32_e32 v224, v104
	v_mov_b32_e32 v117, v189
	v_pk_fma_f32 v[224:225], v[224:225], v[162:163], v[164:165]
	s_waitcnt vmcnt(0)
; #define LAS __attribute__((address_space(3)))
; __device__ __forceinline__ unsigned cvt_pk_bf16(float lo, float hi) { unsigned r; asm volatile("v_cvt_pk_bf16_f32 %0, %1, %2" : "=v"(r) : "v"(lo), "v"(hi)); return r; }
;     template <bool SAMP, bool BND>
;     __device__ __forceinline__ void conv_act(const f32x4 (&acc)[2][2][4][2], const Unit& u, int wr, int fr, int rbase, int ccol, LAS float* halo, const LAS float* wl_) const {
;     ...
;                     for (int bj = 0; bj < 2; ++bj) {
;                         f32x4 prev;
;                         if (SAMP) { const int s = (rbase + 128 * ai + 16 * m - NP) >> 4; prev = *(const f32x4*)(sffn + (unsigned)((s * 2 + (fr & 1)) * UPW + bj * DFF + u.pn * 128 + ccol + 4 * n)); }
;                         else if (m > 0) prev = acc[ai][bj][m > 0 ? m - 1 : 0][n];
;                         else { const int blk = 2 * ai + wr; prev = (f32x4){0.f, 0.f, 0.f, 0.f}; if (blk > 0) prev = *(const LAS f32x4*)(halo + ((blk - 1) * 2 + (fr & 1)) * 256 + bj * 128 + ccol + 4 * n); }
;                         const f32x4 cur = acc[ai][bj][m][n];
; #pragma unroll
;                         for (int j = 0; j < 4; ++j) {
;                             const float p1 = dppf<0x111>(dppf<0x121>(0.f, prev[j]), cur[j]);
;                             const float p2 = dppf<0x112>(dppf<0x122>(0.f, prev[j]), cur[j]);
;                             a[bj][j] = BB[bj][j] + W2[bj][j] * cur[j] + W1[bj][j] * (BND ? p1 * z1 : p1) + W0[bj][j] * (BND ? p2 * z2 : p2);
;                         }
;                         if (BND) { if (ok && t4 < 2 && row >= 2046) *(f32x4*)(offp + (unsigned)(((((row + 2) >> 11) - 1) * 2 + t4) * UPW + bj * DFF + u.pn * 128 + ccol + 4 * n)) = cur; }
;                         __builtin_amdgcn_sched_barrier(0);
;                     }
;                     float o[4];
; #pragma unroll
;                     for (int j = 0; j < 4; ++j) { const float g = a[0][j], v = a[1][j]; o[j] = g * __builtin_amdgcn_rcpf(1.0f + __builtin_amdgcn_exp2f(-g * LOG2E)) * v; }
;                     u32x2 w; w.x = cvt_pk_bf16(o[0], o[1]); w.y = cvt_pk_bf16(o[2], o[3]);
;                     if (n == 0) keep[ai][m] = w;
;                     else if (ok) { u32x4 w4; w4.x = keep[ai][m].x; w4.y = keep[ai][m].y; w4.z = w.x; w4.w = w.y; *(u32x4*)(ACT + (unsigned)(row * DFF + u.pn * 128 + ccol)) = w4; }
	v_mov_b32_dpp v119, v216 row_ror:1 row_mask:0xf bank_mask:0xf
	v_mov_b32_dpp v197, v216 row_ror:2 row_mask:0xf bank_mask:0xf
	s_nop 0
	v_mov_b32_dpp v119, v108 row_shr:1 row_mask:0xf bank_mask:0xf
	v_mov_b32_dpp v201, v217 row_ror:1 row_mask:0xf bank_mask:0xf
	v_mov_b32_dpp v197, v108 row_shr:2 row_mask:0xf bank_mask:0xf
	v_mov_b32_dpp v205, v217 row_ror:2 row_mask:0xf bank_mask:0xf
	v_mov_b32_e32 v108, v105
	v_mov_b32_dpp v221, v218 row_ror:1 row_mask:0xf bank_mask:0xf
	v_mov_b32_dpp v223, v218 row_ror:2 row_mask:0xf bank_mask:0xf
	v_mov_b32_dpp v201, v109 row_shr:1 row_mask:0xf bank_mask:0xf
	v_mov_b32_dpp v205, v109 row_shr:2 row_mask:0xf bank_mask:0xf
	v_pk_fma_f32 v[104:105], v[108:109], v[174:175], v[176:177]
	v_mov_b32_dpp v221, v110 row_shr:1 row_mask:0xf bank_mask:0xf
	v_mov_b32_dpp v223, v110 row_shr:2 row_mask:0xf bank_mask:0xf
	v_mov_b32_e32 v108, v106
	v_mov_b32_e32 v109, v110
	v_mov_b32_dpp v115, v219 row_ror:1 row_mask:0xf bank_mask:0xf
	v_mov_b32_e32 v110, v107
	v_pk_fma_f32 v[108:109], v[108:109], v[170:171], v[172:173]
	v_mov_b32_dpp v115, v111 row_shr:1 row_mask:0xf bank_mask:0xf
	v_mov_b32_dpp v117, v219 row_ror:2 row_mask:0xf bank_mask:0xf
	v_pk_fma_f32 v[106:107], v[110:111], v[124:125], v[160:161]
	v_pk_fma_f32 v[118:119], v[166:167], v[118:119], v[224:225]
	v_pk_fma_f32 v[104:105], v[180:181], v[200:201], v[104:105]
	v_pk_fma_f32 v[108:109], v[178:179], v[220:221], v[108:109]
	v_mov_b32_dpp v117, v111 row_shr:2 row_mask:0xf bank_mask:0xf
	v_pk_fma_f32 v[106:107], v[122:123], v[114:115], v[106:107]
	v_pk_fma_f32 v[118:119], v[168:169], v[196:197], v[118:119]
	v_pk_fma_f32 v[104:105], v[184:185], v[204:205], v[104:105]
	v_pk_fma_f32 v[108:109], v[182:183], v[222:223], v[108:109]
	v_pk_fma_f32 v[106:107], v[126:127], v[116:117], v[106:107]
	v_mul_f32_e32 v111, 0xbfb8aa3b, v104
	v_exp_f32_e32 v111, v111
	v_mul_f32_e32 v110, 0xbfb8aa3b, v118
	v_exp_f32_e32 v110, v110
	v_add_f32_e32 v111, 1.0, v111
	v_rcp_f32_e32 v111, v111
	v_add_f32_e32 v110, 1.0, v110
	v_rcp_f32_e32 v110, v110
	v_mul_f32_e32 v104, v104, v111
	v_mul_f32_e32 v104, v104, v105
	v_mul_f32_e32 v105, 0xbfb8aa3b, v108
	v_exp_f32_e32 v105, v105
	v_mul_f32_e32 v110, v118, v110
	v_mul_f32_e32 v110, v110, v119
	v_cvt_pk_bf16_f32 v104, v110, v104
	v_add_f32_e32 v105, 1.0, v105
	v_rcp_f32_e32 v105, v105
	s_nop 0
	v_mul_f32_e32 v105, v108, v105
	v_mul_f32_e32 v108, 0xbfb8aa3b, v106
	v_exp_f32_e32 v108, v108
	v_mul_f32_e32 v105, v105, v109
	v_add_f32_e32 v108, 1.0, v108
	v_rcp_f32_e32 v108, v108
	s_nop 0
	v_mul_f32_e32 v106, v106, v108
	v_mul_f32_e32 v106, v106, v107
	v_cvt_pk_bf16_f32 v105, v105, v106
	s_add_i32 s0, s19, 0xffff8030
	s_lshr_b32 s0, s0, 3
	s_and_b32 s0, s0, 0x7ffffe
	v_or_b32_e32 v186, s0, v215
	v_mad_u32_u24 v111, v186, s1, v188
	v_add_u32_e32 v106, s3, v111
	v_mov_b32_e32 v107, v189
	v_lshl_add_u64 v[106:107], v[106:107], 2, s[6:7]
	global_load_dwordx4 v[106:109], v[106:107], off
	v_mov_b32_e32 v110, v189
	v_mov_b32_e32 v118, v189
	v_mov_b32_e32 v204, v189
	v_mov_b32_e32 v216, v189
	v_mov_b32_e32 v196, v189
	v_mov_b32_e32 v200, v189
	s_waitcnt vmcnt(0)
	v_mov_b32_dpp v110, v106 row_ror:1 row_mask:0xf bank_mask:0xf
	v_mov_b32_dpp v118, v106 row_ror:2 row_mask:0xf bank_mask:0xf
	v_mov_b32_dpp v204, v108 row_ror:1 row_mask:0xf bank_mask:0xf
	v_mov_b32_dpp v216, v108 row_ror:2 row_mask:0xf bank_mask:0xf
	v_mov_b32_e32 v106, v189
	v_mov_b32_e32 v108, v189
	v_mov_b32_dpp v196, v107 row_ror:1 row_mask:0xf bank_mask:0xf
	v_mov_b32_dpp v200, v107 row_ror:2 row_mask:0xf bank_mask:0xf
	v_mov_b32_dpp v106, v109 row_ror:1 row_mask:0xf bank_mask:0xf
	v_mov_b32_dpp v108, v109 row_ror:2 row_mask:0xf bank_mask:0xf
	v_mov_b32_dpp v110, v96 row_shr:1 row_mask:0xf bank_mask:0xf
	v_mov_b32_dpp v118, v96 row_shr:2 row_mask:0xf bank_mask:0xf
	v_mov_b32_dpp v196, v97 row_shr:1 row_mask:0xf bank_mask:0xf
	v_mov_b32_dpp v200, v97 row_shr:2 row_mask:0xf bank_mask:0xf
	v_mov_b32_dpp v204, v98 row_shr:1 row_mask:0xf bank_mask:0xf
	v_mov_b32_dpp v216, v98 row_shr:2 row_mask:0xf bank_mask:0xf
	v_mov_b32_dpp v106, v99 row_shr:1 row_mask:0xf bank_mask:0xf
	v_mov_b32_dpp v108, v99 row_shr:2 row_mask:0xf bank_mask:0xf
	v_add_u32_e32 v114, s2, v111
	v_mov_b32_e32 v115, v189
	v_lshl_add_u64 v[114:115], v[114:115], 2, s[6:7]
	global_load_dwordx4 v[114:117], v[114:115], off
	v_mov_b32_e32 v111, v189
	v_mov_b32_e32 v119, v189
	v_mov_b32_e32 v197, v189
	v_mov_b32_e32 v201, v189
	v_mov_b32_e32 v205, v189
	v_mov_b32_e32 v217, v189
	v_mov_b32_e32 v219, v100
	v_mov_b32_e32 v107, v189
	v_mov_b32_e32 v218, v96
	v_mov_b32_e32 v109, v189
	v_pk_fma_f32 v[162:163], v[218:219], v[162:163], v[164:165]
	s_waitcnt vmcnt(0)
; #define LAS __attribute__((address_space(3)))
; __device__ __forceinline__ unsigned cvt_pk_bf16(float lo, float hi) { unsigned r; asm volatile("v_cvt_pk_bf16_f32 %0, %1, %2" : "=v"(r) : "v"(lo), "v"(hi)); return r; }
;     template <bool SAMP, bool BND>
;     __device__ __forceinline__ void conv_act(const f32x4 (&acc)[2][2][4][2], const Unit& u, int wr, int fr, int rbase, int ccol, LAS float* halo, const LAS float* wl_) const {
;     ...
;                     for (int bj = 0; bj < 2; ++bj) {
;                         f32x4 prev;
;                         if (SAMP) { const int s = (rbase + 128 * ai + 16 * m - NP) >> 4; prev = *(const f32x4*)(sffn + (unsigned)((s * 2 + (fr & 1)) * UPW + bj * DFF + u.pn * 128 + ccol + 4 * n)); }
;                         else if (m > 0) prev = acc[ai][bj][m > 0 ? m - 1 : 0][n];
;                         else { const int blk = 2 * ai + wr; prev = (f32x4){0.f, 0.f, 0.f, 0.f}; if (blk > 0) prev = *(const LAS f32x4*)(halo + ((blk - 1) * 2 + (fr & 1)) * 256 + bj * 128 + ccol + 4 * n); }
;                         const f32x4 cur = acc[ai][bj][m][n];
; #pragma unroll
;                         for (int j = 0; j < 4; ++j) {
;                             const float p1 = dppf<0x111>(dppf<0x121>(0.f, prev[j]), cur[j]);
;                             const float p2 = dppf<0x112>(dppf<0x122>(0.f, prev[j]), cur[j]);
;                             a[bj][j] = BB[bj][j] + W2[bj][j] * cur[j] + W1[bj][j] * (BND ? p1 * z1 : p1) + W0[bj][j] * (BND ? p2 * z2 : p2);
;                         }
;                         if (BND) { if (ok && t4 < 2 && row >= 2046) *(f32x4*)(offp + (unsigned)(((((row + 2) >> 11) - 1) * 2 + t4) * UPW + bj * DFF + u.pn * 128 + ccol + 4 * n)) = cur; }
;                         __builtin_amdgcn_sched_barrier(0);
;                     }
;                     float o[4];
; #pragma unroll
;                     for (int j = 0; j < 4; ++j) { const float g = a[0][j], v = a[1][j]; o[j] = g * __builtin_amdgcn_rcpf(1.0f + __builtin_amdgcn_exp2f(-g * LOG2E)) * v; }
;                     u32x2 w; w.x = cvt_pk_bf16(o[0], o[1]); w.y = cvt_pk_bf16(o[2], o[3]);
;                     if (n == 0) keep[ai][m] = w;
;                     else if (ok) { u32x4 w4; w4.x = keep[ai][m].x; w4.y = keep[ai][m].y; w4.z = w.x; w4.w = w.y; *(u32x4*)(ACT + (unsigned)(row * DFF + u.pn * 128 + ccol)) = w4; }
	v_mov_b32_dpp v111, v114 row_ror:1 row_mask:0xf bank_mask:0xf
	v_mov_b32_dpp v119, v114 row_ror:2 row_mask:0xf bank_mask:0xf
	s_nop 0
	v_mov_b32_dpp v111, v100 row_shr:1 row_mask:0xf bank_mask:0xf
	v_mov_b32_dpp v197, v115 row_ror:1 row_mask:0xf bank_mask:0xf
	v_mov_b32_dpp v119, v100 row_shr:2 row_mask:0xf bank_mask:0xf
	v_mov_b32_dpp v201, v115 row_ror:2 row_mask:0xf bank_mask:0xf
	v_mov_b32_e32 v100, v97
	v_mov_b32_dpp v205, v116 row_ror:1 row_mask:0xf bank_mask:0xf
	v_mov_b32_dpp v217, v116 row_ror:2 row_mask:0xf bank_mask:0xf
	v_mov_b32_dpp v197, v101 row_shr:1 row_mask:0xf bank_mask:0xf
	v_mov_b32_dpp v201, v101 row_shr:2 row_mask:0xf bank_mask:0xf
	v_pk_fma_f32 v[96:97], v[100:101], v[174:175], v[176:177]
	v_mov_b32_dpp v205, v102 row_shr:1 row_mask:0xf bank_mask:0xf
	v_mov_b32_dpp v217, v102 row_shr:2 row_mask:0xf bank_mask:0xf
	v_mov_b32_e32 v100, v98
	v_mov_b32_e32 v101, v102
	v_mov_b32_dpp v107, v117 row_ror:1 row_mask:0xf bank_mask:0xf
	v_mov_b32_e32 v102, v99
	v_pk_fma_f32 v[100:101], v[100:101], v[170:171], v[172:173]
	v_mov_b32_dpp v107, v103 row_shr:1 row_mask:0xf bank_mask:0xf
	v_mov_b32_dpp v109, v117 row_ror:2 row_mask:0xf bank_mask:0xf
	v_pk_fma_f32 v[98:99], v[102:103], v[124:125], v[160:161]
	v_pk_fma_f32 v[110:111], v[166:167], v[110:111], v[162:163]
	v_pk_fma_f32 v[96:97], v[180:181], v[196:197], v[96:97]
	v_pk_fma_f32 v[100:101], v[178:179], v[204:205], v[100:101]
	v_mov_b32_dpp v109, v103 row_shr:2 row_mask:0xf bank_mask:0xf
	v_pk_fma_f32 v[98:99], v[122:123], v[106:107], v[98:99]
	v_pk_fma_f32 v[110:111], v[168:169], v[118:119], v[110:111]
	v_pk_fma_f32 v[96:97], v[184:185], v[200:201], v[96:97]
	v_pk_fma_f32 v[100:101], v[182:183], v[216:217], v[100:101]
	v_pk_fma_f32 v[98:99], v[126:127], v[108:109], v[98:99]
	v_mul_f32_e32 v103, 0xbfb8aa3b, v96
	v_exp_f32_e32 v103, v103
	v_mul_f32_e32 v102, 0xbfb8aa3b, v110
	v_exp_f32_e32 v102, v102
	v_add_f32_e32 v103, 1.0, v103
	v_rcp_f32_e32 v103, v103
	v_add_f32_e32 v102, 1.0, v102
	v_rcp_f32_e32 v102, v102
	v_mul_f32_e32 v96, v96, v103
	v_mul_f32_e32 v96, v96, v97
	v_mul_f32_e32 v97, 0xbfb8aa3b, v100
	v_exp_f32_e32 v97, v97
	v_mul_f32_e32 v102, v110, v102
	v_mul_f32_e32 v102, v102, v111
	v_cvt_pk_bf16_f32 v96, v102, v96
	v_add_f32_e32 v97, 1.0, v97
	v_rcp_f32_e32 v97, v97
	s_nop 0
	v_mul_f32_e32 v97, v100, v97
	v_mul_f32_e32 v100, 0xbfb8aa3b, v98
	v_exp_f32_e32 v100, v100
	v_mul_f32_e32 v97, v97, v101
	v_add_f32_e32 v100, 1.0, v100
	v_rcp_f32_e32 v100, v100
	s_nop 0
	v_mul_f32_e32 v98, v98, v100
	v_mul_f32_e32 v98, v98, v99
	v_cvt_pk_bf16_f32 v97, v97, v98
	s_add_i32 s0, s19, 0xffff8080
	s_lshr_b32 s0, s0, 3
	s_and_b32 s0, s0, 0x7ffffe
	v_or_b32_e32 v160, s0, v215
	v_mad_u32_u24 v108, v160, s1, v188
	v_add_u32_e32 v98, s3, v108
	v_mov_b32_e32 v99, v189
	v_lshl_add_u64 v[98:99], v[98:99], 2, s[6:7]
	global_load_dwordx4 v[100:103], v[98:99], off
	v_mov_b32_e32 v106, v189
	v_mov_b32_e32 v107, v189
	v_mov_b32_e32 v98, v156
	v_mov_b32_e32 v99, v144
	v_mov_b32_e32 v144, v157
	s_waitcnt vmcnt(0)
	v_mov_b32_dpp v106, v100 row_ror:1 row_mask:0xf bank_mask:0xf
	v_mov_b32_dpp v107, v100 row_ror:2 row_mask:0xf bank_mask:0xf
	s_nop 0
	v_mov_b32_dpp v106, v92 row_shr:1 row_mask:0xf bank_mask:0xf
	v_fma_f32 v100, v93, v149, v141
	v_mov_b32_dpp v107, v92 row_shr:2 row_mask:0xf bank_mask:0xf
	v_fma_f32 v92, v92, v148, v140
	v_pk_mul_f32 v[106:107], v[98:99], v[106:107]
	s_nop 0
	v_add_f32_e32 v92, v92, v106
	v_add_f32_e32 v109, v92, v107
	v_mov_b32_e32 v106, v189
	v_mov_b32_e32 v107, v189
	s_nop 0
	v_mov_b32_dpp v106, v101 row_ror:1 row_mask:0xf bank_mask:0xf
	v_mov_b32_dpp v107, v101 row_ror:2 row_mask:0xf bank_mask:0xf
	v_mov_b32_e32 v101, v189
	v_mov_b32_dpp v106, v93 row_shr:1 row_mask:0xf bank_mask:0xf
	v_mov_b32_dpp v107, v93 row_shr:2 row_mask:0xf bank_mask:0xf
	v_pk_mul_f32 v[92:93], v[144:145], v[106:107]
	v_mov_b32_dpp v101, v102 row_ror:2 row_mask:0xf bank_mask:0xf
	v_add_f32_e32 v92, v100, v92
	v_mov_b32_e32 v100, v189
	v_add_f32_e32 v110, v92, v93
	v_mov_b32_dpp v101, v94 row_shr:2 row_mask:0xf bank_mask:0xf
	v_mov_b32_dpp v100, v102 row_ror:1 row_mask:0xf bank_mask:0xf
	v_mov_b32_e32 v92, v158
	v_mov_b32_e32 v93, v146
	v_mov_b32_dpp v100, v94 row_shr:1 row_mask:0xf bank_mask:0xf
	v_fma_f32 v94, v94, v150, v142
	v_pk_mul_f32 v[100:101], v[92:93], v[100:101]
	v_mov_b32_e32 v146, v159
	v_add_f32_e32 v94, v94, v100
	v_add_f32_e32 v111, v94, v101
	v_mov_b32_e32 v100, v189
	v_mov_b32_e32 v101, v189
	v_fma_f32 v102, v95, v151, v143
	v_mov_b32_dpp v100, v103 row_ror:1 row_mask:0xf bank_mask:0xf
	v_mov_b32_dpp v101, v103 row_ror:2 row_mask:0xf bank_mask:0xf
	s_nop 0
	v_mov_b32_dpp v100, v95 row_shr:1 row_mask:0xf bank_mask:0xf
	v_mov_b32_dpp v101, v95 row_shr:2 row_mask:0xf bank_mask:0xf
	v_pk_mul_f32 v[94:95], v[146:147], v[100:101]
	s_nop 0
	v_add_f32_e32 v94, v102, v94
	v_add_f32_e32 v114, v94, v95
	v_add_u32_e32 v94, s2, v108
	v_mov_b32_e32 v95, v189
	v_lshl_add_u64 v[94:95], v[94:95], 2, s[6:7]
	global_load_dwordx4 v[100:103], v[94:95], off
	v_mov_b32_e32 v106, v189
	v_mov_b32_e32 v107, v189
	v_mov_b32_e32 v94, v152
	v_mov_b32_e32 v95, v132
	v_mov_b32_e32 v132, v153
	s_waitcnt vmcnt(0)
; #define LAS __attribute__((address_space(3)))
; __device__ __forceinline__ unsigned cvt_pk_bf16(float lo, float hi) { unsigned r; asm volatile("v_cvt_pk_bf16_f32 %0, %1, %2" : "=v"(r) : "v"(lo), "v"(hi)); return r; }
;     template <bool SAMP, bool BND>
;     __device__ __forceinline__ void conv_act(const f32x4 (&acc)[2][2][4][2], const Unit& u, int wr, int fr, int rbase, int ccol, LAS float* halo, const LAS float* wl_) const {
;     ...
;                     for (int bj = 0; bj < 2; ++bj) {
;                         f32x4 prev;
;                         if (SAMP) { const int s = (rbase + 128 * ai + 16 * m - NP) >> 4; prev = *(const f32x4*)(sffn + (unsigned)((s * 2 + (fr & 1)) * UPW + bj * DFF + u.pn * 128 + ccol + 4 * n)); }
;                         else if (m > 0) prev = acc[ai][bj][m > 0 ? m - 1 : 0][n];
;                         else { const int blk = 2 * ai + wr; prev = (f32x4){0.f, 0.f, 0.f, 0.f}; if (blk > 0) prev = *(const LAS f32x4*)(halo + ((blk - 1) * 2 + (fr & 1)) * 256 + bj * 128 + ccol + 4 * n); }
;                         const f32x4 cur = acc[ai][bj][m][n];
; #pragma unroll
;                         for (int j = 0; j < 4; ++j) {
;                             const float p1 = dppf<0x111>(dppf<0x121>(0.f, prev[j]), cur[j]);
;                             const float p2 = dppf<0x112>(dppf<0x122>(0.f, prev[j]), cur[j]);
;                             a[bj][j] = BB[bj][j] + W2[bj][j] * cur[j] + W1[bj][j] * (BND ? p1 * z1 : p1) + W0[bj][j] * (BND ? p2 * z2 : p2);
;                         }
;                         if (BND) { if (ok && t4 < 2 && row >= 2046) *(f32x4*)(offp + (unsigned)(((((row + 2) >> 11) - 1) * 2 + t4) * UPW + bj * DFF + u.pn * 128 + ccol + 4 * n)) = cur; }
;                         __builtin_amdgcn_sched_barrier(0);
;                     }
;                     float o[4];
; #pragma unroll
;                     for (int j = 0; j < 4; ++j) { const float g = a[0][j], v = a[1][j]; o[j] = g * __builtin_amdgcn_rcpf(1.0f + __builtin_amdgcn_exp2f(-g * LOG2E)) * v; }
;                     u32x2 w; w.x = cvt_pk_bf16(o[0], o[1]); w.y = cvt_pk_bf16(o[2], o[3]);
;                     if (n == 0) keep[ai][m] = w;
;                     else if (ok) { u32x4 w4; w4.x = keep[ai][m].x; w4.y = keep[ai][m].y; w4.z = w.x; w4.w = w.y; *(u32x4*)(ACT + (unsigned)(row * DFF + u.pn * 128 + ccol)) = w4; }
	v_mov_b32_dpp v106, v100 row_ror:1 row_mask:0xf bank_mask:0xf
	v_mov_b32_dpp v107, v100 row_ror:2 row_mask:0xf bank_mask:0xf
	s_nop 0
	v_mov_b32_dpp v106, v88 row_shr:1 row_mask:0xf bank_mask:0xf
	v_fma_f32 v100, v89, v137, v129
	v_mov_b32_dpp v107, v88 row_shr:2 row_mask:0xf bank_mask:0xf
	v_fma_f32 v88, v88, v136, v128
	v_pk_mul_f32 v[106:107], v[94:95], v[106:107]
	s_nop 0
	v_add_f32_e32 v88, v88, v106
	v_add_f32_e32 v108, v88, v107
	v_mov_b32_e32 v106, v189
	v_mov_b32_e32 v107, v189
	s_nop 0
	v_mov_b32_dpp v106, v101 row_ror:1 row_mask:0xf bank_mask:0xf
	v_mov_b32_dpp v107, v101 row_ror:2 row_mask:0xf bank_mask:0xf
	v_mov_b32_e32 v101, v134
	v_mov_b32_dpp v106, v89 row_shr:1 row_mask:0xf bank_mask:0xf
	v_mov_b32_dpp v107, v89 row_shr:2 row_mask:0xf bank_mask:0xf
	v_pk_mul_f32 v[88:89], v[132:133], v[106:107]
	v_mov_b32_e32 v134, v155
	v_add_f32_e32 v88, v100, v88
	v_add_f32_e32 v106, v88, v89
	v_mov_b32_e32 v88, v189
	v_mov_b32_e32 v89, v189
	v_mov_b32_e32 v100, v154
	v_mov_b32_dpp v88, v102 row_ror:1 row_mask:0xf bank_mask:0xf
	v_mov_b32_dpp v89, v102 row_ror:2 row_mask:0xf bank_mask:0xf
	s_nop 0
	v_mov_b32_dpp v88, v90 row_shr:1 row_mask:0xf bank_mask:0xf
	v_mov_b32_dpp v89, v90 row_shr:2 row_mask:0xf bank_mask:0xf
	v_fma_f32 v90, v90, v138, v130
	v_pk_mul_f32 v[88:89], v[100:101], v[88:89]
	s_nop 0
	v_add_f32_e32 v88, v90, v88
	v_add_f32_e32 v90, v88, v89
	v_mov_b32_e32 v88, v189
	v_mov_b32_e32 v89, v189
	s_nop 0
	v_mov_b32_dpp v88, v103 row_ror:1 row_mask:0xf bank_mask:0xf
	v_mov_b32_dpp v89, v103 row_ror:2 row_mask:0xf bank_mask:0xf
	s_nop 0
	v_mov_b32_dpp v88, v91 row_shr:1 row_mask:0xf bank_mask:0xf
	v_mov_b32_dpp v89, v91 row_shr:2 row_mask:0xf bank_mask:0xf
	v_fma_f32 v91, v91, v139, v131
	v_pk_mul_f32 v[88:89], v[134:135], v[88:89]
	s_nop 0
	v_add_f32_e32 v88, v91, v88
	v_add_f32_e32 v88, v88, v89
	v_mul_f32_e32 v102, 0xbfb8aa3b, v111
	v_exp_f32_e32 v102, v102
	v_mul_f32_e32 v89, 0xbfb8aa3b, v109
	v_exp_f32_e32 v89, v89
	v_mul_f32_e32 v91, 0xbfb8aa3b, v110
	v_add_f32_e32 v102, 1.0, v102
	v_rcp_f32_e32 v102, v102
	v_exp_f32_e32 v91, v91
	v_add_f32_e32 v89, 1.0, v89
	v_rcp_f32_e32 v89, v89
	v_mul_f32_e32 v102, v111, v102
	v_mul_f32_e32 v90, v102, v90
	v_mul_f32_e32 v102, 0xbfb8aa3b, v114
	v_exp_f32_e32 v102, v102
	v_add_f32_e32 v91, 1.0, v91
	v_rcp_f32_e32 v91, v91
	v_mul_f32_e32 v89, v109, v89
	v_add_f32_e32 v102, 1.0, v102
	v_rcp_f32_e32 v102, v102
	v_mul_f32_e32 v89, v89, v108
	v_mul_f32_e32 v91, v110, v91
	v_mul_f32_e32 v91, v91, v106
	v_mul_f32_e32 v102, v114, v102
	v_mul_f32_e32 v102, v102, v88
	v_cvt_pk_bf16_f32 v88, v89, v91
	v_cvt_pk_bf16_f32 v89, v90, v102
	s_add_i32 s0, s19, 0xffff8090
	s_lshr_b32 s0, s0, 3
	s_and_b32 s0, s0, 0x7ffffe
	v_or_b32_e32 v154, s0, v215
	v_mad_u32_u24 v102, v154, s1, v188
	v_add_u32_e32 v90, s3, v102
	v_mov_b32_e32 v91, v189
	v_lshl_add_u64 v[90:91], v[90:91], 2, s[6:7]
	global_load_dwordx4 v[106:109], v[90:91], off
	v_mov_b32_e32 v90, v189
	v_mov_b32_e32 v91, v189
	s_waitcnt vmcnt(0)
	v_mov_b32_dpp v90, v106 row_ror:1 row_mask:0xf bank_mask:0xf
	v_mov_b32_dpp v91, v106 row_ror:2 row_mask:0xf bank_mask:0xf
	s_nop 0
	v_mov_b32_dpp v90, v84 row_shr:1 row_mask:0xf bank_mask:0xf
	v_fma_f32 v106, v85, v149, v141
	v_mov_b32_dpp v91, v84 row_shr:2 row_mask:0xf bank_mask:0xf
	v_fma_f32 v84, v84, v148, v140
	v_pk_mul_f32 v[90:91], v[98:99], v[90:91]
	s_nop 0
	v_add_f32_e32 v84, v84, v90
	v_add_f32_e32 v103, v84, v91
	v_mov_b32_e32 v90, v189
	v_mov_b32_e32 v91, v189
	s_nop 0
	v_mov_b32_dpp v90, v107 row_ror:1 row_mask:0xf bank_mask:0xf
	v_mov_b32_dpp v91, v107 row_ror:2 row_mask:0xf bank_mask:0xf
	s_nop 0
	v_mov_b32_dpp v90, v85 row_shr:1 row_mask:0xf bank_mask:0xf
	v_mov_b32_dpp v91, v85 row_shr:2 row_mask:0xf bank_mask:0xf
	v_pk_mul_f32 v[84:85], v[144:145], v[90:91]
	s_nop 0
	v_add_f32_e32 v84, v106, v84
	v_add_f32_e32 v106, v84, v85
	v_mov_b32_e32 v84, v189
	v_mov_b32_e32 v85, v189
	s_nop 0
	v_mov_b32_dpp v84, v108 row_ror:1 row_mask:0xf bank_mask:0xf
	v_mov_b32_dpp v85, v108 row_ror:2 row_mask:0xf bank_mask:0xf
	s_nop 0
	v_mov_b32_dpp v84, v86 row_shr:1 row_mask:0xf bank_mask:0xf
	v_mov_b32_dpp v85, v86 row_shr:2 row_mask:0xf bank_mask:0xf
	v_fma_f32 v86, v86, v150, v142
	v_pk_mul_f32 v[84:85], v[92:93], v[84:85]
	s_nop 0
	v_add_f32_e32 v84, v86, v84
	v_add_f32_e32 v107, v84, v85
	v_mov_b32_e32 v84, v189
	v_mov_b32_e32 v85, v189
	v_fma_f32 v86, v87, v151, v143
	v_mov_b32_dpp v84, v109 row_ror:1 row_mask:0xf bank_mask:0xf
	v_mov_b32_dpp v85, v109 row_ror:2 row_mask:0xf bank_mask:0xf
	s_nop 0
	v_mov_b32_dpp v84, v87 row_shr:1 row_mask:0xf bank_mask:0xf
	v_mov_b32_dpp v85, v87 row_shr:2 row_mask:0xf bank_mask:0xf
	v_pk_mul_f32 v[84:85], v[146:147], v[84:85]
	s_nop 0
	v_add_f32_e32 v84, v86, v84
	v_add_f32_e32 v108, v84, v85
	v_add_u32_e32 v84, s2, v102
	v_mov_b32_e32 v85, v189
	v_lshl_add_u64 v[84:85], v[84:85], 2, s[6:7]
	global_load_dwordx4 v[84:87], v[84:85], off
	v_mov_b32_e32 v90, v189
	v_mov_b32_e32 v91, v189
	s_waitcnt vmcnt(0)
; #define LAS __attribute__((address_space(3)))
; __device__ __forceinline__ unsigned cvt_pk_bf16(float lo, float hi) { unsigned r; asm volatile("v_cvt_pk_bf16_f32 %0, %1, %2" : "=v"(r) : "v"(lo), "v"(hi)); return r; }
;     template <bool SAMP, bool BND>
;     __device__ __forceinline__ void conv_act(const f32x4 (&acc)[2][2][4][2], const Unit& u, int wr, int fr, int rbase, int ccol, LAS float* halo, const LAS float* wl_) const {
;     ...
;                     for (int bj = 0; bj < 2; ++bj) {
;                         f32x4 prev;
;                         if (SAMP) { const int s = (rbase + 128 * ai + 16 * m - NP) >> 4; prev = *(const f32x4*)(sffn + (unsigned)((s * 2 + (fr & 1)) * UPW + bj * DFF + u.pn * 128 + ccol + 4 * n)); }
;                         else if (m > 0) prev = acc[ai][bj][m > 0 ? m - 1 : 0][n];
;                         else { const int blk = 2 * ai + wr; prev = (f32x4){0.f, 0.f, 0.f, 0.f}; if (blk > 0) prev = *(const LAS f32x4*)(halo + ((blk - 1) * 2 + (fr & 1)) * 256 + bj * 128 + ccol + 4 * n); }
;                         const f32x4 cur = acc[ai][bj][m][n];
; #pragma unroll
;                         for (int j = 0; j < 4; ++j) {
;                             const float p1 = dppf<0x111>(dppf<0x121>(0.f, prev[j]), cur[j]);
;                             const float p2 = dppf<0x112>(dppf<0x122>(0.f, prev[j]), cur[j]);
;                             a[bj][j] = BB[bj][j] + W2[bj][j] * cur[j] + W1[bj][j] * (BND ? p1 * z1 : p1) + W0[bj][j] * (BND ? p2 * z2 : p2);
;                         }
;                         if (BND) { if (ok && t4 < 2 && row >= 2046) *(f32x4*)(offp + (unsigned)(((((row + 2) >> 11) - 1) * 2 + t4) * UPW + bj * DFF + u.pn * 128 + ccol + 4 * n)) = cur; }
;                         __builtin_amdgcn_sched_barrier(0);
;                     }
;                     float o[4];
; #pragma unroll
;                     for (int j = 0; j < 4; ++j) { const float g = a[0][j], v = a[1][j]; o[j] = g * __builtin_amdgcn_rcpf(1.0f + __builtin_amdgcn_exp2f(-g * LOG2E)) * v; }
;                     u32x2 w; w.x = cvt_pk_bf16(o[0], o[1]); w.y = cvt_pk_bf16(o[2], o[3]);
;                     if (n == 0) keep[ai][m] = w;
;                     else if (ok) { u32x4 w4; w4.x = keep[ai][m].x; w4.y = keep[ai][m].y; w4.z = w.x; w4.w = w.y; *(u32x4*)(ACT + (unsigned)(row * DFF + u.pn * 128 + ccol)) = w4; }
	v_mov_b32_dpp v90, v84 row_ror:1 row_mask:0xf bank_mask:0xf
	v_mov_b32_dpp v91, v84 row_ror:2 row_mask:0xf bank_mask:0xf
	s_nop 0
	v_mov_b32_dpp v90, v80 row_shr:1 row_mask:0xf bank_mask:0xf
	v_mov_b32_dpp v91, v80 row_shr:2 row_mask:0xf bank_mask:0xf
	v_fma_f32 v80, v80, v136, v128
	v_pk_mul_f32 v[90:91], v[94:95], v[90:91]
	s_nop 0
	v_add_f32_e32 v80, v80, v90
	v_add_f32_e32 v84, v80, v91
	v_mov_b32_e32 v90, v189
	v_mov_b32_e32 v91, v189
	s_nop 0
	v_mov_b32_dpp v90, v85 row_ror:1 row_mask:0xf bank_mask:0xf
	v_mov_b32_dpp v91, v85 row_ror:2 row_mask:0xf bank_mask:0xf
	v_fma_f32 v85, v81, v137, v129
	v_mov_b32_dpp v90, v81 row_shr:1 row_mask:0xf bank_mask:0xf
	v_mov_b32_dpp v91, v81 row_shr:2 row_mask:0xf bank_mask:0xf
	v_pk_mul_f32 v[80:81], v[132:133], v[90:91]
	s_nop 0
	v_add_f32_e32 v80, v85, v80
	v_add_f32_e32 v85, v80, v81
	v_mov_b32_e32 v80, v189
	v_mov_b32_e32 v81, v189
	s_nop 0
	v_mov_b32_dpp v80, v86 row_ror:1 row_mask:0xf bank_mask:0xf
	v_mov_b32_dpp v81, v86 row_ror:2 row_mask:0xf bank_mask:0xf
	s_nop 0
	v_mov_b32_dpp v80, v82 row_shr:1 row_mask:0xf bank_mask:0xf
	v_mov_b32_dpp v81, v82 row_shr:2 row_mask:0xf bank_mask:0xf
	v_fma_f32 v82, v82, v138, v130
	v_pk_mul_f32 v[80:81], v[100:101], v[80:81]
	s_nop 0
	v_add_f32_e32 v80, v82, v80
	v_add_f32_e32 v82, v80, v81
	v_mov_b32_e32 v80, v189
	v_mov_b32_e32 v81, v189
	s_nop 0
	v_mov_b32_dpp v80, v87 row_ror:1 row_mask:0xf bank_mask:0xf
	v_mov_b32_dpp v81, v87 row_ror:2 row_mask:0xf bank_mask:0xf
	s_nop 0
	v_mov_b32_dpp v80, v83 row_shr:1 row_mask:0xf bank_mask:0xf
	v_mov_b32_dpp v81, v83 row_shr:2 row_mask:0xf bank_mask:0xf
	v_fma_f32 v83, v83, v139, v131
	v_pk_mul_f32 v[80:81], v[134:135], v[80:81]
	s_nop 0
	v_add_f32_e32 v80, v83, v80
	v_add_f32_e32 v80, v80, v81
	v_mul_f32_e32 v81, 0xbfb8aa3b, v103
	v_exp_f32_e32 v81, v81
	v_mul_f32_e32 v83, 0xbfb8aa3b, v106
	v_exp_f32_e32 v83, v83
	v_add_f32_e32 v81, 1.0, v81
	v_rcp_f32_e32 v81, v81
	v_add_f32_e32 v83, 1.0, v83
	v_rcp_f32_e32 v83, v83
	v_mul_f32_e32 v81, v103, v81
	v_mul_f32_e32 v81, v81, v84
	v_mul_f32_e32 v84, 0xbfb8aa3b, v107
	v_exp_f32_e32 v84, v84
	v_mul_f32_e32 v83, v106, v83
	v_mul_f32_e32 v83, v83, v85
	v_add_f32_e32 v84, 1.0, v84
	v_rcp_f32_e32 v84, v84
	s_nop 0
	v_mul_f32_e32 v84, v107, v84
	v_mul_f32_e32 v82, v84, v82
	v_mul_f32_e32 v84, 0xbfb8aa3b, v108
	v_exp_f32_e32 v84, v84
	s_nop 0
	v_add_f32_e32 v84, 1.0, v84
	v_rcp_f32_e32 v84, v84
	s_nop 0
	v_mul_f32_e32 v84, v108, v84
	v_mul_f32_e32 v84, v84, v80
	v_cvt_pk_bf16_f32 v80, v81, v83
	v_cvt_pk_bf16_f32 v81, v82, v84
	s_add_i32 s0, s19, 0xffff80a0
	s_lshr_b32 s0, s0, 3
	s_and_b32 s0, s0, 0x7ffffe
	v_or_b32_e32 v153, s0, v215
	v_mad_u32_u24 v90, v153, s1, v188
	v_add_u32_e32 v82, s3, v90
	v_mov_b32_e32 v83, v189
	v_lshl_add_u64 v[82:83], v[82:83], 2, s[6:7]
	global_load_dwordx4 v[82:85], v[82:83], off
	v_mov_b32_e32 v86, v189
	v_mov_b32_e32 v87, v189
	s_waitcnt vmcnt(0)
	v_mov_b32_dpp v86, v82 row_ror:1 row_mask:0xf bank_mask:0xf
	v_mov_b32_dpp v87, v82 row_ror:2 row_mask:0xf bank_mask:0xf
	s_nop 0
	v_mov_b32_dpp v86, v76 row_shr:1 row_mask:0xf bank_mask:0xf
	v_fma_f32 v82, v77, v149, v141
	v_mov_b32_dpp v87, v76 row_shr:2 row_mask:0xf bank_mask:0xf
	v_fma_f32 v76, v76, v148, v140
	v_pk_mul_f32 v[86:87], v[98:99], v[86:87]
	s_nop 0
	v_add_f32_e32 v76, v76, v86
	v_add_f32_e32 v91, v76, v87
	v_mov_b32_e32 v86, v189
	v_mov_b32_e32 v87, v189
	s_nop 0
	v_mov_b32_dpp v86, v83 row_ror:1 row_mask:0xf bank_mask:0xf
	v_mov_b32_dpp v87, v83 row_ror:2 row_mask:0xf bank_mask:0xf
	s_nop 0
	v_mov_b32_dpp v86, v77 row_shr:1 row_mask:0xf bank_mask:0xf
	v_mov_b32_dpp v87, v77 row_shr:2 row_mask:0xf bank_mask:0xf
	v_pk_mul_f32 v[76:77], v[144:145], v[86:87]
	s_nop 0
	v_add_f32_e32 v76, v82, v76
	v_add_f32_e32 v86, v76, v77
	v_mov_b32_e32 v76, v189
	v_mov_b32_e32 v77, v189
	s_nop 0
	v_mov_b32_dpp v76, v84 row_ror:1 row_mask:0xf bank_mask:0xf
	v_mov_b32_dpp v77, v84 row_ror:2 row_mask:0xf bank_mask:0xf
	s_nop 0
	v_mov_b32_dpp v76, v78 row_shr:1 row_mask:0xf bank_mask:0xf
	v_mov_b32_dpp v77, v78 row_shr:2 row_mask:0xf bank_mask:0xf
	v_fma_f32 v78, v78, v150, v142
	v_pk_mul_f32 v[76:77], v[92:93], v[76:77]
	s_nop 0
	v_add_f32_e32 v76, v78, v76
	v_add_f32_e32 v84, v76, v77
	v_mov_b32_e32 v76, v189
	v_mov_b32_e32 v77, v189
	v_fma_f32 v78, v79, v151, v143
	v_mov_b32_dpp v76, v85 row_ror:1 row_mask:0xf bank_mask:0xf
	v_mov_b32_dpp v77, v85 row_ror:2 row_mask:0xf bank_mask:0xf
	s_nop 0
	v_mov_b32_dpp v76, v79 row_shr:1 row_mask:0xf bank_mask:0xf
	v_mov_b32_dpp v77, v79 row_shr:2 row_mask:0xf bank_mask:0xf
	v_pk_mul_f32 v[76:77], v[146:147], v[76:77]
	s_nop 0
	v_add_f32_e32 v76, v78, v76
	v_add_f32_e32 v85, v76, v77
	v_add_u32_e32 v76, s2, v90
	v_mov_b32_e32 v77, v189
	v_lshl_add_u64 v[76:77], v[76:77], 2, s[6:7]
	global_load_dwordx4 v[76:79], v[76:77], off
	v_mov_b32_e32 v82, v189
	v_mov_b32_e32 v83, v189
	s_waitcnt vmcnt(0)
; #define LAS __attribute__((address_space(3)))
; __device__ __forceinline__ unsigned cvt_pk_bf16(float lo, float hi) { unsigned r; asm volatile("v_cvt_pk_bf16_f32 %0, %1, %2" : "=v"(r) : "v"(lo), "v"(hi)); return r; }
;     template <bool SAMP, bool BND>
;     __device__ __forceinline__ void conv_act(const f32x4 (&acc)[2][2][4][2], const Unit& u, int wr, int fr, int rbase, int ccol, LAS float* halo, const LAS float* wl_) const {
;     ...
;                     for (int bj = 0; bj < 2; ++bj) {
;                         f32x4 prev;
;                         if (SAMP) { const int s = (rbase + 128 * ai + 16 * m - NP) >> 4; prev = *(const f32x4*)(sffn + (unsigned)((s * 2 + (fr & 1)) * UPW + bj * DFF + u.pn * 128 + ccol + 4 * n)); }
;                         else if (m > 0) prev = acc[ai][bj][m > 0 ? m - 1 : 0][n];
;                         else { const int blk = 2 * ai + wr; prev = (f32x4){0.f, 0.f, 0.f, 0.f}; if (blk > 0) prev = *(const LAS f32x4*)(halo + ((blk - 1) * 2 + (fr & 1)) * 256 + bj * 128 + ccol + 4 * n); }
;                         const f32x4 cur = acc[ai][bj][m][n];
; #pragma unroll
;                         for (int j = 0; j < 4; ++j) {
;                             const float p1 = dppf<0x111>(dppf<0x121>(0.f, prev[j]), cur[j]);
;                             const float p2 = dppf<0x112>(dppf<0x122>(0.f, prev[j]), cur[j]);
;                             a[bj][j] = BB[bj][j] + W2[bj][j] * cur[j] + W1[bj][j] * (BND ? p1 * z1 : p1) + W0[bj][j] * (BND ? p2 * z2 : p2);
;                         }
;                         if (BND) { if (ok && t4 < 2 && row >= 2046) *(f32x4*)(offp + (unsigned)(((((row + 2) >> 11) - 1) * 2 + t4) * UPW + bj * DFF + u.pn * 128 + ccol + 4 * n)) = cur; }
;                         __builtin_amdgcn_sched_barrier(0);
;                     }
;                     float o[4];
; #pragma unroll
;                     for (int j = 0; j < 4; ++j) { const float g = a[0][j], v = a[1][j]; o[j] = g * __builtin_amdgcn_rcpf(1.0f + __builtin_amdgcn_exp2f(-g * LOG2E)) * v; }
;                     u32x2 w; w.x = cvt_pk_bf16(o[0], o[1]); w.y = cvt_pk_bf16(o[2], o[3]);
;                     if (n == 0) keep[ai][m] = w;
;                     else if (ok) { u32x4 w4; w4.x = keep[ai][m].x; w4.y = keep[ai][m].y; w4.z = w.x; w4.w = w.y; *(u32x4*)(ACT + (unsigned)(row * DFF + u.pn * 128 + ccol)) = w4; }
	v_mov_b32_dpp v82, v76 row_ror:1 row_mask:0xf bank_mask:0xf
	v_mov_b32_dpp v83, v76 row_ror:2 row_mask:0xf bank_mask:0xf
	s_nop 0
	v_mov_b32_dpp v82, v72 row_shr:1 row_mask:0xf bank_mask:0xf
	v_mov_b32_dpp v83, v72 row_shr:2 row_mask:0xf bank_mask:0xf
	v_fma_f32 v72, v72, v136, v128
	v_pk_mul_f32 v[82:83], v[94:95], v[82:83]
	s_nop 0
	v_add_f32_e32 v72, v72, v82
	v_add_f32_e32 v76, v72, v83
	v_mov_b32_e32 v82, v189
	v_mov_b32_e32 v83, v189
	s_nop 0
	v_mov_b32_dpp v82, v77 row_ror:1 row_mask:0xf bank_mask:0xf
	v_mov_b32_dpp v83, v77 row_ror:2 row_mask:0xf bank_mask:0xf
	v_fma_f32 v77, v73, v137, v129
	v_mov_b32_dpp v82, v73 row_shr:1 row_mask:0xf bank_mask:0xf
	v_mov_b32_dpp v83, v73 row_shr:2 row_mask:0xf bank_mask:0xf
	v_pk_mul_f32 v[72:73], v[132:133], v[82:83]
	s_nop 0
	v_add_f32_e32 v72, v77, v72
	v_add_f32_e32 v77, v72, v73
	v_mov_b32_e32 v72, v189
	v_mov_b32_e32 v73, v189
	s_nop 0
	v_mov_b32_dpp v72, v78 row_ror:1 row_mask:0xf bank_mask:0xf
	v_mov_b32_dpp v73, v78 row_ror:2 row_mask:0xf bank_mask:0xf
	s_nop 0
	v_mov_b32_dpp v72, v74 row_shr:1 row_mask:0xf bank_mask:0xf
	v_mov_b32_dpp v73, v74 row_shr:2 row_mask:0xf bank_mask:0xf
	v_fma_f32 v74, v74, v138, v130
	v_pk_mul_f32 v[72:73], v[100:101], v[72:73]
	s_nop 0
	v_add_f32_e32 v72, v74, v72
	v_add_f32_e32 v74, v72, v73
	v_mov_b32_e32 v72, v189
	v_mov_b32_e32 v73, v189
	s_nop 0
	v_mov_b32_dpp v72, v79 row_ror:1 row_mask:0xf bank_mask:0xf
	v_mov_b32_dpp v73, v79 row_ror:2 row_mask:0xf bank_mask:0xf
	s_nop 0
	v_mov_b32_dpp v72, v75 row_shr:1 row_mask:0xf bank_mask:0xf
	v_mov_b32_dpp v73, v75 row_shr:2 row_mask:0xf bank_mask:0xf
	v_fma_f32 v75, v75, v139, v131
	v_pk_mul_f32 v[72:73], v[134:135], v[72:73]
	s_nop 0
	v_add_f32_e32 v72, v75, v72
	v_add_f32_e32 v72, v72, v73
	v_mul_f32_e32 v73, 0xbfb8aa3b, v91
	v_exp_f32_e32 v73, v73
	v_mul_f32_e32 v75, 0xbfb8aa3b, v86
	v_exp_f32_e32 v75, v75
	v_add_f32_e32 v73, 1.0, v73
	v_rcp_f32_e32 v73, v73
	v_add_f32_e32 v75, 1.0, v75
	v_rcp_f32_e32 v75, v75
	v_mul_f32_e32 v73, v91, v73
	v_mul_f32_e32 v73, v73, v76
	v_mul_f32_e32 v76, 0xbfb8aa3b, v84
	v_exp_f32_e32 v76, v76
	v_mul_f32_e32 v75, v86, v75
	v_mul_f32_e32 v75, v75, v77
	v_add_f32_e32 v76, 1.0, v76
	v_rcp_f32_e32 v76, v76
	s_nop 0
	v_mul_f32_e32 v76, v84, v76
	v_mul_f32_e32 v74, v76, v74
	v_mul_f32_e32 v76, 0xbfb8aa3b, v85
	v_exp_f32_e32 v76, v76
	s_nop 0
	v_add_f32_e32 v76, 1.0, v76
	v_rcp_f32_e32 v76, v76
	s_nop 0
	v_mul_f32_e32 v76, v85, v76
	v_mul_f32_e32 v76, v76, v72
	v_cvt_pk_bf16_f32 v72, v73, v75
	v_cvt_pk_bf16_f32 v73, v74, v76
	s_addk_i32 s19, 0x80b0
	s_lshr_b32 s0, s19, 3
	s_and_b32 s0, s0, 0x7ffffe
	v_or_b32_e32 v152, s0, v215
	v_mad_u32_u24 v82, v152, s1, v188
	v_add_u32_e32 v74, s3, v82
	v_mov_b32_e32 v75, v189
	v_lshl_add_u64 v[74:75], v[74:75], 2, s[6:7]
	global_load_dwordx4 v[74:77], v[74:75], off
	v_mov_b32_e32 v78, v189
	v_mov_b32_e32 v79, v189
	v_fmac_f32_e32 v143, v71, v151
	s_waitcnt vmcnt(0)
	v_mov_b32_dpp v78, v74 row_ror:1 row_mask:0xf bank_mask:0xf
	v_mov_b32_dpp v79, v74 row_ror:2 row_mask:0xf bank_mask:0xf
	s_nop 0
	v_mov_b32_dpp v78, v68 row_shr:1 row_mask:0xf bank_mask:0xf
	v_fma_f32 v74, v69, v149, v141
	v_mov_b32_dpp v79, v68 row_shr:2 row_mask:0xf bank_mask:0xf
	v_fma_f32 v68, v68, v148, v140
	v_pk_mul_f32 v[78:79], v[98:99], v[78:79]
	s_nop 0
	v_add_f32_e32 v68, v68, v78
	v_add_f32_e32 v83, v68, v79
	v_mov_b32_e32 v78, v189
	v_mov_b32_e32 v79, v189
	s_nop 0
	v_mov_b32_dpp v78, v75 row_ror:1 row_mask:0xf bank_mask:0xf
	v_mov_b32_dpp v79, v75 row_ror:2 row_mask:0xf bank_mask:0xf
	s_nop 0
	v_mov_b32_dpp v78, v69 row_shr:1 row_mask:0xf bank_mask:0xf
	v_mov_b32_dpp v79, v69 row_shr:2 row_mask:0xf bank_mask:0xf
	v_pk_mul_f32 v[68:69], v[144:145], v[78:79]
	s_nop 0
	v_add_f32_e32 v68, v74, v68
	v_add_f32_e32 v78, v68, v69
	v_mov_b32_e32 v68, v189
	v_mov_b32_e32 v69, v189
	s_nop 0
	v_mov_b32_dpp v68, v76 row_ror:1 row_mask:0xf bank_mask:0xf
	v_mov_b32_dpp v69, v76 row_ror:2 row_mask:0xf bank_mask:0xf
	s_nop 0
	v_mov_b32_dpp v68, v70 row_shr:1 row_mask:0xf bank_mask:0xf
	v_mov_b32_dpp v69, v70 row_shr:2 row_mask:0xf bank_mask:0xf
	v_fma_f32 v70, v70, v150, v142
	v_pk_mul_f32 v[68:69], v[92:93], v[68:69]
	s_nop 0
	v_add_f32_e32 v68, v70, v68
	v_add_f32_e32 v76, v68, v69
	v_mov_b32_e32 v68, v189
	v_mov_b32_e32 v69, v189
	s_nop 0
	v_mov_b32_dpp v68, v77 row_ror:1 row_mask:0xf bank_mask:0xf
	v_mov_b32_dpp v69, v77 row_ror:2 row_mask:0xf bank_mask:0xf
	s_nop 0
	v_mov_b32_dpp v68, v71 row_shr:1 row_mask:0xf bank_mask:0xf
	v_mov_b32_dpp v69, v71 row_shr:2 row_mask:0xf bank_mask:0xf
	v_pk_mul_f32 v[68:69], v[146:147], v[68:69]
	s_nop 0
	v_add_f32_e32 v68, v143, v68
	v_add_f32_e32 v77, v68, v69
	v_add_u32_e32 v68, s2, v82
	v_mov_b32_e32 v69, v189
	v_lshl_add_u64 v[68:69], v[68:69], 2, s[6:7]
	global_load_dwordx4 v[68:71], v[68:69], off
	v_mov_b32_e32 v74, v189
	v_mov_b32_e32 v75, v189
	v_fmac_f32_e32 v131, v67, v139
	s_waitcnt vmcnt(0)
; #define LAS __attribute__((address_space(3)))
;     template <bool SAMP, bool BND>
;     __device__ __forceinline__ void conv_act(const f32x4 (&acc)[2][2][4][2], const Unit& u, int wr, int fr, int rbase, int ccol, LAS float* halo, const LAS float* wl_) const {
;     ...
;         for (int n = 0; n < 2; ++n) {
;             f32x4 W0[2], W1[2], W2[2], BB[2];
; #pragma unroll
;             for (int bj = 0; bj < 2; ++bj) {
;                 const int tc = bj * 128 + ccol + 4 * n;
;                 W0[bj] = *(const LAS f32x4*)(wl_ + tc); W1[bj] = *(const LAS f32x4*)(wl_ + 256 + tc); W2[bj] = *(const LAS f32x4*)(wl_ + 512 + tc); BB[bj] = *(const LAS f32x4*)(wl_ + 768 + tc);
;             }
; #pragma unroll
;             for (int ai = 0; ai < 2; ++ai)
; #pragma unroll
;                 for (int m = 0; m < 4; ++m) {
;                     const int row = rbase + 128 * ai + 16 * m + fr;
;                     const bool ok = SAMP || (row < NP && !(ai == 0 && m == 0 && wr == 0 && fr < 2));
;                     const int t4 = (row + 2) & 2047;
;                     const float z1 = (BND && t4 == 2) ? 0.f : 1.f, z2 = (BND && (t4 == 2 || t4 == 3)) ? 0.f : 1.f;
;                     f32x4 a[2];
; #pragma unroll
;                     for (int bj = 0; bj < 2; ++bj) {
;                         f32x4 prev;
;                         if (SAMP) { const int s = (rbase + 128 * ai + 16 * m - NP) >> 4; prev = *(const f32x4*)(sffn + (unsigned)((s * 2 + (fr & 1)) * UPW + bj * DFF + u.pn * 128 + ccol + 4 * n)); }
;                         else if (m > 0) prev = acc[ai][bj][m > 0 ? m - 1 : 0][n];
;                         else { const int blk = 2 * ai + wr; prev = (f32x4){0.f, 0.f, 0.f, 0.f}; if (blk > 0) prev = *(const LAS f32x4*)(halo + ((blk - 1) * 2 + (fr & 1)) * 256 + bj * 128 + ccol + 4 * n); }
;                         const f32x4 cur = acc[ai][bj][m][n];
; #pragma unroll
;                         for (int j = 0; j < 4; ++j) {
;                             const float p1 = dppf<0x111>(dppf<0x121>(0.f, prev[j]), cur[j]);
;                             const float p2 = dppf<0x112>(dppf<0x122>(0.f, prev[j]), cur[j]);
;                             a[bj][j] = BB[bj][j] + W2[bj][j] * cur[j] + W1[bj][j] * (BND ? p1 * z1 : p1) + W0[bj][j] * (BND ? p2 * z2 : p2);
;                         }
	v_mov_b32_dpp v74, v68 row_ror:1 row_mask:0xf bank_mask:0xf
	v_mov_b32_dpp v75, v68 row_ror:2 row_mask:0xf bank_mask:0xf
	s_nop 0
	v_mov_b32_dpp v74, v64 row_shr:1 row_mask:0xf bank_mask:0xf
	v_mov_b32_dpp v75, v64 row_shr:2 row_mask:0xf bank_mask:0xf
	v_fma_f32 v64, v64, v136, v128
	v_pk_mul_f32 v[74:75], v[94:95], v[74:75]
	s_nop 0
	v_add_f32_e32 v64, v64, v74
	v_add_f32_e32 v68, v64, v75
	v_mov_b32_e32 v74, v189
	v_mov_b32_e32 v75, v189
	s_nop 0
	v_mov_b32_dpp v74, v69 row_ror:1 row_mask:0xf bank_mask:0xf
	v_mov_b32_dpp v75, v69 row_ror:2 row_mask:0xf bank_mask:0xf
	v_fma_f32 v69, v65, v137, v129
	v_mov_b32_dpp v74, v65 row_shr:1 row_mask:0xf bank_mask:0xf
	v_mov_b32_dpp v75, v65 row_shr:2 row_mask:0xf bank_mask:0xf
	v_pk_mul_f32 v[64:65], v[132:133], v[74:75]
	s_nop 0
	v_add_f32_e32 v64, v69, v64
	v_add_f32_e32 v69, v64, v65
	v_mov_b32_e32 v64, v189
	v_mov_b32_e32 v65, v189
	s_nop 0
	v_mov_b32_dpp v64, v70 row_ror:1 row_mask:0xf bank_mask:0xf
	v_mov_b32_dpp v65, v70 row_ror:2 row_mask:0xf bank_mask:0xf
	s_nop 0
	v_mov_b32_dpp v64, v66 row_shr:1 row_mask:0xf bank_mask:0xf
	v_mov_b32_dpp v65, v66 row_shr:2 row_mask:0xf bank_mask:0xf
	v_fma_f32 v66, v66, v138, v130
	v_pk_mul_f32 v[64:65], v[100:101], v[64:65]
	s_nop 0
	v_add_f32_e32 v64, v66, v64
	v_add_f32_e32 v66, v64, v65
	v_mov_b32_e32 v64, v189
	v_mov_b32_e32 v65, v189
	s_nop 0
	v_mov_b32_dpp v64, v71 row_ror:1 row_mask:0xf bank_mask:0xf
	v_mov_b32_dpp v65, v71 row_ror:2 row_mask:0xf bank_mask:0xf
	s_nop 0
	v_mov_b32_dpp v64, v67 row_shr:1 row_mask:0xf bank_mask:0xf
	v_mov_b32_dpp v65, v67 row_shr:2 row_mask:0xf bank_mask:0xf
	v_pk_mul_f32 v[64:65], v[134:135], v[64:65]
	s_nop 0
	v_add_f32_e32 v64, v131, v64
	v_add_f32_e32 v64, v64, v65
	v_mul_f32_e32 v65, 0xbfb8aa3b, v83
	v_exp_f32_e32 v65, v65
	v_mul_f32_e32 v67, 0xbfb8aa3b, v78
	v_exp_f32_e32 v67, v67
	v_add_f32_e32 v65, 1.0, v65
	v_rcp_f32_e32 v65, v65
	v_add_f32_e32 v67, 1.0, v67
	v_rcp_f32_e32 v67, v67
	v_mul_f32_e32 v65, v83, v65
	v_mul_f32_e32 v65, v65, v68
	v_mul_f32_e32 v68, 0xbfb8aa3b, v76
	v_exp_f32_e32 v68, v68
	v_mul_f32_e32 v67, v78, v67
	v_mul_f32_e32 v67, v67, v69
	v_add_f32_e32 v68, 1.0, v68
	v_rcp_f32_e32 v68, v68
	s_nop 0
	v_mul_f32_e32 v68, v76, v68
	v_mul_f32_e32 v66, v68, v66
	v_mul_f32_e32 v68, 0xbfb8aa3b, v77
	v_exp_f32_e32 v68, v68
	s_nop 0
	v_add_f32_e32 v68, 1.0, v68
	v_rcp_f32_e32 v68, v68
	s_nop 0
	v_mul_f32_e32 v68, v77, v68
	v_mul_f32_e32 v68, v68, v64
	v_cvt_pk_bf16_f32 v64, v65, v67
	v_cvt_pk_bf16_f32 v65, v66, v68
	v_or_b32_e32 v146, 4, v188
	v_mad_u32_u24 v74, v214, s1, v146
	v_add_u32_e32 v70, s3, v74
	v_mov_b32_e32 v71, v189
	v_lshl_add_u64 v[70:71], v[70:71], 2, s[6:7]
	ds_read_b128 v[100:103], v213 offset:16
	ds_read_b128 v[124:127], v213 offset:1040
	ds_read_b128 v[108:111], v213 offset:2064
	ds_read_b128 v[92:95], v213 offset:3088
	ds_read_b128 v[76:79], v213 offset:528
	ds_read_b128 v[116:119], v213 offset:1552
	ds_read_b128 v[84:87], v213 offset:2576
	ds_read_b128 v[66:69], v213 offset:3600
	global_load_dwordx4 v[128:131], v[70:71], off
	v_mov_b32_e32 v98, v189
	v_mov_b32_e32 v122, v189
	v_mov_b32_e32 v136, v189
	v_mov_b32_e32 v70, v189
	v_mov_b32_e32 v144, v189
	v_mov_b32_e32 v114, v189
	v_mov_b32_e32 v106, v189
	s_waitcnt vmcnt(0)
	v_mov_b32_dpp v98, v128 row_ror:1 row_mask:0xf bank_mask:0xf
	v_mov_b32_dpp v122, v128 row_ror:2 row_mask:0xf bank_mask:0xf
	v_mov_b32_e32 v128, v189
	v_mov_b32_dpp v136, v129 row_ror:2 row_mask:0xf bank_mask:0xf
	v_mov_b32_dpp v70, v130 row_ror:1 row_mask:0xf bank_mask:0xf
	v_mov_b32_dpp v128, v129 row_ror:1 row_mask:0xf bank_mask:0xf
	v_mov_b32_dpp v144, v130 row_ror:2 row_mask:0xf bank_mask:0xf
	v_mov_b32_dpp v114, v131 row_ror:1 row_mask:0xf bank_mask:0xf
	v_mov_b32_dpp v106, v131 row_ror:2 row_mask:0xf bank_mask:0xf
	v_mov_b32_dpp v98, v60 row_shr:1 row_mask:0xf bank_mask:0xf
	v_mov_b32_dpp v122, v60 row_shr:2 row_mask:0xf bank_mask:0xf
	v_mov_b32_dpp v128, v61 row_shr:1 row_mask:0xf bank_mask:0xf
	v_mov_b32_dpp v136, v61 row_shr:2 row_mask:0xf bank_mask:0xf
	v_mov_b32_dpp v70, v62 row_shr:1 row_mask:0xf bank_mask:0xf
	v_mov_b32_dpp v144, v62 row_shr:2 row_mask:0xf bank_mask:0xf
	v_mov_b32_dpp v114, v63 row_shr:1 row_mask:0xf bank_mask:0xf
	v_mov_b32_dpp v106, v63 row_shr:2 row_mask:0xf bank_mask:0xf
	v_add_u32_e32 v74, s2, v74
	v_mov_b32_e32 v75, v189
	v_lshl_add_u64 v[74:75], v[74:75], 2, s[6:7]
	global_load_dwordx4 v[148:151], v[74:75], off
	v_mov_b32_e32 v99, v189
	v_mov_b32_e32 v123, v189
	v_mov_b32_e32 v90, v60
	v_mov_b32_e32 v91, v56
	s_waitcnt lgkmcnt(5)
	v_mov_b32_e32 v74, v108
	s_waitcnt lgkmcnt(1)
	v_mov_b32_e32 v75, v84
	v_mov_b32_e32 v82, v92
	s_waitcnt lgkmcnt(0)
	v_mov_b32_e32 v83, v66
	v_mov_b32_e32 v129, v189
	v_mov_b32_e32 v137, v189
	v_pk_fma_f32 v[130:131], v[90:91], v[74:75], v[82:83]
	v_mov_b32_e32 v90, v124
	v_mov_b32_e32 v91, v116
	v_mov_b32_e32 v132, v109
	v_mov_b32_e32 v133, v85
	v_mov_b32_e32 v134, v93
	v_mov_b32_e32 v135, v67
	v_mov_b32_e32 v138, v125
	v_mov_b32_e32 v139, v117
	v_mov_b32_e32 v71, v189
	v_mov_b32_e32 v142, v101
	v_mov_b32_e32 v143, v77
	v_mov_b32_e32 v145, v189
	v_mov_b32_e32 v60, v62
	v_mov_b32_e32 v140, v102
	v_mov_b32_e32 v141, v78
	v_mov_b32_e32 v115, v189
	v_mov_b32_e32 v107, v189
	s_waitcnt vmcnt(0)
; __device__ __forceinline__ unsigned cvt_pk_bf16(float lo, float hi) { unsigned r; asm volatile("v_cvt_pk_bf16_f32 %0, %1, %2" : "=v"(r) : "v"(lo), "v"(hi)); return r; }
;     template <bool SAMP, bool BND>
;     __device__ __forceinline__ void conv_act(const f32x4 (&acc)[2][2][4][2], const Unit& u, int wr, int fr, int rbase, int ccol, LAS float* halo, const LAS float* wl_) const {
;     ...
;                         const f32x4 cur = acc[ai][bj][m][n];
; #pragma unroll
;                         for (int j = 0; j < 4; ++j) {
;                             const float p1 = dppf<0x111>(dppf<0x121>(0.f, prev[j]), cur[j]);
;                             const float p2 = dppf<0x112>(dppf<0x122>(0.f, prev[j]), cur[j]);
;                             a[bj][j] = BB[bj][j] + W2[bj][j] * cur[j] + W1[bj][j] * (BND ? p1 * z1 : p1) + W0[bj][j] * (BND ? p2 * z2 : p2);
;                         }
;                         if (BND) { if (ok && t4 < 2 && row >= 2046) *(f32x4*)(offp + (unsigned)(((((row + 2) >> 11) - 1) * 2 + t4) * UPW + bj * DFF + u.pn * 128 + ccol + 4 * n)) = cur; }
;                         __builtin_amdgcn_sched_barrier(0);
;                     }
;                     float o[4];
; #pragma unroll
;                     for (int j = 0; j < 4; ++j) { const float g = a[0][j], v = a[1][j]; o[j] = g * __builtin_amdgcn_rcpf(1.0f + __builtin_amdgcn_exp2f(-g * LOG2E)) * v; }
;                     u32x2 w; w.x = cvt_pk_bf16(o[0], o[1]); w.y = cvt_pk_bf16(o[2], o[3]);
;                     if (n == 0) keep[ai][m] = w;
;                     else if (ok) { u32x4 w4; w4.x = keep[ai][m].x; w4.y = keep[ai][m].y; w4.z = w.x; w4.w = w.y; *(u32x4*)(ACT + (unsigned)(row * DFF + u.pn * 128 + ccol)) = w4; }
	v_mov_b32_dpp v99, v148 row_ror:1 row_mask:0xf bank_mask:0xf
	v_mov_b32_dpp v123, v148 row_ror:2 row_mask:0xf bank_mask:0xf
	s_nop 0
	v_mov_b32_dpp v99, v56 row_shr:1 row_mask:0xf bank_mask:0xf
	v_mov_b32_dpp v129, v149 row_ror:1 row_mask:0xf bank_mask:0xf
	v_mov_b32_dpp v123, v56 row_shr:2 row_mask:0xf bank_mask:0xf
	v_mov_b32_dpp v137, v149 row_ror:2 row_mask:0xf bank_mask:0xf
	v_mov_b32_e32 v56, v61
	v_pk_fma_f32 v[130:131], v[90:91], v[98:99], v[130:131]
	v_mov_b32_e32 v98, v100
	v_mov_b32_e32 v99, v76
	v_mov_b32_dpp v129, v57 row_shr:1 row_mask:0xf bank_mask:0xf
	v_mov_b32_dpp v137, v57 row_shr:2 row_mask:0xf bank_mask:0xf
	v_pk_fma_f32 v[56:57], v[56:57], v[132:133], v[134:135]
	v_pk_fma_f32 v[122:123], v[98:99], v[122:123], v[130:131]
	v_pk_fma_f32 v[56:57], v[138:139], v[128:129], v[56:57]
	v_mov_b32_dpp v71, v150 row_ror:1 row_mask:0xf bank_mask:0xf
	v_mov_b32_e32 v61, v58
	v_mov_b32_e32 v128, v110
	v_mov_b32_e32 v129, v86
	v_mov_b32_e32 v130, v94
	v_mov_b32_e32 v131, v68
	v_pk_fma_f32 v[56:57], v[142:143], v[136:137], v[56:57]
	v_mov_b32_dpp v71, v58 row_shr:1 row_mask:0xf bank_mask:0xf
	v_mov_b32_dpp v145, v150 row_ror:2 row_mask:0xf bank_mask:0xf
	v_pk_fma_f32 v[60:61], v[60:61], v[128:129], v[130:131]
	v_mov_b32_e32 v136, v126
	v_mov_b32_e32 v137, v118
	v_mov_b32_dpp v145, v58 row_shr:2 row_mask:0xf bank_mask:0xf
	v_pk_fma_f32 v[60:61], v[136:137], v[70:71], v[60:61]
	v_mov_b32_dpp v115, v151 row_ror:1 row_mask:0xf bank_mask:0xf
	v_pk_fma_f32 v[144:145], v[140:141], v[144:145], v[60:61]
	v_mov_b32_dpp v107, v151 row_ror:2 row_mask:0xf bank_mask:0xf
	v_mov_b32_e32 v58, v63
	v_mov_b32_e32 v60, v111
	v_mov_b32_e32 v61, v87
	v_mov_b32_e32 v70, v95
	v_mov_b32_e32 v71, v69
	v_mov_b32_dpp v115, v59 row_shr:1 row_mask:0xf bank_mask:0xf
	v_mov_b32_dpp v107, v59 row_shr:2 row_mask:0xf bank_mask:0xf
	v_pk_fma_f32 v[62:63], v[58:59], v[60:61], v[70:71]
	v_mov_b32_e32 v58, v127
	v_mov_b32_e32 v59, v119
	v_pk_fma_f32 v[114:115], v[58:59], v[114:115], v[62:63]
	v_mov_b32_e32 v62, v103
	v_mov_b32_e32 v63, v79
	v_pk_fma_f32 v[106:107], v[62:63], v[106:107], v[114:115]
	v_mul_f32_e32 v115, 0xbfb8aa3b, v56
	v_exp_f32_e32 v115, v115
	v_mul_f32_e32 v114, 0xbfb8aa3b, v122
	v_exp_f32_e32 v114, v114
	s_movk_i32 s0, 0xb00
	v_add_f32_e32 v115, 1.0, v115
	v_rcp_f32_e32 v115, v115
	v_add_f32_e32 v114, 1.0, v114
	v_rcp_f32_e32 v114, v114
	v_mul_f32_e32 v56, v56, v115
	v_mul_f32_e32 v56, v56, v57
	v_mul_f32_e32 v57, 0xbfb8aa3b, v144
	v_exp_f32_e32 v57, v57
	v_mul_f32_e32 v115, 0xbfb8aa3b, v106
	v_exp_f32_e32 v115, v115
	v_mul_f32_e32 v114, v122, v114
	v_add_f32_e32 v57, 1.0, v57
	v_rcp_f32_e32 v57, v57
	v_add_f32_e32 v115, 1.0, v115
	v_rcp_f32_e32 v115, v115
	v_mul_f32_e32 v114, v114, v123
	v_mul_f32_e32 v57, v144, v57
	v_mul_f32_e32 v57, v57, v145
	v_mul_f32_e32 v106, v106, v115
	v_cvt_pk_bf16_f32 v122, v114, v56
	v_mul_lo_u32 v56, v195, s0
	v_mul_f32_e32 v106, v106, v107
	v_cvt_pk_bf16_f32 v123, v57, v106
	v_add3_u32 v56, v188, s3, v56
	v_mov_b32_e32 v57, v189
	v_lshl_add_u64 v[106:107], v[56:57], 1, s[4:5]
	global_store_dwordx4 v[106:107], v[120:123], off
	v_mad_u32_u24 v57, v198, s1, v146
	v_add_u32_e32 v106, s3, v57
	v_mov_b32_e32 v107, v189
	v_lshl_add_u64 v[106:107], v[106:107], 2, s[6:7]
	global_load_dwordx4 v[120:123], v[106:107], off
	v_mov_b32_e32 v144, v189
	v_mov_b32_e32 v148, v189
	v_mov_b32_e32 v150, v189
	v_mov_b32_e32 v156, v189
	v_mov_b32_e32 v158, v189
	v_mov_b32_e32 v162, v189
	v_mov_b32_e32 v106, v189
	v_mov_b32_e32 v114, v189
	s_waitcnt vmcnt(0)
	v_mov_b32_dpp v144, v120 row_ror:1 row_mask:0xf bank_mask:0xf
	v_mov_b32_dpp v148, v120 row_ror:2 row_mask:0xf bank_mask:0xf
	v_mov_b32_dpp v150, v121 row_ror:1 row_mask:0xf bank_mask:0xf
	v_mov_b32_dpp v156, v121 row_ror:2 row_mask:0xf bank_mask:0xf
	v_mov_b32_dpp v158, v122 row_ror:1 row_mask:0xf bank_mask:0xf
	v_mov_b32_dpp v162, v122 row_ror:2 row_mask:0xf bank_mask:0xf
	v_mov_b32_dpp v106, v123 row_ror:1 row_mask:0xf bank_mask:0xf
	v_mov_b32_dpp v114, v123 row_ror:2 row_mask:0xf bank_mask:0xf
	v_mov_b32_dpp v144, v48 row_shr:1 row_mask:0xf bank_mask:0xf
	v_mov_b32_dpp v148, v48 row_shr:2 row_mask:0xf bank_mask:0xf
	v_mov_b32_dpp v150, v49 row_shr:1 row_mask:0xf bank_mask:0xf
	v_mov_b32_dpp v156, v49 row_shr:2 row_mask:0xf bank_mask:0xf
	v_mov_b32_dpp v158, v50 row_shr:1 row_mask:0xf bank_mask:0xf
	v_mov_b32_dpp v162, v50 row_shr:2 row_mask:0xf bank_mask:0xf
	v_mov_b32_dpp v106, v51 row_shr:1 row_mask:0xf bank_mask:0xf
	v_mov_b32_dpp v114, v51 row_shr:2 row_mask:0xf bank_mask:0xf
	v_add_u32_e32 v120, s2, v57
	v_mov_b32_e32 v121, v189
	v_lshl_add_u64 v[120:121], v[120:121], 2, s[6:7]
	global_load_dwordx4 v[120:123], v[120:121], off
	v_mov_b32_e32 v145, v189
	v_mov_b32_e32 v149, v189
	v_mov_b32_e32 v151, v189
	v_mov_b32_e32 v157, v189
	v_mov_b32_e32 v159, v189
	v_mov_b32_e32 v163, v189
	v_mov_b32_e32 v165, v52
	v_mov_b32_e32 v107, v189
	v_mov_b32_e32 v164, v48
	v_mov_b32_e32 v115, v189
	v_pk_fma_f32 v[164:165], v[164:165], v[74:75], v[82:83]
	s_waitcnt vmcnt(0)
; __device__ __forceinline__ unsigned cvt_pk_bf16(float lo, float hi) { unsigned r; asm volatile("v_cvt_pk_bf16_f32 %0, %1, %2" : "=v"(r) : "v"(lo), "v"(hi)); return r; }
;     template <bool SAMP, bool BND>
;     __device__ __forceinline__ void conv_act(const f32x4 (&acc)[2][2][4][2], const Unit& u, int wr, int fr, int rbase, int ccol, LAS float* halo, const LAS float* wl_) const {
;     ...
;                         const f32x4 cur = acc[ai][bj][m][n];
; #pragma unroll
;                         for (int j = 0; j < 4; ++j) {
;                             const float p1 = dppf<0x111>(dppf<0x121>(0.f, prev[j]), cur[j]);
;                             const float p2 = dppf<0x112>(dppf<0x122>(0.f, prev[j]), cur[j]);
;                             a[bj][j] = BB[bj][j] + W2[bj][j] * cur[j] + W1[bj][j] * (BND ? p1 * z1 : p1) + W0[bj][j] * (BND ? p2 * z2 : p2);
;                         }
;                         if (BND) { if (ok && t4 < 2 && row >= 2046) *(f32x4*)(offp + (unsigned)(((((row + 2) >> 11) - 1) * 2 + t4) * UPW + bj * DFF + u.pn * 128 + ccol + 4 * n)) = cur; }
;                         __builtin_amdgcn_sched_barrier(0);
;                     }
;                     float o[4];
; #pragma unroll
;                     for (int j = 0; j < 4; ++j) { const float g = a[0][j], v = a[1][j]; o[j] = g * __builtin_amdgcn_rcpf(1.0f + __builtin_amdgcn_exp2f(-g * LOG2E)) * v; }
;                     u32x2 w; w.x = cvt_pk_bf16(o[0], o[1]); w.y = cvt_pk_bf16(o[2], o[3]);
;                     if (n == 0) keep[ai][m] = w;
;                     else if (ok) { u32x4 w4; w4.x = keep[ai][m].x; w4.y = keep[ai][m].y; w4.z = w.x; w4.w = w.y; *(u32x4*)(ACT + (unsigned)(row * DFF + u.pn * 128 + ccol)) = w4; }
	v_mov_b32_dpp v145, v120 row_ror:1 row_mask:0xf bank_mask:0xf
	v_mov_b32_dpp v149, v120 row_ror:2 row_mask:0xf bank_mask:0xf
	s_nop 0
	v_mov_b32_dpp v145, v52 row_shr:1 row_mask:0xf bank_mask:0xf
	v_mov_b32_dpp v151, v121 row_ror:1 row_mask:0xf bank_mask:0xf
	v_mov_b32_dpp v149, v52 row_shr:2 row_mask:0xf bank_mask:0xf
	v_mov_b32_dpp v157, v121 row_ror:2 row_mask:0xf bank_mask:0xf
	v_mov_b32_e32 v52, v49
	v_mov_b32_dpp v159, v122 row_ror:1 row_mask:0xf bank_mask:0xf
	v_mov_b32_dpp v163, v122 row_ror:2 row_mask:0xf bank_mask:0xf
	v_mov_b32_dpp v151, v53 row_shr:1 row_mask:0xf bank_mask:0xf
	v_mov_b32_dpp v157, v53 row_shr:2 row_mask:0xf bank_mask:0xf
	v_pk_fma_f32 v[48:49], v[52:53], v[132:133], v[134:135]
	v_mov_b32_dpp v159, v54 row_shr:1 row_mask:0xf bank_mask:0xf
	v_mov_b32_dpp v163, v54 row_shr:2 row_mask:0xf bank_mask:0xf
	v_mov_b32_e32 v52, v50
	v_mov_b32_e32 v53, v54
	v_mov_b32_dpp v107, v123 row_ror:1 row_mask:0xf bank_mask:0xf
	v_mov_b32_e32 v54, v51
	v_pk_fma_f32 v[52:53], v[52:53], v[128:129], v[130:131]
	v_mov_b32_dpp v107, v55 row_shr:1 row_mask:0xf bank_mask:0xf
	v_mov_b32_dpp v115, v123 row_ror:2 row_mask:0xf bank_mask:0xf
	v_pk_fma_f32 v[50:51], v[54:55], v[60:61], v[70:71]
	v_pk_fma_f32 v[144:145], v[90:91], v[144:145], v[164:165]
	v_pk_fma_f32 v[48:49], v[138:139], v[150:151], v[48:49]
	v_pk_fma_f32 v[52:53], v[136:137], v[158:159], v[52:53]
	v_mov_b32_dpp v115, v55 row_shr:2 row_mask:0xf bank_mask:0xf
	v_pk_fma_f32 v[50:51], v[58:59], v[106:107], v[50:51]
	v_pk_fma_f32 v[144:145], v[98:99], v[148:149], v[144:145]
	v_pk_fma_f32 v[48:49], v[142:143], v[156:157], v[48:49]
	v_pk_fma_f32 v[52:53], v[140:141], v[162:163], v[52:53]
	v_pk_fma_f32 v[50:51], v[62:63], v[114:115], v[50:51]
	v_mul_f32_e32 v55, 0xbfb8aa3b, v48
	v_exp_f32_e32 v55, v55
	v_mul_f32_e32 v54, 0xbfb8aa3b, v144
	v_exp_f32_e32 v54, v54
	v_add_f32_e32 v55, 1.0, v55
	v_rcp_f32_e32 v55, v55
	v_add_f32_e32 v54, 1.0, v54
	v_rcp_f32_e32 v54, v54
	v_mul_f32_e32 v48, v48, v55
	v_mul_f32_e32 v48, v48, v49
	v_mul_f32_e32 v49, 0xbfb8aa3b, v52
	v_exp_f32_e32 v49, v49
	v_mul_f32_e32 v54, v144, v54
	v_mul_f32_e32 v54, v54, v145
	v_cvt_pk_bf16_f32 v114, v54, v48
	v_add_f32_e32 v49, 1.0, v49
	v_rcp_f32_e32 v49, v49
	v_add_u32_e32 v48, 0xb000, v56
	v_mul_f32_e32 v49, v52, v49
	v_mul_f32_e32 v52, 0xbfb8aa3b, v50
	v_exp_f32_e32 v52, v52
	v_mul_f32_e32 v49, v49, v53
	v_add_f32_e32 v52, 1.0, v52
	v_rcp_f32_e32 v52, v52
	s_nop 0
	v_mul_f32_e32 v50, v50, v52
	v_mul_f32_e32 v50, v50, v51
	v_cvt_pk_bf16_f32 v115, v49, v50
	v_mov_b32_e32 v49, v189
	v_lshl_add_u64 v[48:49], v[48:49], 1, s[4:5]
	global_store_dwordx4 v[48:49], v[112:115], off
	v_mad_u32_u24 v52, v187, s1, v146
	v_add_u32_e32 v48, s3, v52
	v_mov_b32_e32 v49, v189
	v_lshl_add_u64 v[48:49], v[48:49], 2, s[6:7]
	global_load_dwordx4 v[48:51], v[48:49], off
	v_mov_b32_e32 v106, v189
	v_mov_b32_e32 v112, v189
	v_mov_b32_e32 v122, v189
	v_mov_b32_e32 v144, v189
	v_mov_b32_e32 v114, v189
	v_mov_b32_e32 v120, v189
	s_waitcnt vmcnt(0)
	v_mov_b32_dpp v106, v48 row_ror:1 row_mask:0xf bank_mask:0xf
	v_mov_b32_dpp v112, v48 row_ror:2 row_mask:0xf bank_mask:0xf
	v_mov_b32_dpp v122, v50 row_ror:1 row_mask:0xf bank_mask:0xf
	v_mov_b32_dpp v144, v50 row_ror:2 row_mask:0xf bank_mask:0xf
	v_mov_b32_e32 v48, v189
	v_mov_b32_e32 v50, v189
	v_mov_b32_dpp v114, v49 row_ror:1 row_mask:0xf bank_mask:0xf
	v_mov_b32_dpp v120, v49 row_ror:2 row_mask:0xf bank_mask:0xf
	v_mov_b32_dpp v48, v51 row_ror:1 row_mask:0xf bank_mask:0xf
	v_mov_b32_dpp v50, v51 row_ror:2 row_mask:0xf bank_mask:0xf
	v_mov_b32_dpp v106, v40 row_shr:1 row_mask:0xf bank_mask:0xf
	v_mov_b32_dpp v112, v40 row_shr:2 row_mask:0xf bank_mask:0xf
	v_mov_b32_dpp v114, v41 row_shr:1 row_mask:0xf bank_mask:0xf
	v_mov_b32_dpp v120, v41 row_shr:2 row_mask:0xf bank_mask:0xf
	v_mov_b32_dpp v122, v42 row_shr:1 row_mask:0xf bank_mask:0xf
	v_mov_b32_dpp v144, v42 row_shr:2 row_mask:0xf bank_mask:0xf
	v_mov_b32_dpp v48, v43 row_shr:1 row_mask:0xf bank_mask:0xf
	v_mov_b32_dpp v50, v43 row_shr:2 row_mask:0xf bank_mask:0xf
	v_add_u32_e32 v52, s2, v52
	v_mov_b32_e32 v53, v189
	v_lshl_add_u64 v[52:53], v[52:53], 2, s[6:7]
	global_load_dwordx4 v[52:55], v[52:53], off
	v_mov_b32_e32 v107, v189
	v_mov_b32_e32 v113, v189
	v_mov_b32_e32 v115, v189
	v_mov_b32_e32 v121, v189
	v_mov_b32_e32 v123, v189
	v_mov_b32_e32 v145, v189
	v_mov_b32_e32 v149, v44
	v_mov_b32_e32 v49, v189
	v_mov_b32_e32 v148, v40
	v_mov_b32_e32 v51, v189
	v_pk_fma_f32 v[148:149], v[148:149], v[74:75], v[82:83]
	s_waitcnt vmcnt(0)
; __device__ __forceinline__ unsigned cvt_pk_bf16(float lo, float hi) { unsigned r; asm volatile("v_cvt_pk_bf16_f32 %0, %1, %2" : "=v"(r) : "v"(lo), "v"(hi)); return r; }
;     template <bool SAMP, bool BND>
;     __device__ __forceinline__ void conv_act(const f32x4 (&acc)[2][2][4][2], const Unit& u, int wr, int fr, int rbase, int ccol, LAS float* halo, const LAS float* wl_) const {
;     ...
;                         const f32x4 cur = acc[ai][bj][m][n];
; #pragma unroll
;                         for (int j = 0; j < 4; ++j) {
;                             const float p1 = dppf<0x111>(dppf<0x121>(0.f, prev[j]), cur[j]);
;                             const float p2 = dppf<0x112>(dppf<0x122>(0.f, prev[j]), cur[j]);
;                             a[bj][j] = BB[bj][j] + W2[bj][j] * cur[j] + W1[bj][j] * (BND ? p1 * z1 : p1) + W0[bj][j] * (BND ? p2 * z2 : p2);
;                         }
;                         if (BND) { if (ok && t4 < 2 && row >= 2046) *(f32x4*)(offp + (unsigned)(((((row + 2) >> 11) - 1) * 2 + t4) * UPW + bj * DFF + u.pn * 128 + ccol + 4 * n)) = cur; }
;                         __builtin_amdgcn_sched_barrier(0);
;                     }
;                     float o[4];
; #pragma unroll
;                     for (int j = 0; j < 4; ++j) { const float g = a[0][j], v = a[1][j]; o[j] = g * __builtin_amdgcn_rcpf(1.0f + __builtin_amdgcn_exp2f(-g * LOG2E)) * v; }
;                     u32x2 w; w.x = cvt_pk_bf16(o[0], o[1]); w.y = cvt_pk_bf16(o[2], o[3]);
;                     if (n == 0) keep[ai][m] = w;
;                     else if (ok) { u32x4 w4; w4.x = keep[ai][m].x; w4.y = keep[ai][m].y; w4.z = w.x; w4.w = w.y; *(u32x4*)(ACT + (unsigned)(row * DFF + u.pn * 128 + ccol)) = w4; }
	v_mov_b32_dpp v107, v52 row_ror:1 row_mask:0xf bank_mask:0xf
	v_mov_b32_dpp v113, v52 row_ror:2 row_mask:0xf bank_mask:0xf
	s_nop 0
	v_mov_b32_dpp v107, v44 row_shr:1 row_mask:0xf bank_mask:0xf
	v_mov_b32_dpp v115, v53 row_ror:1 row_mask:0xf bank_mask:0xf
	v_mov_b32_dpp v113, v44 row_shr:2 row_mask:0xf bank_mask:0xf
	v_mov_b32_dpp v121, v53 row_ror:2 row_mask:0xf bank_mask:0xf
	v_mov_b32_e32 v44, v41
	v_mov_b32_dpp v123, v54 row_ror:1 row_mask:0xf bank_mask:0xf
	v_mov_b32_dpp v145, v54 row_ror:2 row_mask:0xf bank_mask:0xf
	v_mov_b32_dpp v115, v45 row_shr:1 row_mask:0xf bank_mask:0xf
	v_mov_b32_dpp v121, v45 row_shr:2 row_mask:0xf bank_mask:0xf
	v_pk_fma_f32 v[40:41], v[44:45], v[132:133], v[134:135]
	v_mov_b32_dpp v123, v46 row_shr:1 row_mask:0xf bank_mask:0xf
	v_mov_b32_dpp v145, v46 row_shr:2 row_mask:0xf bank_mask:0xf
	v_mov_b32_e32 v44, v42
	v_mov_b32_e32 v45, v46
	v_mov_b32_dpp v49, v55 row_ror:1 row_mask:0xf bank_mask:0xf
	v_mov_b32_e32 v46, v43
	v_pk_fma_f32 v[44:45], v[44:45], v[128:129], v[130:131]
	v_mov_b32_dpp v49, v47 row_shr:1 row_mask:0xf bank_mask:0xf
	v_mov_b32_dpp v51, v55 row_ror:2 row_mask:0xf bank_mask:0xf
	v_pk_fma_f32 v[42:43], v[46:47], v[60:61], v[70:71]
	v_pk_fma_f32 v[106:107], v[90:91], v[106:107], v[148:149]
	v_pk_fma_f32 v[40:41], v[138:139], v[114:115], v[40:41]
	v_pk_fma_f32 v[44:45], v[136:137], v[122:123], v[44:45]
	v_mov_b32_dpp v51, v47 row_shr:2 row_mask:0xf bank_mask:0xf
	v_pk_fma_f32 v[42:43], v[58:59], v[48:49], v[42:43]
	v_pk_fma_f32 v[106:107], v[98:99], v[112:113], v[106:107]
	v_pk_fma_f32 v[40:41], v[142:143], v[120:121], v[40:41]
	v_pk_fma_f32 v[44:45], v[140:141], v[144:145], v[44:45]
	v_pk_fma_f32 v[42:43], v[62:63], v[50:51], v[42:43]
	v_mul_f32_e32 v47, 0xbfb8aa3b, v40
	v_exp_f32_e32 v47, v47
	v_mul_f32_e32 v46, 0xbfb8aa3b, v106
	v_exp_f32_e32 v46, v46
	v_add_f32_e32 v47, 1.0, v47
	v_rcp_f32_e32 v47, v47
	v_add_f32_e32 v46, 1.0, v46
	v_rcp_f32_e32 v46, v46
	v_mul_f32_e32 v40, v40, v47
	v_mul_f32_e32 v40, v40, v41
	v_mul_f32_e32 v41, 0xbfb8aa3b, v44
	v_exp_f32_e32 v41, v41
	v_mul_f32_e32 v46, v106, v46
	v_mul_f32_e32 v46, v46, v107
	v_cvt_pk_bf16_f32 v106, v46, v40
	v_add_f32_e32 v41, 1.0, v41
	v_rcp_f32_e32 v41, v41
	v_add_u32_e32 v40, 0x16000, v56
	v_mul_f32_e32 v41, v44, v41
	v_mul_f32_e32 v44, 0xbfb8aa3b, v42
	v_exp_f32_e32 v44, v44
	v_mul_f32_e32 v41, v41, v45
	v_add_f32_e32 v44, 1.0, v44
	v_rcp_f32_e32 v44, v44
	s_nop 0
	v_mul_f32_e32 v42, v42, v44
	v_mul_f32_e32 v42, v42, v43
	v_cvt_pk_bf16_f32 v107, v41, v42
	v_mov_b32_e32 v41, v189
	v_lshl_add_u64 v[40:41], v[40:41], 1, s[4:5]
	global_store_dwordx4 v[40:41], v[104:107], off
	v_mad_u32_u24 v44, v186, s1, v146
	v_add_u32_e32 v40, s3, v44
	v_mov_b32_e32 v41, v189
	v_lshl_add_u64 v[40:41], v[40:41], 2, s[6:7]
	global_load_dwordx4 v[40:43], v[40:41], off
	v_mov_b32_e32 v48, v189
	v_mov_b32_e32 v50, v189
	v_mov_b32_e32 v104, v189
	v_mov_b32_e32 v106, v189
	v_mov_b32_e32 v52, v189
	v_mov_b32_e32 v54, v189
	s_waitcnt vmcnt(0)
	v_mov_b32_dpp v48, v40 row_ror:1 row_mask:0xf bank_mask:0xf
	v_mov_b32_dpp v50, v40 row_ror:2 row_mask:0xf bank_mask:0xf
	v_mov_b32_dpp v104, v42 row_ror:1 row_mask:0xf bank_mask:0xf
	v_mov_b32_dpp v106, v42 row_ror:2 row_mask:0xf bank_mask:0xf
	v_mov_b32_e32 v40, v189
	v_mov_b32_e32 v42, v189
	v_mov_b32_dpp v52, v41 row_ror:1 row_mask:0xf bank_mask:0xf
	v_mov_b32_dpp v54, v41 row_ror:2 row_mask:0xf bank_mask:0xf
	v_mov_b32_dpp v40, v43 row_ror:1 row_mask:0xf bank_mask:0xf
	v_mov_b32_dpp v42, v43 row_ror:2 row_mask:0xf bank_mask:0xf
	v_mov_b32_dpp v48, v32 row_shr:1 row_mask:0xf bank_mask:0xf
	v_mov_b32_dpp v50, v32 row_shr:2 row_mask:0xf bank_mask:0xf
	v_mov_b32_dpp v52, v33 row_shr:1 row_mask:0xf bank_mask:0xf
	v_mov_b32_dpp v54, v33 row_shr:2 row_mask:0xf bank_mask:0xf
	v_mov_b32_dpp v104, v34 row_shr:1 row_mask:0xf bank_mask:0xf
	v_mov_b32_dpp v106, v34 row_shr:2 row_mask:0xf bank_mask:0xf
	v_mov_b32_dpp v40, v35 row_shr:1 row_mask:0xf bank_mask:0xf
	v_mov_b32_dpp v42, v35 row_shr:2 row_mask:0xf bank_mask:0xf
	v_add_u32_e32 v44, s2, v44
	v_mov_b32_e32 v45, v189
	v_lshl_add_u64 v[44:45], v[44:45], 2, s[6:7]
	global_load_dwordx4 v[44:47], v[44:45], off
	v_mov_b32_e32 v49, v189
	v_mov_b32_e32 v51, v189
	v_mov_b32_e32 v53, v189
	v_mov_b32_e32 v55, v189
	v_mov_b32_e32 v105, v189
	v_mov_b32_e32 v107, v189
	v_mov_b32_e32 v113, v36
	v_mov_b32_e32 v41, v189
	v_mov_b32_e32 v112, v32
	v_mov_b32_e32 v43, v189
	v_pk_fma_f32 v[74:75], v[112:113], v[74:75], v[82:83]
	s_waitcnt vmcnt(0)
; __device__ __forceinline__ unsigned cvt_pk_bf16(float lo, float hi) { unsigned r; asm volatile("v_cvt_pk_bf16_f32 %0, %1, %2" : "=v"(r) : "v"(lo), "v"(hi)); return r; }
;     template <bool SAMP, bool BND>
;     __device__ __forceinline__ void conv_act(const f32x4 (&acc)[2][2][4][2], const Unit& u, int wr, int fr, int rbase, int ccol, LAS float* halo, const LAS float* wl_) const {
;     ...
;                         const f32x4 cur = acc[ai][bj][m][n];
; #pragma unroll
;                         for (int j = 0; j < 4; ++j) {
;                             const float p1 = dppf<0x111>(dppf<0x121>(0.f, prev[j]), cur[j]);
;                             const float p2 = dppf<0x112>(dppf<0x122>(0.f, prev[j]), cur[j]);
;                             a[bj][j] = BB[bj][j] + W2[bj][j] * cur[j] + W1[bj][j] * (BND ? p1 * z1 : p1) + W0[bj][j] * (BND ? p2 * z2 : p2);
;                         }
;                         if (BND) { if (ok && t4 < 2 && row >= 2046) *(f32x4*)(offp + (unsigned)(((((row + 2) >> 11) - 1) * 2 + t4) * UPW + bj * DFF + u.pn * 128 + ccol + 4 * n)) = cur; }
;                         __builtin_amdgcn_sched_barrier(0);
;                     }
;                     float o[4];
; #pragma unroll
;                     for (int j = 0; j < 4; ++j) { const float g = a[0][j], v = a[1][j]; o[j] = g * __builtin_amdgcn_rcpf(1.0f + __builtin_amdgcn_exp2f(-g * LOG2E)) * v; }
;                     u32x2 w; w.x = cvt_pk_bf16(o[0], o[1]); w.y = cvt_pk_bf16(o[2], o[3]);
;                     if (n == 0) keep[ai][m] = w;
;                     else if (ok) { u32x4 w4; w4.x = keep[ai][m].x; w4.y = keep[ai][m].y; w4.z = w.x; w4.w = w.y; *(u32x4*)(ACT + (unsigned)(row * DFF + u.pn * 128 + ccol)) = w4; }
	v_mov_b32_dpp v49, v44 row_ror:1 row_mask:0xf bank_mask:0xf
	v_mov_b32_dpp v51, v44 row_ror:2 row_mask:0xf bank_mask:0xf
	s_nop 0
	v_mov_b32_dpp v49, v36 row_shr:1 row_mask:0xf bank_mask:0xf
	v_mov_b32_dpp v53, v45 row_ror:1 row_mask:0xf bank_mask:0xf
	v_mov_b32_dpp v51, v36 row_shr:2 row_mask:0xf bank_mask:0xf
	v_mov_b32_dpp v55, v45 row_ror:2 row_mask:0xf bank_mask:0xf
	v_mov_b32_e32 v36, v33
	v_mov_b32_dpp v105, v46 row_ror:1 row_mask:0xf bank_mask:0xf
	v_mov_b32_dpp v107, v46 row_ror:2 row_mask:0xf bank_mask:0xf
	v_mov_b32_dpp v53, v37 row_shr:1 row_mask:0xf bank_mask:0xf
	v_mov_b32_dpp v55, v37 row_shr:2 row_mask:0xf bank_mask:0xf
	v_pk_fma_f32 v[32:33], v[36:37], v[132:133], v[134:135]
	v_mov_b32_dpp v105, v38 row_shr:1 row_mask:0xf bank_mask:0xf
	v_mov_b32_dpp v107, v38 row_shr:2 row_mask:0xf bank_mask:0xf
	v_mov_b32_e32 v36, v34
	v_mov_b32_e32 v37, v38
	v_mov_b32_dpp v41, v47 row_ror:1 row_mask:0xf bank_mask:0xf
	v_mov_b32_e32 v38, v35
	v_pk_fma_f32 v[36:37], v[36:37], v[128:129], v[130:131]
	v_mov_b32_dpp v41, v39 row_shr:1 row_mask:0xf bank_mask:0xf
	v_mov_b32_dpp v43, v47 row_ror:2 row_mask:0xf bank_mask:0xf
	v_pk_fma_f32 v[34:35], v[38:39], v[60:61], v[70:71]
	v_pk_fma_f32 v[48:49], v[90:91], v[48:49], v[74:75]
	v_pk_fma_f32 v[32:33], v[138:139], v[52:53], v[32:33]
	v_pk_fma_f32 v[36:37], v[136:137], v[104:105], v[36:37]
	v_mov_b32_dpp v43, v39 row_shr:2 row_mask:0xf bank_mask:0xf
	v_pk_fma_f32 v[34:35], v[58:59], v[40:41], v[34:35]
	v_pk_fma_f32 v[48:49], v[98:99], v[50:51], v[48:49]
	v_pk_fma_f32 v[32:33], v[142:143], v[54:55], v[32:33]
	v_pk_fma_f32 v[36:37], v[140:141], v[106:107], v[36:37]
	v_pk_fma_f32 v[34:35], v[62:63], v[42:43], v[34:35]
	v_mul_f32_e32 v39, 0xbfb8aa3b, v32
	v_exp_f32_e32 v39, v39
	v_mul_f32_e32 v38, 0xbfb8aa3b, v48
	v_exp_f32_e32 v38, v38
	v_add_f32_e32 v39, 1.0, v39
	v_rcp_f32_e32 v39, v39
	v_add_f32_e32 v38, 1.0, v38
	v_rcp_f32_e32 v38, v38
	v_mul_f32_e32 v32, v32, v39
	v_mul_f32_e32 v32, v32, v33
	v_mul_f32_e32 v33, 0xbfb8aa3b, v36
	v_exp_f32_e32 v33, v33
	v_mul_f32_e32 v38, v48, v38
	v_mul_f32_e32 v38, v38, v49
	v_cvt_pk_bf16_f32 v98, v38, v32
	v_add_f32_e32 v33, 1.0, v33
	v_rcp_f32_e32 v33, v33
	v_add_u32_e32 v32, 0x21000, v56
	v_mul_f32_e32 v33, v36, v33
	v_mul_f32_e32 v36, 0xbfb8aa3b, v34
	v_exp_f32_e32 v36, v36
	v_mul_f32_e32 v33, v33, v37
	v_add_f32_e32 v36, 1.0, v36
	v_rcp_f32_e32 v36, v36
	s_nop 0
	v_mul_f32_e32 v34, v34, v36
	v_mul_f32_e32 v34, v34, v35
	v_cvt_pk_bf16_f32 v99, v33, v34
	v_mov_b32_e32 v33, v189
	v_lshl_add_u64 v[32:33], v[32:33], 1, s[4:5]
	global_store_dwordx4 v[32:33], v[96:99], off
	v_mad_u32_u24 v40, v160, s1, v146
	v_add_u32_e32 v32, s3, v40
	v_mov_b32_e32 v33, v189
	v_lshl_add_u64 v[32:33], v[32:33], 2, s[6:7]
	global_load_dwordx4 v[34:37], v[32:33], off
	v_mov_b32_e32 v38, v189
	v_mov_b32_e32 v39, v189
	v_mov_b32_e32 v32, v124
	v_mov_b32_e32 v33, v100
	v_mov_b32_e32 v100, v125
	s_waitcnt vmcnt(0)
	v_mov_b32_dpp v38, v34 row_ror:1 row_mask:0xf bank_mask:0xf
	v_mov_b32_dpp v39, v34 row_ror:2 row_mask:0xf bank_mask:0xf
	s_nop 0
	v_mov_b32_dpp v38, v28 row_shr:1 row_mask:0xf bank_mask:0xf
	v_fma_f32 v34, v29, v109, v93
	v_mov_b32_dpp v39, v28 row_shr:2 row_mask:0xf bank_mask:0xf
	v_fma_f32 v28, v28, v108, v92
	v_pk_mul_f32 v[38:39], v[32:33], v[38:39]
	s_nop 0
	v_add_f32_e32 v28, v28, v38
	v_add_f32_e32 v41, v28, v39
	v_mov_b32_e32 v38, v189
	v_mov_b32_e32 v39, v189
	s_nop 0
	v_mov_b32_dpp v38, v35 row_ror:1 row_mask:0xf bank_mask:0xf
	v_mov_b32_dpp v39, v35 row_ror:2 row_mask:0xf bank_mask:0xf
	v_mov_b32_e32 v35, v189
	v_mov_b32_dpp v38, v29 row_shr:1 row_mask:0xf bank_mask:0xf
	v_mov_b32_dpp v39, v29 row_shr:2 row_mask:0xf bank_mask:0xf
	v_pk_mul_f32 v[28:29], v[100:101], v[38:39]
	v_mov_b32_dpp v35, v36 row_ror:2 row_mask:0xf bank_mask:0xf
	v_add_f32_e32 v28, v34, v28
	v_mov_b32_e32 v34, v189
	v_add_f32_e32 v42, v28, v29
	v_mov_b32_dpp v35, v30 row_shr:2 row_mask:0xf bank_mask:0xf
	v_mov_b32_dpp v34, v36 row_ror:1 row_mask:0xf bank_mask:0xf
	v_mov_b32_e32 v28, v126
	v_mov_b32_e32 v29, v102
	v_mov_b32_dpp v34, v30 row_shr:1 row_mask:0xf bank_mask:0xf
	v_fma_f32 v30, v30, v110, v94
	v_pk_mul_f32 v[34:35], v[28:29], v[34:35]
	v_mov_b32_e32 v102, v127
	v_add_f32_e32 v30, v30, v34
	v_add_f32_e32 v43, v30, v35
	v_mov_b32_e32 v34, v189
	v_mov_b32_e32 v35, v189
	v_fma_f32 v36, v31, v111, v95
	v_mov_b32_dpp v34, v37 row_ror:1 row_mask:0xf bank_mask:0xf
	v_mov_b32_dpp v35, v37 row_ror:2 row_mask:0xf bank_mask:0xf
	s_nop 0
	v_mov_b32_dpp v34, v31 row_shr:1 row_mask:0xf bank_mask:0xf
	v_mov_b32_dpp v35, v31 row_shr:2 row_mask:0xf bank_mask:0xf
	v_pk_mul_f32 v[30:31], v[102:103], v[34:35]
	s_nop 0
	v_add_f32_e32 v30, v36, v30
	v_add_f32_e32 v44, v30, v31
	v_add_u32_e32 v30, s2, v40
	v_mov_b32_e32 v31, v189
	v_lshl_add_u64 v[30:31], v[30:31], 2, s[6:7]
	global_load_dwordx4 v[34:37], v[30:31], off
	v_mov_b32_e32 v38, v189
	v_mov_b32_e32 v39, v189
	v_mov_b32_e32 v30, v116
	v_mov_b32_e32 v31, v76
	v_mov_b32_e32 v76, v117
	s_waitcnt vmcnt(0)
; __device__ __forceinline__ unsigned cvt_pk_bf16(float lo, float hi) { unsigned r; asm volatile("v_cvt_pk_bf16_f32 %0, %1, %2" : "=v"(r) : "v"(lo), "v"(hi)); return r; }
;     template <bool SAMP, bool BND>
;     __device__ __forceinline__ void conv_act(const f32x4 (&acc)[2][2][4][2], const Unit& u, int wr, int fr, int rbase, int ccol, LAS float* halo, const LAS float* wl_) const {
;     ...
;                         const f32x4 cur = acc[ai][bj][m][n];
; #pragma unroll
;                         for (int j = 0; j < 4; ++j) {
;                             const float p1 = dppf<0x111>(dppf<0x121>(0.f, prev[j]), cur[j]);
;                             const float p2 = dppf<0x112>(dppf<0x122>(0.f, prev[j]), cur[j]);
;                             a[bj][j] = BB[bj][j] + W2[bj][j] * cur[j] + W1[bj][j] * (BND ? p1 * z1 : p1) + W0[bj][j] * (BND ? p2 * z2 : p2);
;                         }
;                         if (BND) { if (ok && t4 < 2 && row >= 2046) *(f32x4*)(offp + (unsigned)(((((row + 2) >> 11) - 1) * 2 + t4) * UPW + bj * DFF + u.pn * 128 + ccol + 4 * n)) = cur; }
;                         __builtin_amdgcn_sched_barrier(0);
;                     }
;                     float o[4];
; #pragma unroll
;                     for (int j = 0; j < 4; ++j) { const float g = a[0][j], v = a[1][j]; o[j] = g * __builtin_amdgcn_rcpf(1.0f + __builtin_amdgcn_exp2f(-g * LOG2E)) * v; }
;                     u32x2 w; w.x = cvt_pk_bf16(o[0], o[1]); w.y = cvt_pk_bf16(o[2], o[3]);
;                     if (n == 0) keep[ai][m] = w;
;                     else if (ok) { u32x4 w4; w4.x = keep[ai][m].x; w4.y = keep[ai][m].y; w4.z = w.x; w4.w = w.y; *(u32x4*)(ACT + (unsigned)(row * DFF + u.pn * 128 + ccol)) = w4; }
	v_mov_b32_dpp v38, v34 row_ror:1 row_mask:0xf bank_mask:0xf
	v_mov_b32_dpp v39, v34 row_ror:2 row_mask:0xf bank_mask:0xf
	s_nop 0
	v_mov_b32_dpp v38, v24 row_shr:1 row_mask:0xf bank_mask:0xf
	v_fma_f32 v34, v25, v85, v67
	v_mov_b32_dpp v39, v24 row_shr:2 row_mask:0xf bank_mask:0xf
	v_fma_f32 v24, v24, v84, v66
	v_pk_mul_f32 v[38:39], v[30:31], v[38:39]
	s_nop 0
	v_add_f32_e32 v24, v24, v38
	v_add_f32_e32 v40, v24, v39
	v_mov_b32_e32 v38, v189
	v_mov_b32_e32 v39, v189
	s_nop 0
	v_mov_b32_dpp v38, v35 row_ror:1 row_mask:0xf bank_mask:0xf
	v_mov_b32_dpp v39, v35 row_ror:2 row_mask:0xf bank_mask:0xf
	v_mov_b32_e32 v35, v189
	v_mov_b32_dpp v38, v25 row_shr:1 row_mask:0xf bank_mask:0xf
	v_mov_b32_dpp v39, v25 row_shr:2 row_mask:0xf bank_mask:0xf
	v_pk_mul_f32 v[24:25], v[76:77], v[38:39]
	v_mov_b32_dpp v35, v36 row_ror:2 row_mask:0xf bank_mask:0xf
	v_add_f32_e32 v24, v34, v24
	v_mov_b32_e32 v34, v189
	v_add_f32_e32 v38, v24, v25
	v_mov_b32_dpp v35, v26 row_shr:2 row_mask:0xf bank_mask:0xf
	v_mov_b32_dpp v34, v36 row_ror:1 row_mask:0xf bank_mask:0xf
	v_mov_b32_e32 v24, v118
	v_mov_b32_e32 v25, v78
	v_mov_b32_dpp v34, v26 row_shr:1 row_mask:0xf bank_mask:0xf
	v_fma_f32 v26, v26, v86, v68
	v_pk_mul_f32 v[34:35], v[24:25], v[34:35]
	v_mov_b32_e32 v78, v119
	v_add_f32_e32 v26, v26, v34
	v_add_f32_e32 v36, v26, v35
	v_mov_b32_e32 v34, v189
	v_mov_b32_e32 v35, v189
	s_nop 0
	v_mov_b32_dpp v34, v37 row_ror:1 row_mask:0xf bank_mask:0xf
	v_mov_b32_dpp v35, v37 row_ror:2 row_mask:0xf bank_mask:0xf
	v_fma_f32 v37, v27, v87, v69
	v_mov_b32_dpp v34, v27 row_shr:1 row_mask:0xf bank_mask:0xf
	v_mov_b32_dpp v35, v27 row_shr:2 row_mask:0xf bank_mask:0xf
	v_pk_mul_f32 v[26:27], v[78:79], v[34:35]
	s_nop 0
	v_add_f32_e32 v26, v37, v26
	v_add_f32_e32 v26, v26, v27
	v_mul_f32_e32 v35, 0xbfb8aa3b, v43
	v_exp_f32_e32 v35, v35
	v_mul_f32_e32 v27, 0xbfb8aa3b, v41
	v_exp_f32_e32 v27, v27
	v_mul_f32_e32 v34, 0xbfb8aa3b, v42
	v_add_f32_e32 v35, 1.0, v35
	v_rcp_f32_e32 v35, v35
	v_exp_f32_e32 v34, v34
	v_add_f32_e32 v27, 1.0, v27
	v_rcp_f32_e32 v27, v27
	v_mul_f32_e32 v35, v43, v35
	v_mul_f32_e32 v35, v35, v36
	v_mul_f32_e32 v36, 0xbfb8aa3b, v44
	v_exp_f32_e32 v36, v36
	v_add_f32_e32 v34, 1.0, v34
	v_rcp_f32_e32 v34, v34
	v_mul_f32_e32 v27, v41, v27
	v_add_f32_e32 v36, 1.0, v36
	v_rcp_f32_e32 v36, v36
	v_mul_f32_e32 v27, v27, v40
	v_mul_f32_e32 v34, v42, v34
	v_mul_f32_e32 v34, v34, v38
	v_mul_f32_e32 v36, v44, v36
	v_mul_f32_e32 v26, v36, v26
	v_cvt_pk_bf16_f32 v90, v27, v34
	v_cvt_pk_bf16_f32 v91, v35, v26
	v_add_u32_e32 v26, 0x58000, v56
	v_mov_b32_e32 v27, v189
	v_lshl_add_u64 v[26:27], v[26:27], 1, s[4:5]
	global_store_dwordx4 v[26:27], v[88:91], off
	v_mad_u32_u24 v38, v154, s1, v146
	v_add_u32_e32 v26, s3, v38
	v_mov_b32_e32 v27, v189
	v_lshl_add_u64 v[26:27], v[26:27], 2, s[6:7]
	global_load_dwordx4 v[34:37], v[26:27], off
	v_mov_b32_e32 v26, v189
	v_mov_b32_e32 v27, v189
	s_waitcnt vmcnt(0)
	v_mov_b32_dpp v26, v34 row_ror:1 row_mask:0xf bank_mask:0xf
	v_mov_b32_dpp v27, v34 row_ror:2 row_mask:0xf bank_mask:0xf
	s_nop 0
	v_mov_b32_dpp v26, v20 row_shr:1 row_mask:0xf bank_mask:0xf
	v_mov_b32_dpp v27, v20 row_shr:2 row_mask:0xf bank_mask:0xf
	v_fma_f32 v20, v20, v108, v92
	v_pk_mul_f32 v[26:27], v[32:33], v[26:27]
	s_nop 0
	v_add_f32_e32 v20, v20, v26
	v_add_f32_e32 v34, v20, v27
	v_mov_b32_e32 v26, v189
	v_mov_b32_e32 v27, v189
	s_nop 0
	v_mov_b32_dpp v26, v35 row_ror:1 row_mask:0xf bank_mask:0xf
	v_mov_b32_dpp v27, v35 row_ror:2 row_mask:0xf bank_mask:0xf
	v_fma_f32 v35, v21, v109, v93
	v_mov_b32_dpp v26, v21 row_shr:1 row_mask:0xf bank_mask:0xf
	v_mov_b32_dpp v27, v21 row_shr:2 row_mask:0xf bank_mask:0xf
	v_pk_mul_f32 v[20:21], v[100:101], v[26:27]
	s_nop 0
	v_add_f32_e32 v20, v35, v20
	v_add_f32_e32 v35, v20, v21
	v_mov_b32_e32 v20, v189
	v_mov_b32_e32 v21, v189
	s_nop 0
	v_mov_b32_dpp v20, v36 row_ror:1 row_mask:0xf bank_mask:0xf
	v_mov_b32_dpp v21, v36 row_ror:2 row_mask:0xf bank_mask:0xf
	s_nop 0
	v_mov_b32_dpp v20, v22 row_shr:1 row_mask:0xf bank_mask:0xf
	v_mov_b32_dpp v21, v22 row_shr:2 row_mask:0xf bank_mask:0xf
	v_fma_f32 v22, v22, v110, v94
	v_pk_mul_f32 v[20:21], v[28:29], v[20:21]
	s_nop 0
	v_add_f32_e32 v20, v22, v20
	v_add_f32_e32 v36, v20, v21
	v_mov_b32_e32 v20, v189
	v_mov_b32_e32 v21, v189
	v_fma_f32 v22, v23, v111, v95
	v_mov_b32_dpp v20, v37 row_ror:1 row_mask:0xf bank_mask:0xf
	v_mov_b32_dpp v21, v37 row_ror:2 row_mask:0xf bank_mask:0xf
	s_nop 0
	v_mov_b32_dpp v20, v23 row_shr:1 row_mask:0xf bank_mask:0xf
	v_mov_b32_dpp v21, v23 row_shr:2 row_mask:0xf bank_mask:0xf
	v_pk_mul_f32 v[20:21], v[102:103], v[20:21]
	s_nop 0
	v_add_f32_e32 v20, v22, v20
	v_add_f32_e32 v37, v20, v21
	v_add_u32_e32 v20, s2, v38
	v_mov_b32_e32 v21, v189
	v_lshl_add_u64 v[20:21], v[20:21], 2, s[6:7]
	global_load_dwordx4 v[20:23], v[20:21], off
	v_mov_b32_e32 v26, v189
	v_mov_b32_e32 v27, v189
	s_waitcnt vmcnt(0)
; __device__ __forceinline__ unsigned cvt_pk_bf16(float lo, float hi) { unsigned r; asm volatile("v_cvt_pk_bf16_f32 %0, %1, %2" : "=v"(r) : "v"(lo), "v"(hi)); return r; }
;     template <bool SAMP, bool BND>
;     __device__ __forceinline__ void conv_act(const f32x4 (&acc)[2][2][4][2], const Unit& u, int wr, int fr, int rbase, int ccol, LAS float* halo, const LAS float* wl_) const {
;     ...
;                         const f32x4 cur = acc[ai][bj][m][n];
; #pragma unroll
;                         for (int j = 0; j < 4; ++j) {
;                             const float p1 = dppf<0x111>(dppf<0x121>(0.f, prev[j]), cur[j]);
;                             const float p2 = dppf<0x112>(dppf<0x122>(0.f, prev[j]), cur[j]);
;                             a[bj][j] = BB[bj][j] + W2[bj][j] * cur[j] + W1[bj][j] * (BND ? p1 * z1 : p1) + W0[bj][j] * (BND ? p2 * z2 : p2);
;                         }
;                         if (BND) { if (ok && t4 < 2 && row >= 2046) *(f32x4*)(offp + (unsigned)(((((row + 2) >> 11) - 1) * 2 + t4) * UPW + bj * DFF + u.pn * 128 + ccol + 4 * n)) = cur; }
;                         __builtin_amdgcn_sched_barrier(0);
;                     }
;                     float o[4];
; #pragma unroll
;                     for (int j = 0; j < 4; ++j) { const float g = a[0][j], v = a[1][j]; o[j] = g * __builtin_amdgcn_rcpf(1.0f + __builtin_amdgcn_exp2f(-g * LOG2E)) * v; }
;                     u32x2 w; w.x = cvt_pk_bf16(o[0], o[1]); w.y = cvt_pk_bf16(o[2], o[3]);
;                     if (n == 0) keep[ai][m] = w;
;                     else if (ok) { u32x4 w4; w4.x = keep[ai][m].x; w4.y = keep[ai][m].y; w4.z = w.x; w4.w = w.y; *(u32x4*)(ACT + (unsigned)(row * DFF + u.pn * 128 + ccol)) = w4; }
	v_mov_b32_dpp v26, v20 row_ror:1 row_mask:0xf bank_mask:0xf
	v_mov_b32_dpp v27, v20 row_ror:2 row_mask:0xf bank_mask:0xf
	s_nop 0
	v_mov_b32_dpp v26, v16 row_shr:1 row_mask:0xf bank_mask:0xf
	v_mov_b32_dpp v27, v16 row_shr:2 row_mask:0xf bank_mask:0xf
	v_fma_f32 v16, v16, v84, v66
	v_pk_mul_f32 v[26:27], v[30:31], v[26:27]
	s_nop 0
	v_add_f32_e32 v16, v16, v26
	v_add_f32_e32 v20, v16, v27
	v_mov_b32_e32 v26, v189
	v_mov_b32_e32 v27, v189
	s_nop 0
	v_mov_b32_dpp v26, v21 row_ror:1 row_mask:0xf bank_mask:0xf
	v_mov_b32_dpp v27, v21 row_ror:2 row_mask:0xf bank_mask:0xf
	v_fma_f32 v21, v17, v85, v67
	v_mov_b32_dpp v26, v17 row_shr:1 row_mask:0xf bank_mask:0xf
	v_mov_b32_dpp v27, v17 row_shr:2 row_mask:0xf bank_mask:0xf
	v_pk_mul_f32 v[16:17], v[76:77], v[26:27]
	s_nop 0
	v_add_f32_e32 v16, v21, v16
	v_add_f32_e32 v21, v16, v17
	v_mov_b32_e32 v16, v189
	v_mov_b32_e32 v17, v189
	s_nop 0
	v_mov_b32_dpp v16, v22 row_ror:1 row_mask:0xf bank_mask:0xf
	v_mov_b32_dpp v17, v22 row_ror:2 row_mask:0xf bank_mask:0xf
	s_nop 0
	v_mov_b32_dpp v16, v18 row_shr:1 row_mask:0xf bank_mask:0xf
	v_mov_b32_dpp v17, v18 row_shr:2 row_mask:0xf bank_mask:0xf
	v_fma_f32 v18, v18, v86, v68
	v_pk_mul_f32 v[16:17], v[24:25], v[16:17]
	s_nop 0
	v_add_f32_e32 v16, v18, v16
	v_add_f32_e32 v18, v16, v17
	v_mov_b32_e32 v16, v189
	v_mov_b32_e32 v17, v189
	s_nop 0
	v_mov_b32_dpp v16, v23 row_ror:1 row_mask:0xf bank_mask:0xf
	v_mov_b32_dpp v17, v23 row_ror:2 row_mask:0xf bank_mask:0xf
	s_nop 0
	v_mov_b32_dpp v16, v19 row_shr:1 row_mask:0xf bank_mask:0xf
	v_mov_b32_dpp v17, v19 row_shr:2 row_mask:0xf bank_mask:0xf
	v_fma_f32 v19, v19, v87, v69
	v_pk_mul_f32 v[16:17], v[78:79], v[16:17]
	s_nop 0
	v_add_f32_e32 v16, v19, v16
	v_add_f32_e32 v16, v16, v17
	v_mul_f32_e32 v17, 0xbfb8aa3b, v34
	v_exp_f32_e32 v17, v17
	v_mul_f32_e32 v19, 0xbfb8aa3b, v35
	v_exp_f32_e32 v19, v19
	v_add_f32_e32 v17, 1.0, v17
	v_rcp_f32_e32 v17, v17
	v_add_f32_e32 v19, 1.0, v19
	v_rcp_f32_e32 v19, v19
	v_mul_f32_e32 v17, v34, v17
	v_mul_f32_e32 v17, v17, v20
	v_mul_f32_e32 v20, 0xbfb8aa3b, v36
	v_exp_f32_e32 v20, v20
	v_mul_f32_e32 v19, v35, v19
	v_mul_f32_e32 v19, v19, v21
	v_cvt_pk_bf16_f32 v82, v17, v19
	v_add_f32_e32 v20, 1.0, v20
	v_rcp_f32_e32 v20, v20
	v_mov_b32_e32 v17, v189
	v_mul_f32_e32 v20, v36, v20
	v_mul_f32_e32 v18, v20, v18
	v_mul_f32_e32 v20, 0xbfb8aa3b, v37
	v_exp_f32_e32 v20, v20
	s_nop 0
	v_add_f32_e32 v20, 1.0, v20
	v_rcp_f32_e32 v20, v20
	s_nop 0
	v_mul_f32_e32 v20, v37, v20
	v_mul_f32_e32 v16, v20, v16
	v_cvt_pk_bf16_f32 v83, v18, v16
	v_add_u32_e32 v16, 0x63000, v56
	v_lshl_add_u64 v[16:17], v[16:17], 1, s[4:5]
	global_store_dwordx4 v[16:17], v[80:83], off
	v_mad_u32_u24 v22, v153, s1, v146
	v_add_u32_e32 v16, s3, v22
	v_mov_b32_e32 v17, v189
	v_lshl_add_u64 v[16:17], v[16:17], 2, s[6:7]
	global_load_dwordx4 v[16:19], v[16:17], off
	v_mov_b32_e32 v20, v189
	v_mov_b32_e32 v21, v189
	s_waitcnt vmcnt(0)
	v_mov_b32_dpp v20, v16 row_ror:1 row_mask:0xf bank_mask:0xf
	v_mov_b32_dpp v21, v16 row_ror:2 row_mask:0xf bank_mask:0xf
	s_nop 0
	v_mov_b32_dpp v20, v12 row_shr:1 row_mask:0xf bank_mask:0xf
	v_fma_f32 v16, v13, v109, v93
	v_mov_b32_dpp v21, v12 row_shr:2 row_mask:0xf bank_mask:0xf
	v_fma_f32 v12, v12, v108, v92
	v_pk_mul_f32 v[20:21], v[32:33], v[20:21]
	s_nop 0
	v_add_f32_e32 v12, v12, v20
	v_add_f32_e32 v23, v12, v21
	v_mov_b32_e32 v20, v189
	v_mov_b32_e32 v21, v189
	s_nop 0
	v_mov_b32_dpp v20, v17 row_ror:1 row_mask:0xf bank_mask:0xf
	v_mov_b32_dpp v21, v17 row_ror:2 row_mask:0xf bank_mask:0xf
	s_nop 0
	v_mov_b32_dpp v20, v13 row_shr:1 row_mask:0xf bank_mask:0xf
	v_mov_b32_dpp v21, v13 row_shr:2 row_mask:0xf bank_mask:0xf
	v_pk_mul_f32 v[12:13], v[100:101], v[20:21]
	s_nop 0
	v_add_f32_e32 v12, v16, v12
	v_add_f32_e32 v20, v12, v13
	v_mov_b32_e32 v12, v189
	v_mov_b32_e32 v13, v189
	s_nop 0
	v_mov_b32_dpp v12, v18 row_ror:1 row_mask:0xf bank_mask:0xf
	v_mov_b32_dpp v13, v18 row_ror:2 row_mask:0xf bank_mask:0xf
	s_nop 0
	v_mov_b32_dpp v12, v14 row_shr:1 row_mask:0xf bank_mask:0xf
	v_mov_b32_dpp v13, v14 row_shr:2 row_mask:0xf bank_mask:0xf
	v_fma_f32 v14, v14, v110, v94
	v_pk_mul_f32 v[12:13], v[28:29], v[12:13]
	s_nop 0
	v_add_f32_e32 v12, v14, v12
	v_add_f32_e32 v18, v12, v13
	v_mov_b32_e32 v12, v189
	v_mov_b32_e32 v13, v189
	v_fma_f32 v14, v15, v111, v95
	v_mov_b32_dpp v12, v19 row_ror:1 row_mask:0xf bank_mask:0xf
	v_mov_b32_dpp v13, v19 row_ror:2 row_mask:0xf bank_mask:0xf
	s_nop 0
	v_mov_b32_dpp v12, v15 row_shr:1 row_mask:0xf bank_mask:0xf
	v_mov_b32_dpp v13, v15 row_shr:2 row_mask:0xf bank_mask:0xf
	v_pk_mul_f32 v[12:13], v[102:103], v[12:13]
	s_nop 0
	v_add_f32_e32 v12, v14, v12
	v_add_f32_e32 v19, v12, v13
	v_add_u32_e32 v12, s2, v22
	v_mov_b32_e32 v13, v189
	v_lshl_add_u64 v[12:13], v[12:13], 2, s[6:7]
	global_load_dwordx4 v[12:15], v[12:13], off
	v_mov_b32_e32 v16, v189
	v_mov_b32_e32 v17, v189
	s_waitcnt vmcnt(0)
; __device__ __forceinline__ unsigned cvt_pk_bf16(float lo, float hi) { unsigned r; asm volatile("v_cvt_pk_bf16_f32 %0, %1, %2" : "=v"(r) : "v"(lo), "v"(hi)); return r; }
;     template <bool SAMP, bool BND>
;     __device__ __forceinline__ void conv_act(const f32x4 (&acc)[2][2][4][2], const Unit& u, int wr, int fr, int rbase, int ccol, LAS float* halo, const LAS float* wl_) const {
;     ...
;                         const f32x4 cur = acc[ai][bj][m][n];
; #pragma unroll
;                         for (int j = 0; j < 4; ++j) {
;                             const float p1 = dppf<0x111>(dppf<0x121>(0.f, prev[j]), cur[j]);
;                             const float p2 = dppf<0x112>(dppf<0x122>(0.f, prev[j]), cur[j]);
;                             a[bj][j] = BB[bj][j] + W2[bj][j] * cur[j] + W1[bj][j] * (BND ? p1 * z1 : p1) + W0[bj][j] * (BND ? p2 * z2 : p2);
;                         }
;                         if (BND) { if (ok && t4 < 2 && row >= 2046) *(f32x4*)(offp + (unsigned)(((((row + 2) >> 11) - 1) * 2 + t4) * UPW + bj * DFF + u.pn * 128 + ccol + 4 * n)) = cur; }
;                         __builtin_amdgcn_sched_barrier(0);
;                     }
;                     float o[4];
; #pragma unroll
;                     for (int j = 0; j < 4; ++j) { const float g = a[0][j], v = a[1][j]; o[j] = g * __builtin_amdgcn_rcpf(1.0f + __builtin_amdgcn_exp2f(-g * LOG2E)) * v; }
;                     u32x2 w; w.x = cvt_pk_bf16(o[0], o[1]); w.y = cvt_pk_bf16(o[2], o[3]);
;                     if (n == 0) keep[ai][m] = w;
;                     else if (ok) { u32x4 w4; w4.x = keep[ai][m].x; w4.y = keep[ai][m].y; w4.z = w.x; w4.w = w.y; *(u32x4*)(ACT + (unsigned)(row * DFF + u.pn * 128 + ccol)) = w4; }
	v_mov_b32_dpp v16, v12 row_ror:1 row_mask:0xf bank_mask:0xf
	v_mov_b32_dpp v17, v12 row_ror:2 row_mask:0xf bank_mask:0xf
	s_nop 0
	v_mov_b32_dpp v16, v8 row_shr:1 row_mask:0xf bank_mask:0xf
	v_mov_b32_dpp v17, v8 row_shr:2 row_mask:0xf bank_mask:0xf
	v_fma_f32 v8, v8, v84, v66
	v_pk_mul_f32 v[16:17], v[30:31], v[16:17]
	s_nop 0
	v_add_f32_e32 v8, v8, v16
	v_add_f32_e32 v12, v8, v17
	v_mov_b32_e32 v16, v189
	v_mov_b32_e32 v17, v189
	s_nop 0
	v_mov_b32_dpp v16, v13 row_ror:1 row_mask:0xf bank_mask:0xf
	v_mov_b32_dpp v17, v13 row_ror:2 row_mask:0xf bank_mask:0xf
	v_fma_f32 v13, v9, v85, v67
	v_mov_b32_dpp v16, v9 row_shr:1 row_mask:0xf bank_mask:0xf
	v_mov_b32_dpp v17, v9 row_shr:2 row_mask:0xf bank_mask:0xf
	v_pk_mul_f32 v[8:9], v[76:77], v[16:17]
	s_nop 0
	v_add_f32_e32 v8, v13, v8
	v_add_f32_e32 v13, v8, v9
	v_mov_b32_e32 v8, v189
	v_mov_b32_e32 v9, v189
	s_nop 0
	v_mov_b32_dpp v8, v14 row_ror:1 row_mask:0xf bank_mask:0xf
	v_mov_b32_dpp v9, v14 row_ror:2 row_mask:0xf bank_mask:0xf
	s_nop 0
	v_mov_b32_dpp v8, v10 row_shr:1 row_mask:0xf bank_mask:0xf
	v_mov_b32_dpp v9, v10 row_shr:2 row_mask:0xf bank_mask:0xf
	v_fma_f32 v10, v10, v86, v68
	v_pk_mul_f32 v[8:9], v[24:25], v[8:9]
	s_nop 0
	v_add_f32_e32 v8, v10, v8
	v_add_f32_e32 v10, v8, v9
	v_mov_b32_e32 v8, v189
	v_mov_b32_e32 v9, v189
	s_nop 0
	v_mov_b32_dpp v8, v15 row_ror:1 row_mask:0xf bank_mask:0xf
	v_mov_b32_dpp v9, v15 row_ror:2 row_mask:0xf bank_mask:0xf
	s_nop 0
	v_mov_b32_dpp v8, v11 row_shr:1 row_mask:0xf bank_mask:0xf
	v_mov_b32_dpp v9, v11 row_shr:2 row_mask:0xf bank_mask:0xf
	v_fma_f32 v11, v11, v87, v69
	v_pk_mul_f32 v[8:9], v[78:79], v[8:9]
	s_nop 0
	v_add_f32_e32 v8, v11, v8
	v_add_f32_e32 v8, v8, v9
	v_mul_f32_e32 v9, 0xbfb8aa3b, v23
	v_exp_f32_e32 v9, v9
	v_mul_f32_e32 v11, 0xbfb8aa3b, v20
	v_exp_f32_e32 v11, v11
	v_add_f32_e32 v9, 1.0, v9
	v_rcp_f32_e32 v9, v9
	v_add_f32_e32 v11, 1.0, v11
	v_rcp_f32_e32 v11, v11
	v_mul_f32_e32 v9, v23, v9
	v_mul_f32_e32 v9, v9, v12
	v_mul_f32_e32 v12, 0xbfb8aa3b, v18
	v_exp_f32_e32 v12, v12
	v_mul_f32_e32 v11, v20, v11
	v_mul_f32_e32 v11, v11, v13
	v_cvt_pk_bf16_f32 v74, v9, v11
	v_add_f32_e32 v12, 1.0, v12
	v_rcp_f32_e32 v12, v12
	v_mov_b32_e32 v9, v189
	v_mul_f32_e32 v12, v18, v12
	v_mul_f32_e32 v10, v12, v10
	v_mul_f32_e32 v12, 0xbfb8aa3b, v19
	v_exp_f32_e32 v12, v12
	s_nop 0
	v_add_f32_e32 v12, 1.0, v12
	v_rcp_f32_e32 v12, v12
	s_nop 0
	v_mul_f32_e32 v12, v19, v12
	v_mul_f32_e32 v8, v12, v8
	v_cvt_pk_bf16_f32 v75, v10, v8
	v_add_u32_e32 v8, 0x6e000, v56
	v_lshl_add_u64 v[8:9], v[8:9], 1, s[4:5]
	global_store_dwordx4 v[8:9], v[72:75], off
	v_mad_u32_u24 v14, v152, s1, v146
	v_add_u32_e32 v8, s3, v14
	v_mov_b32_e32 v9, v189
	v_lshl_add_u64 v[8:9], v[8:9], 2, s[6:7]
	global_load_dwordx4 v[8:11], v[8:9], off
	v_mov_b32_e32 v12, v189
	v_mov_b32_e32 v13, v189
	v_fmac_f32_e32 v95, v7, v111
	s_waitcnt vmcnt(0)
	v_mov_b32_dpp v12, v8 row_ror:1 row_mask:0xf bank_mask:0xf
	v_mov_b32_dpp v13, v8 row_ror:2 row_mask:0xf bank_mask:0xf
	s_nop 0
	v_mov_b32_dpp v12, v4 row_shr:1 row_mask:0xf bank_mask:0xf
	v_fma_f32 v8, v5, v109, v93
	v_mov_b32_dpp v13, v4 row_shr:2 row_mask:0xf bank_mask:0xf
	v_fma_f32 v4, v4, v108, v92
	v_pk_mul_f32 v[12:13], v[32:33], v[12:13]
	s_nop 0
	v_add_f32_e32 v4, v4, v12
	v_add_f32_e32 v15, v4, v13
	v_mov_b32_e32 v12, v189
	v_mov_b32_e32 v13, v189
	s_nop 0
	v_mov_b32_dpp v12, v9 row_ror:1 row_mask:0xf bank_mask:0xf
	v_mov_b32_dpp v13, v9 row_ror:2 row_mask:0xf bank_mask:0xf
	s_nop 0
	v_mov_b32_dpp v12, v5 row_shr:1 row_mask:0xf bank_mask:0xf
	v_mov_b32_dpp v13, v5 row_shr:2 row_mask:0xf bank_mask:0xf
	v_pk_mul_f32 v[4:5], v[100:101], v[12:13]
	s_nop 0
	v_add_f32_e32 v4, v8, v4
	v_add_f32_e32 v12, v4, v5
	v_mov_b32_e32 v4, v189
	v_mov_b32_e32 v5, v189
	s_nop 0
	v_mov_b32_dpp v4, v10 row_ror:1 row_mask:0xf bank_mask:0xf
	v_mov_b32_dpp v5, v10 row_ror:2 row_mask:0xf bank_mask:0xf
	s_nop 0
	v_mov_b32_dpp v4, v6 row_shr:1 row_mask:0xf bank_mask:0xf
	v_mov_b32_dpp v5, v6 row_shr:2 row_mask:0xf bank_mask:0xf
	v_fma_f32 v6, v6, v110, v94
	v_pk_mul_f32 v[4:5], v[28:29], v[4:5]
	s_nop 0
	v_add_f32_e32 v4, v6, v4
	v_add_f32_e32 v10, v4, v5
	v_mov_b32_e32 v4, v189
	v_mov_b32_e32 v5, v189
	s_nop 0
	v_mov_b32_dpp v4, v11 row_ror:1 row_mask:0xf bank_mask:0xf
	v_mov_b32_dpp v5, v11 row_ror:2 row_mask:0xf bank_mask:0xf
	s_nop 0
	v_mov_b32_dpp v4, v7 row_shr:1 row_mask:0xf bank_mask:0xf
	v_mov_b32_dpp v5, v7 row_shr:2 row_mask:0xf bank_mask:0xf
	v_pk_mul_f32 v[4:5], v[102:103], v[4:5]
	s_nop 0
	v_add_f32_e32 v4, v95, v4
	v_add_f32_e32 v11, v4, v5
	v_add_u32_e32 v4, s2, v14
	v_mov_b32_e32 v5, v189
	v_lshl_add_u64 v[4:5], v[4:5], 2, s[6:7]
	global_load_dwordx4 v[4:7], v[4:5], off
	v_mov_b32_e32 v8, v189
	v_mov_b32_e32 v9, v189
	v_fmac_f32_e32 v69, v3, v87
	s_waitcnt vmcnt(0)
; #define LAS __attribute__((address_space(3)))
; __device__ __forceinline__ unsigned cvt_pk_bf16(float lo, float hi) { unsigned r; asm volatile("v_cvt_pk_bf16_f32 %0, %1, %2" : "=v"(r) : "v"(lo), "v"(hi)); return r; }
; __device__ __forceinline__ const float* karg(int k) { kargp_t p = (kargp_t)__builtin_amdgcn_kernarg_segment_ptr(); asm volatile("" : "+s"(p)); return *(const float* const __attribute__((address_space(4)))*)(p + 8 * k); }
;     __device__ __forceinline__ void pre_issue(const Unit& u, int ui, int wid, int lane, LAS unsigned char* lds) const {
;         pre_rows((const float*)((unsigned char*)karg(20) + WS_SSQ) + (1u << 18), u.pad, ui, wid, lane, lds);
;         const int arr = wid >> 1, hf = wid & 1;
;         const float* src = (arr < 3 ? karg(15) + (size_t)l * 3 * UPW + (size_t)arr * UPW : karg(16) + (size_t)l * UPW) + hf * DFF + u.pn * 128 + lane;
;         LAS unsigned* wd = (LAS unsigned*)(lds + EXTRA_OFF + X_W) + (ui & 1) * 1024 + arr * 256 + hf * 128;
;         __builtin_amdgcn_global_load_lds((const unsigned*)src, wd, 4, 0, 0);
;         __builtin_amdgcn_global_load_lds((const unsigned*)(src + 64), wd + 64, 4, 0, 0);
;     template <bool SAMP, bool BND>
;     __device__ __forceinline__ void conv_act(const f32x4 (&acc)[2][2][4][2], const Unit& u, int wr, int fr, int rbase, int ccol, LAS float* halo, const LAS float* wl_) const {
;     ...
;                     for (int j = 0; j < 4; ++j) { const float g = a[0][j], v = a[1][j]; o[j] = g * __builtin_amdgcn_rcpf(1.0f + __builtin_amdgcn_exp2f(-g * LOG2E)) * v; }
;                     u32x2 w; w.x = cvt_pk_bf16(o[0], o[1]); w.y = cvt_pk_bf16(o[2], o[3]);
;                     if (n == 0) keep[ai][m] = w;
;                     else if (ok) { u32x4 w4; w4.x = keep[ai][m].x; w4.y = keep[ai][m].y; w4.z = w.x; w4.w = w.y; *(u32x4*)(ACT + (unsigned)(row * DFF + u.pn * 128 + ccol)) = w4; }
	v_mov_b32_dpp v8, v4 row_ror:1 row_mask:0xf bank_mask:0xf
	v_mov_b32_dpp v9, v4 row_ror:2 row_mask:0xf bank_mask:0xf
	s_nop 0
	v_mov_b32_dpp v8, v0 row_shr:1 row_mask:0xf bank_mask:0xf
	v_mov_b32_dpp v9, v0 row_shr:2 row_mask:0xf bank_mask:0xf
	v_fma_f32 v0, v0, v84, v66
	v_pk_mul_f32 v[8:9], v[30:31], v[8:9]
	s_nop 0
	v_add_f32_e32 v0, v0, v8
	v_add_f32_e32 v4, v0, v9
	v_mov_b32_e32 v8, v189
	v_mov_b32_e32 v9, v189
	s_nop 0
	v_mov_b32_dpp v8, v5 row_ror:1 row_mask:0xf bank_mask:0xf
	v_mov_b32_dpp v9, v5 row_ror:2 row_mask:0xf bank_mask:0xf
	v_fma_f32 v5, v1, v85, v67
	v_mov_b32_dpp v8, v1 row_shr:1 row_mask:0xf bank_mask:0xf
	v_mov_b32_dpp v9, v1 row_shr:2 row_mask:0xf bank_mask:0xf
	v_pk_mul_f32 v[0:1], v[76:77], v[8:9]
	s_nop 0
	v_add_f32_e32 v0, v5, v0
	v_add_f32_e32 v5, v0, v1
	v_mov_b32_e32 v0, v189
	v_mov_b32_e32 v1, v189
	s_nop 0
	v_mov_b32_dpp v0, v6 row_ror:1 row_mask:0xf bank_mask:0xf
	v_mov_b32_dpp v1, v6 row_ror:2 row_mask:0xf bank_mask:0xf
	s_nop 0
	v_mov_b32_dpp v0, v2 row_shr:1 row_mask:0xf bank_mask:0xf
	v_mov_b32_dpp v1, v2 row_shr:2 row_mask:0xf bank_mask:0xf
	v_fma_f32 v2, v2, v86, v68
	v_pk_mul_f32 v[0:1], v[24:25], v[0:1]
	s_nop 0
	v_add_f32_e32 v0, v2, v0
	v_add_f32_e32 v2, v0, v1
	v_mov_b32_e32 v0, v189
	v_mov_b32_e32 v1, v189
	s_nop 0
	v_mov_b32_dpp v0, v7 row_ror:1 row_mask:0xf bank_mask:0xf
	v_mov_b32_dpp v1, v7 row_ror:2 row_mask:0xf bank_mask:0xf
	s_nop 0
	v_mov_b32_dpp v0, v3 row_shr:1 row_mask:0xf bank_mask:0xf
	v_mov_b32_dpp v1, v3 row_shr:2 row_mask:0xf bank_mask:0xf
	v_pk_mul_f32 v[0:1], v[78:79], v[0:1]
	s_nop 0
	v_add_f32_e32 v0, v69, v0
	v_add_f32_e32 v0, v0, v1
	v_mul_f32_e32 v1, 0xbfb8aa3b, v15
	v_exp_f32_e32 v1, v1
	v_mul_f32_e32 v3, 0xbfb8aa3b, v12
	v_exp_f32_e32 v3, v3
	v_add_f32_e32 v1, 1.0, v1
	v_rcp_f32_e32 v1, v1
	v_add_f32_e32 v3, 1.0, v3
	v_rcp_f32_e32 v3, v3
	v_mul_f32_e32 v1, v15, v1
	v_mul_f32_e32 v1, v1, v4
	v_mul_f32_e32 v4, 0xbfb8aa3b, v10
	v_exp_f32_e32 v4, v4
	v_mul_f32_e32 v3, v12, v3
	v_mul_f32_e32 v3, v3, v5
	v_cvt_pk_bf16_f32 v66, v1, v3
	v_add_f32_e32 v4, 1.0, v4
	v_rcp_f32_e32 v4, v4
	v_mov_b32_e32 v1, v189
	v_mul_f32_e32 v4, v10, v4
	v_mul_f32_e32 v2, v4, v2
	v_mul_f32_e32 v4, 0xbfb8aa3b, v11
	v_exp_f32_e32 v4, v4
	s_nop 0
	v_add_f32_e32 v4, 1.0, v4
	v_rcp_f32_e32 v4, v4
	s_nop 0
	v_mul_f32_e32 v4, v11, v4
	v_mul_f32_e32 v0, v4, v0
	v_cvt_pk_bf16_f32 v67, v2, v0
	v_add_u32_e32 v0, 0x79000, v56
	v_lshl_add_u64 v[0:1], v[0:1], 1, s[4:5]
	global_store_dwordx4 v[0:1], v[64:67], off
.LBB0_768:
	s_andn2_b64 vcc, exec, s[36:37]
	s_mov_b64 s[2:3], -1
	s_cbranch_vccnz .LBB0_741
	v_readlane_b32 s0, v255, 11
	v_readlane_b32 s1, v255, 12
	s_waitcnt lgkmcnt(0)
	v_readlane_b32 s2, v255, 52
	v_readlane_b32 s3, v255, 53
	s_nop 4
	s_lshl_b32 s0, s15, 10
	s_and_b32 s0, s0, 0x400
	s_lshl_b32 s0, s0, 2
	s_add_i32 s1, s65, s0
	s_ashr_i32 s5, s34, 31
	s_add_u32 s4, s34, s39
	s_addc_u32 s5, s5, s66
	s_lshl_b64 s[4:5], s[4:5], 4
	s_waitcnt lgkmcnt(0)
	s_add_u32 s2, s2, s4
	s_addc_u32 s3, s3, s5
	v_mov_b32_e32 v195, v189
	v_lshl_add_u64 v[0:1], s[2:3], 0, v[194:195]
	s_mov_b64 s[2:3], 0xa800000
	v_lshl_add_u64 v[2:3], v[0:1], 0, s[2:3]
	s_mov_b32 m0, s1
	s_mov_b64 s[2:3], 0xa800100
	global_load_lds_dword v[2:3], off
	v_lshl_add_u64 v[0:1], v[0:1], 0, s[2:3]
	s_add_i32 m0, s1, 0x100
	s_mov_b64 s[4:5], -1
	global_load_lds_dword v[0:1], off
	s_and_b64 vcc, exec, s[12:13]
	s_cbranch_vccz .LBB0_771
	v_readlane_b32 s2, v255, 11
	v_readlane_b32 s3, v255, 12
	v_readlane_b32 s2, v255, 56
	v_readlane_b32 s3, v255, 57
	s_nop 4
	s_mov_b64 s[4:5], 0
.LBB0_771:
	s_andn2_b64 vcc, exec, s[4:5]
	v_readlane_b32 s4, v255, 26
	v_readlane_b32 s5, v255, 27
	s_cbranch_vccnz .LBB0_773
	s_waitcnt lgkmcnt(0)
	v_readlane_b32 s2, v255, 11
	v_readlane_b32 s3, v255, 12
	v_readlane_b32 s2, v255, 54
	v_readlane_b32 s3, v255, 55
	s_nop 4
	v_readlane_b32 s4, v255, 26
	v_readlane_b32 s5, v255, 27
	s_mul_i32 s1, s4, 0x10800
	s_waitcnt lgkmcnt(0)
	s_add_u32 s2, s2, s1
	s_mul_hi_u32 s1, s4, 0x10800
	v_readlane_b32 s4, v255, 24
	s_addc_u32 s3, s3, s1
	v_readlane_b32 s5, v255, 25

; #define LAS __attribute__((address_space(3)))
;     template <bool SAMP, bool BND>
;     __device__ __forceinline__ void conv_act(const f32x4 (&acc)[2][2][4][2], const Unit& u, int wr, int fr, int rbase, int ccol, LAS float* halo, const LAS float* wl_) const {
;         unsigned char* wsb = (unsigned char*)karg(20);
;         bf16_t* ACT = (bf16_t*)(wsb + WS_ACT); const float* sffn = karg(5) + (size_t)l * SB * 2 * UPW; float* offp = (float*)karg(19) + O_FP + (size_t)l * NB * 2 * UPW;
;         u32x2 keep[2][4];
; #pragma unroll
;         for (int n = 0; n < 2; ++n) {
;             f32x4 W0[2], W1[2], W2[2], BB[2];
; #pragma unroll
;             for (int bj = 0; bj < 2; ++bj) {
;                 const int tc = bj * 128 + ccol + 4 * n;
;                 W0[bj] = *(const LAS f32x4*)(wl_ + tc); W1[bj] = *(const LAS f32x4*)(wl_ + 256 + tc); W2[bj] = *(const LAS f32x4*)(wl_ + 512 + tc); BB[bj] = *(const LAS f32x4*)(wl_ + 768 + tc);
;             }
; #pragma unroll
;             for (int ai = 0; ai < 2; ++ai)
; #pragma unroll
;                 for (int m = 0; m < 4; ++m) {
;                     const int row = rbase + 128 * ai + 16 * m + fr;
;                     const bool ok = SAMP || (row < NP && !(ai == 0 && m == 0 && wr == 0 && fr < 2));
;                     const int t4 = (row + 2) & 2047;
;                     const float z1 = (BND && t4 == 2) ? 0.f : 1.f, z2 = (BND && (t4 == 2 || t4 == 3)) ? 0.f : 1.f;
;                     f32x4 a[2];
; #pragma unroll
;                     for (int bj = 0; bj < 2; ++bj) {
;                         f32x4 prev;
;                         if (SAMP) { const int s = (rbase + 128 * ai + 16 * m - NP) >> 4; prev = *(const f32x4*)(sffn + (unsigned)((s * 2 + (fr & 1)) * UPW + bj * DFF + u.pn * 128 + ccol + 4 * n)); }
;                         else if (m > 0) prev = acc[ai][bj][m > 0 ? m - 1 : 0][n];
;                         else { const int blk = 2 * ai + wr; prev = (f32x4){0.f, 0.f, 0.f, 0.f}; if (blk > 0) prev = *(const LAS f32x4*)(halo + ((blk - 1) * 2 + (fr & 1)) * 256 + bj * 128 + ccol + 4 * n); }
;                         const f32x4 cur = acc[ai][bj][m][n];
; #pragma unroll
;                         for (int j = 0; j < 4; ++j) {
;                             const float p1 = dppf<0x111>(dppf<0x121>(0.f, prev[j]), cur[j]);
;                             const float p2 = dppf<0x112>(dppf<0x122>(0.f, prev[j]), cur[j]);
.LBB0_776:
	v_readlane_b32 s0, v255, 50
	v_readlane_b32 s1, v255, 51
	s_nop 4
	v_readlane_b32 s42, v255, 52
	v_readlane_b32 s43, v255, 53
	s_nop 4
	v_add_u32_e32 v187, s19, v195
	s_mov_b32 s2, 0x8000
	v_readlane_b32 s8, v255, 26
	v_cmp_gt_i32_e64 s[4:5], s2, v187
	s_mul_i32 s2, s8, 0xb0000
	s_waitcnt lgkmcnt(0)
	s_add_u32 s0, s0, s2
	s_mul_hi_u32 s2, s8, 0xb0000
	s_addc_u32 s1, s1, s2
	v_cmp_lt_i32_e32 vcc, 1, v195
	s_add_u32 s2, s0, 0x10240000
	v_add_u32_e32 v148, 2, v187
	s_addc_u32 s3, s1, 0
	s_or_b64 s[0:1], s[20:21], vcc
	v_and_b32_e32 v149, 0x7ff, v148
	v_lshrrev_b32_e32 v133, 10, v148
	s_and_b64 s[40:41], s[0:1], s[4:5]
	v_subrev_co_u32_e32 v132, vcc, 2, v149
	s_movk_i32 s4, 0x7fd
	v_and_b32_e32 v133, 0x1ffffe, v133
	s_and_b64 s[0:1], s[40:41], vcc
	v_cmp_lt_i32_e32 vcc, s4, v187
	v_add_u32_e32 v231, v132, v133
	v_mov_b32_e32 v132, v189
	v_mov_b32_e32 v133, v189
	v_mov_b32_e32 v134, v189
	v_mov_b32_e32 v135, v189
	v_mov_b32_e32 v136, v189
	v_mov_b32_e32 v137, v189
	v_mov_b32_e32 v146, v189
	v_mov_b32_e32 v147, v189
	s_and_b64 s[52:53], vcc, s[0:1]
	s_movk_i32 s0, 0x1600
	v_mov_b32_dpp v132, v128 row_ror:1 row_mask:0xf bank_mask:0xf
	v_mov_b32_dpp v133, v128 row_ror:2 row_mask:0xf bank_mask:0xf
	v_mov_b32_dpp v134, v129 row_ror:1 row_mask:0xf bank_mask:0xf
	v_mov_b32_dpp v135, v129 row_ror:2 row_mask:0xf bank_mask:0xf
	v_mov_b32_dpp v136, v130 row_ror:1 row_mask:0xf bank_mask:0xf
	v_mov_b32_dpp v137, v130 row_ror:2 row_mask:0xf bank_mask:0xf
	v_mov_b32_dpp v146, v131 row_ror:1 row_mask:0xf bank_mask:0xf
	v_mov_b32_dpp v147, v131 row_ror:2 row_mask:0xf bank_mask:0xf
	v_mad_i32_i24 v150, v231, s0, v188
	v_mov_b32_dpp v132, v124 row_shr:1 row_mask:0xf bank_mask:0xf
	v_mov_b32_dpp v133, v124 row_shr:2 row_mask:0xf bank_mask:0xf
	v_mov_b32_dpp v134, v125 row_shr:1 row_mask:0xf bank_mask:0xf
	v_mov_b32_dpp v135, v125 row_shr:2 row_mask:0xf bank_mask:0xf
	v_mov_b32_dpp v136, v126 row_shr:1 row_mask:0xf bank_mask:0xf
	v_mov_b32_dpp v137, v126 row_shr:2 row_mask:0xf bank_mask:0xf
	v_mov_b32_dpp v146, v127 row_shr:1 row_mask:0xf bank_mask:0xf
	v_mov_b32_dpp v147, v127 row_shr:2 row_mask:0xf bank_mask:0xf
	v_readlane_b32 s9, v255, 27
	s_and_saveexec_b64 s[4:5], s[52:53]
	s_cbranch_execz .LBB0_778
	v_lshl_add_u32 v128, s38, 7, v150
	v_mov_b32_e32 v129, v189
	v_lshl_add_u64 v[128:129], v[128:129], 2, s[2:3]
	global_store_dwordx4 v[128:129], v[124:127], off

; #define LAS __attribute__((address_space(3)))
;     template <bool SAMP, bool BND>
;     __device__ __forceinline__ void conv_act(const f32x4 (&acc)[2][2][4][2], const Unit& u, int wr, int fr, int rbase, int ccol, LAS float* halo, const LAS float* wl_) const {
;     ...
;                     const int row = rbase + 128 * ai + 16 * m + fr;
;                     const bool ok = SAMP || (row < NP && !(ai == 0 && m == 0 && wr == 0 && fr < 2));
;                     const int t4 = (row + 2) & 2047;
;                     const float z1 = (BND && t4 == 2) ? 0.f : 1.f, z2 = (BND && (t4 == 2 || t4 == 3)) ? 0.f : 1.f;
;                     f32x4 a[2];
; #pragma unroll
;                     for (int bj = 0; bj < 2; ++bj) {
;                         f32x4 prev;
;                         if (SAMP) { const int s = (rbase + 128 * ai + 16 * m - NP) >> 4; prev = *(const f32x4*)(sffn + (unsigned)((s * 2 + (fr & 1)) * UPW + bj * DFF + u.pn * 128 + ccol + 4 * n)); }
;                         else if (m > 0) prev = acc[ai][bj][m > 0 ? m - 1 : 0][n];
;                         else { const int blk = 2 * ai + wr; prev = (f32x4){0.f, 0.f, 0.f, 0.f}; if (blk > 0) prev = *(const LAS f32x4*)(halo + ((blk - 1) * 2 + (fr & 1)) * 256 + bj * 128 + ccol + 4 * n); }
;                         const f32x4 cur = acc[ai][bj][m][n];
; #pragma unroll
;                         for (int j = 0; j < 4; ++j) {
;                             const float p1 = dppf<0x111>(dppf<0x121>(0.f, prev[j]), cur[j]);
;                             const float p2 = dppf<0x112>(dppf<0x122>(0.f, prev[j]), cur[j]);
;                             a[bj][j] = BB[bj][j] + W2[bj][j] * cur[j] + W1[bj][j] * (BND ? p1 * z1 : p1) + W0[bj][j] * (BND ? p2 * z2 : p2);
.LBB0_877:
	v_readlane_b32 s2, v255, 52
	v_readlane_b32 s3, v255, 53
	s_nop 4
	s_waitcnt lgkmcnt(0)
	v_cndmask_b32_e64 v144, v124, v128, s[98:99]
	v_cndmask_b32_e64 v145, v124, v128, s[100:101]
	v_cndmask_b32_e64 v128, v125, v129, s[98:99]
	v_cndmask_b32_e64 v146, v125, v129, s[100:101]
	v_cndmask_b32_e64 v147, v126, v130, s[100:101]
	v_cndmask_b32_e64 v129, v126, v130, s[98:99]
	v_cndmask_b32_e64 v148, v127, v131, s[100:101]
	v_cndmask_b32_e64 v130, v127, v131, s[98:99]
	s_and_b64 vcc, exec, s[6:7]
	v_mov_b32_e32 v141, 0
	v_mov_b32_e32 v142, 0
	v_mov_b32_e32 v143, 0
	s_cbranch_vccnz .LBB0_879
	ds_read_b128 v[140:143], v196 offset:512

;     __device__ __forceinline__ bool next(int i, Unit& u) const {
;         long L = (long)i * G + c; const int npr = 128 * nN;
;         u.kind = 0; u.pad = 0;
;         if (L < npr) { pg8::map_tile((int)L, 128, nN, u.pm, u.pn); u.nt = nt; u.slice = 0; u.nsplit = 1; u.tile = 0; u.a = A + (size_t)u.pm * tstep; u.b = Bt + (size_t)u.pn * tstep; return true; }
;         L -= npr; if (L >= 2 * nN * S) return false;
;         const int tile = (int)(L / S), sl = (int)(L % S), nts = nt / S;
;         u.pm = 128 + (tile & 1); u.pn = tile >> 1; u.nt = nts; u.slice = sl; u.nsplit = S; u.tile = tile;
;         u.a = A + (size_t)u.pm * tstep + (size_t)sl * nts * 128; u.b = Bt + (size_t)u.pn * tstep + (size_t)sl * nts * 128; return true;
; __global__ void __launch_bounds__(512, 2) fwd_mega(Args args) {
;     ...
;         {
;             PHASE_BEGIN
;             SchedGemm S{(const char*)ACT, (const char*)(wl + W_DOWN), 4, G, bxp, 44, 2, (l * 4 + 3) * 64, (size_t)256 * DFF * 2};
;             EpiRes E{XG, SSQ};
;             pg8::gemm_phase<EpiRes, SchedGemm, true, true>(lds, DFF, S, E);
.LBB0_962:
	s_or_b64 exec, exec, s[2:3]
	v_mov_b32_e32 v144, v191
	s_mov_b32 s38, s91
	s_mov_b64 s[0:1], s[88:89]
	s_waitcnt lgkmcnt(0)
	s_barrier
	v_readlane_b32 s2, v255, 52
	v_readlane_b32 s3, v255, 53
	s_nop 4
	v_readlane_b32 s0, v255, 22
	v_readlane_b32 s1, v255, 23
	s_mov_b32 s36, s75
	v_mov_b32_e32 v136, v191
	s_waitcnt lgkmcnt(0)
	s_add_u32 s39, s2, 0xaa00000
	s_addc_u32 s40, s3, 0
	s_add_u32 s0, s2, s0
	s_addc_u32 s1, s3, s1
	s_add_u32 s41, s0, 0x1400000
	s_addc_u32 s42, s1, 0
	v_readfirstlane_b32 s37, v144
	s_cmpk_gt_i32 s38, 0x1ff
	v_readfirstlane_b32 s7, v136
	s_mov_b64 s[8:9], -1
	s_cbranch_scc0 .LBB0_965
	s_and_b32 s0, s38, 0x7ffffff0
	s_mov_b64 s[8:9], 0
	s_cmpk_lg_i32 s0, 0x200
	s_mov_b64 s[4:5], 0
	s_cbranch_scc1 .LBB0_965
	s_bfe_u32 s1, s38, 0x10001
	s_lshr_b32 s0, s38, 1
	s_or_b32 s44, s1, 0x80
	s_bfe_u32 s24, s38, 0x30001
	s_and_b32 s6, s38, 1
	s_bfe_u32 s43, s0, 0x20001
	s_mul_i32 s0, s44, 0x160000
	s_add_u32 s0, s39, s0
	s_addc_u32 s1, s40, 0
	s_mul_i32 s4, s6, 0xb00
	s_add_u32 s26, s0, s4
	s_addc_u32 s27, s1, 0
	s_mul_i32 s0, s43, 0x160000
	s_add_u32 s0, s41, s0
	s_addc_u32 s1, s42, 0
	s_add_u32 s28, s0, s4
	s_addc_u32 s29, s1, 0
	s_mov_b32 s0, 2
	s_mov_b32 s1, 22
	s_mov_b64 s[4:5], -1

; #define LAS __attribute__((address_space(3)))
; __device__ __forceinline__ const float* karg(int k) { kargp_t p = (kargp_t)__builtin_amdgcn_kernarg_segment_ptr(); asm volatile("" : "+s"(p)); return *(const float* const __attribute__((address_space(4)))*)(p + 8 * k); }
; #define PG8_BAR __builtin_amdgcn_s_barrier()
; template <class Epi, class Sched, bool ALIGN_EPI = false, bool SP2 = false>
; __device__ __forceinline__ void gemm_phase(PG8_LAS unsigned char* lds, const int Kdim, const Sched& S, const Epi& E) {
;     ...
;         if (cur.nsplit > 1) {
;             float* part = (float*)((unsigned char*)karg(20) + WS_PART);
;             unsigned* cnt = (unsigned*)((unsigned char*)karg(20) + WS_CTL + 32768) + S.cbase + cur.tile;
;             f32x4* mine = (f32x4*)(part + ((size_t)cur.tile * 2 + cur.slice) * 65536) + tid;
; #pragma unroll
;             for (int a = 0; a < 2; ++a)
; #pragma unroll
;                 for (int b = 0; b < 2; ++b)
; #pragma unroll
;                     for (int m = 0; m < 4; ++m) {
; #pragma unroll
;                         for (int n = 0; n < 2; ++n) { f32x4* p_ = mine + (((a * 2 + b) * 4 + m) * 2 + n) * 512; asm volatile("global_store_dwordx4 %0, %1, off sc1\n\ts_nop 1" :: "v"(p_), "v"(acc[a][b][m][n]) : "memory"); }
;                         __builtin_amdgcn_sched_barrier(0);
;                     }
;             asm volatile("s_waitcnt vmcnt(0)" ::: "memory");
;             PG8_BAR;
;             LAS unsigned* flag = (LAS unsigned*)(lds + EXTRA_OFF + 8192 + 64);
;             if (tid == 0) {
;                 const unsigned old = __hip_atomic_fetch_add(cnt, 1u, __ATOMIC_RELAXED, __HIP_MEMORY_SCOPE_AGENT);
;                 if (old == 1u) { __builtin_amdgcn_fence(__ATOMIC_ACQUIRE, "agent"); asm volatile("s_waitcnt vmcnt(0)" ::: "memory"); }
;                 *flag = old;
.LBB0_982:
	s_cmp_lt_i32 s0, 2
	s_mov_b64 s[26:27], -1
	s_cbranch_scc1 .LBB0_991
	s_mov_b64 s[0:1], s[88:89]
	v_readlane_b32 s0, v255, 52
	v_readlane_b32 s1, v255, 53
	s_nop 4
	s_ashr_i32 s25, s24, 31
	s_ashr_i32 s7, s6, 31
	s_lshl_b64 s[28:29], s[24:25], 19
	s_mov_b64 s[26:27], s[88:89]
	s_waitcnt lgkmcnt(0)
	s_add_u32 s0, s0, s28
	s_addc_u32 s1, s1, s29
	s_add_u32 s0, s0, 0x20000000
	s_addc_u32 s1, s1, 0
	s_lshl_b64 s[28:29], s[6:7], 18
	s_add_u32 s28, s0, s28
	s_addc_u32 s29, s1, s29
	v_lshl_add_u64 v[128:129], v[136:137], 4, s[28:29]
	global_store_dwordx4 v[128:129], v[124:127], off sc1
	s_nop 1
	s_mov_b64 s[28:29], 0x2000
	v_lshl_add_u64 v[130:131], v[128:129], 0, s[28:29]
	global_store_dwordx4 v[130:131], v[120:123], off sc1
	s_nop 1
	s_mov_b64 s[28:29], 0x4000
	v_lshl_add_u64 v[130:131], v[128:129], 0, s[28:29]
	global_store_dwordx4 v[130:131], v[108:111], off sc1
	s_nop 1
	s_mov_b64 s[28:29], 0x6000
	v_lshl_add_u64 v[130:131], v[128:129], 0, s[28:29]
	global_store_dwordx4 v[130:131], v[104:107], off sc1
	s_nop 1
	s_mov_b64 s[28:29], 0x8000
	v_lshl_add_u64 v[130:131], v[128:129], 0, s[28:29]
	global_store_dwordx4 v[130:131], v[92:95], off sc1
	s_nop 1
	s_mov_b64 s[28:29], 0xa000
	v_lshl_add_u64 v[130:131], v[128:129], 0, s[28:29]
	global_store_dwordx4 v[130:131], v[88:91], off sc1
	s_nop 1
	s_mov_b64 s[28:29], 0xc000
	v_lshl_add_u64 v[130:131], v[128:129], 0, s[28:29]
	global_store_dwordx4 v[130:131], v[76:79], off sc1
	s_nop 1
	s_mov_b64 s[28:29], 0xe000
	v_lshl_add_u64 v[130:131], v[128:129], 0, s[28:29]
	global_store_dwordx4 v[130:131], v[72:75], off sc1
	s_nop 1
	s_mov_b64 s[28:29], 0x10000
	v_lshl_add_u64 v[130:131], v[128:129], 0, s[28:29]
	global_store_dwordx4 v[130:131], v[116:119], off sc1
	s_nop 1
	s_mov_b64 s[28:29], 0x12000
	v_lshl_add_u64 v[130:131], v[128:129], 0, s[28:29]
	global_store_dwordx4 v[130:131], v[112:115], off sc1
	s_nop 1
	s_mov_b64 s[28:29], 0x14000
	v_lshl_add_u64 v[130:131], v[128:129], 0, s[28:29]
	global_store_dwordx4 v[130:131], v[100:103], off sc1
	s_nop 1
	s_mov_b64 s[28:29], 0x16000
	v_lshl_add_u64 v[130:131], v[128:129], 0, s[28:29]
	global_store_dwordx4 v[130:131], v[96:99], off sc1
	s_nop 1
	s_mov_b64 s[28:29], 0x18000
	v_lshl_add_u64 v[130:131], v[128:129], 0, s[28:29]
	global_store_dwordx4 v[130:131], v[84:87], off sc1
	s_nop 1
	s_mov_b64 s[28:29], 0x1a000
	v_lshl_add_u64 v[130:131], v[128:129], 0, s[28:29]
	global_store_dwordx4 v[130:131], v[80:83], off sc1
	s_nop 1
	s_mov_b64 s[28:29], 0x1c000
	v_lshl_add_u64 v[130:131], v[128:129], 0, s[28:29]
	global_store_dwordx4 v[130:131], v[68:71], off sc1
	s_nop 1
	s_mov_b64 s[28:29], 0x1e000
	v_lshl_add_u64 v[130:131], v[128:129], 0, s[28:29]
	global_store_dwordx4 v[130:131], v[64:67], off sc1
	s_nop 1
	s_mov_b64 s[28:29], 0x20000
	v_lshl_add_u64 v[130:131], v[128:129], 0, s[28:29]
	global_store_dwordx4 v[130:131], v[60:63], off sc1
	s_nop 1
	s_mov_b64 s[28:29], 0x22000
	v_lshl_add_u64 v[130:131], v[128:129], 0, s[28:29]
	global_store_dwordx4 v[130:131], v[56:59], off sc1
	s_nop 1
	s_mov_b64 s[28:29], 0x24000
	v_lshl_add_u64 v[130:131], v[128:129], 0, s[28:29]
	global_store_dwordx4 v[130:131], v[44:47], off sc1
	s_nop 1
	s_mov_b64 s[28:29], 0x26000
	v_lshl_add_u64 v[130:131], v[128:129], 0, s[28:29]
	global_store_dwordx4 v[130:131], v[40:43], off sc1
	s_nop 1
	s_mov_b64 s[28:29], 0x28000
	v_lshl_add_u64 v[130:131], v[128:129], 0, s[28:29]
	global_store_dwordx4 v[130:131], v[28:31], off sc1
	s_nop 1
	s_mov_b64 s[28:29], 0x2a000
	v_lshl_add_u64 v[130:131], v[128:129], 0, s[28:29]
	global_store_dwordx4 v[130:131], v[24:27], off sc1
	s_nop 1
	s_mov_b64 s[28:29], 0x2c000
	v_lshl_add_u64 v[130:131], v[128:129], 0, s[28:29]
	global_store_dwordx4 v[130:131], v[12:15], off sc1
	s_nop 1
	s_mov_b64 s[28:29], 0x2e000
	v_lshl_add_u64 v[130:131], v[128:129], 0, s[28:29]
	global_store_dwordx4 v[130:131], v[8:11], off sc1
	s_nop 1
	s_mov_b64 s[28:29], 0x30000
	v_lshl_add_u64 v[130:131], v[128:129], 0, s[28:29]
	global_store_dwordx4 v[130:131], v[52:55], off sc1
	s_nop 1
	s_mov_b64 s[28:29], 0x32000
	v_lshl_add_u64 v[130:131], v[128:129], 0, s[28:29]
	global_store_dwordx4 v[130:131], v[48:51], off sc1
	s_nop 1
	s_mov_b64 s[28:29], 0x34000
	v_lshl_add_u64 v[130:131], v[128:129], 0, s[28:29]
	global_store_dwordx4 v[130:131], v[36:39], off sc1
	s_nop 1
	s_mov_b64 s[28:29], 0x36000
	v_lshl_add_u64 v[130:131], v[128:129], 0, s[28:29]
	global_store_dwordx4 v[130:131], v[32:35], off sc1
	s_nop 1
	s_mov_b64 s[28:29], 0x38000
	v_lshl_add_u64 v[130:131], v[128:129], 0, s[28:29]
	global_store_dwordx4 v[130:131], v[20:23], off sc1
	s_nop 1
	s_mov_b64 s[28:29], 0x3a000
	v_lshl_add_u64 v[130:131], v[128:129], 0, s[28:29]
	global_store_dwordx4 v[130:131], v[16:19], off sc1
	s_nop 1
	s_mov_b64 s[28:29], 0x3c000
	v_lshl_add_u64 v[130:131], v[128:129], 0, s[28:29]
	global_store_dwordx4 v[130:131], v[4:7], off sc1
	s_nop 1
	s_mov_b64 s[28:29], 0x3e000
	v_lshl_add_u64 v[128:129], v[128:129], 0, s[28:29]
	global_store_dwordx4 v[128:129], v[0:3], off sc1
	s_nop 1
	s_waitcnt vmcnt(0)
	s_barrier
	s_and_saveexec_b64 s[28:29], s[4:5]
	s_cbranch_execz .LBB0_989
	s_mov_b64 s[34:35], exec
	v_mbcnt_lo_u32_b32 v128, s34, 0
	v_mbcnt_hi_u32_b32 v128, s35, v128
	v_cmp_eq_u32_e32 vcc, 0, v128
	s_and_saveexec_b64 s[30:31], vcc
	s_cbranch_execz .LBB0_986
	v_readlane_b32 s26, v255, 52
	v_readlane_b32 s27, v255, 53
	s_nop 4
	v_mov_b32_e32 v130, 0x8000
	s_waitcnt lgkmcnt(0)
	s_add_u32 s7, s26, s16
	s_addc_u32 s26, s27, s17
	s_lshl_b64 s[24:25], s[24:25], 2
	s_add_u32 s24, s7, s24
	s_addc_u32 s25, s26, s25
	s_bcnt1_i32_b64 s7, s[34:35]
	v_mov_b32_e32 v129, s7
	global_atomic_add v129, v130, v129, s[24:25] offset:768 sc0

; __device__ __forceinline__ unsigned xb_ld(unsigned* p)              { return __hip_atomic_load(p, __ATOMIC_RELAXED, __HIP_MEMORY_SCOPE_AGENT); }
; __device__ __forceinline__ void xcd_barrier_complete(unsigned* bar, unsigned x, unsigned& nloc, unsigned& nx) {
;     const unsigned G = gridDim.x * gridDim.y * gridDim.z;
;     unsigned sum, cnt, mine, sp = 0u;
;     for (;;) {
;         sum = 0u; cnt = 0u; mine = 0u;
; #pragma unroll
;         for (unsigned j = 0; j < 16; ++j) { const unsigned c = xb_ld(&bar[XB_XCNT(j)]); sum += c; cnt += (c > 0u) ? 1u : 0u; mine = (j == x) ? c : mine; }
; __device__ __forceinline__ void xcd_barrier(const XcdBarrier& b) {
;     asm volatile("s_waitcnt vmcnt(0)" ::: "memory");
;     __syncthreads();
;     int t_o = threadIdx.x; asm volatile("" : "+v"(t_o));
;     if (t_o == 0) {
;         unsigned* bar = b.bar;
;         __builtin_amdgcn_s_waitcnt(0);
;         unsigned nloc = b.st[0], nx = b.st[1];
;         if (nloc == 0u) { xcd_barrier_complete(bar, b.x, nloc, nx); b.st[0] = nloc; b.st[1] = nx; }
.LBB0_1024:
	s_mov_b64 s[4:5], s[88:89]
	s_getreg_b32 s1, hwreg(HW_REG_XCC_ID, 0, 4)
	s_waitcnt vmcnt(0)
	v_mov_b32_e32 v0, v191
	s_waitcnt vmcnt(0) lgkmcnt(0)
	s_barrier
	s_nop 0
	v_cmp_eq_u32_e32 vcc, 0, v0
	s_and_saveexec_b64 s[2:3], vcc
	s_cbranch_execz .LBB0_188
	v_readlane_b32 s6, v255, 8
	v_readlane_b32 s4, v255, 52
	v_readlane_b32 s5, v255, 53
	s_nop 4
	s_waitcnt vmcnt(0) expcnt(0) lgkmcnt(0)
	v_mov_b32_e32 v0, s6
	ds_read_b32 v2, v0
	v_readlane_b32 s6, v255, 9
	s_and_b32 s1, s1, 15
	s_waitcnt lgkmcnt(0)
	v_cmp_ne_u32_e32 vcc, 0, v2
	v_mov_b32_e32 v0, s6
	ds_read_b32 v0, v0
	s_cbranch_vccnz .LBB0_1040
	s_add_u32 s6, s4, 0x1200
	s_addc_u32 s7, s5, 0
	s_add_u32 s8, s4, 0x1400
	s_addc_u32 s9, s5, 0
	s_add_u32 s10, s4, 0x1500
	s_addc_u32 s11, s5, 0
	s_add_u32 s12, s4, 0x1600
	s_addc_u32 s13, s5, 0
	s_add_u32 s14, s4, 0x1700
	s_addc_u32 s15, s5, 0
	s_add_u32 s16, s4, 0x1800
	s_addc_u32 s17, s5, 0
	s_add_u32 s18, s4, 0x1900
	s_addc_u32 s19, s5, 0
	s_add_u32 s20, s4, 0x1a00
	s_addc_u32 s21, s5, 0
	s_add_u32 s22, s4, 0x1b00
	s_addc_u32 s23, s5, 0
	s_add_u32 s24, s4, 0x1c00
	s_addc_u32 s25, s5, 0
	s_add_u32 s26, s4, 0x1d00
	s_addc_u32 s27, s5, 0
	s_add_u32 s28, s4, 0x1e00
	s_addc_u32 s29, s5, 0
	s_add_u32 s30, s4, 0x1f00
	s_addc_u32 s31, s5, 0
	s_add_u32 s34, s4, 0x2000
	s_addc_u32 s35, s5, 0
	s_add_u32 s36, s4, 0x2100
	s_addc_u32 s37, s5, 0
	s_add_u32 s38, s4, 0x2200
	s_addc_u32 s39, s5, 0
	s_add_u32 s40, s4, 0x2300
	s_addc_u32 s41, s5, 0
	s_mov_b32 s48, 1
	s_branch .LBB0_1028
